# kloops-without-per-phase-setprio-flips
# speedup vs baseline: 1.0086x; 1.0086x over previous
; #define PG8_STAGE(bufoff, gbase, hoff, imm) do { _Pragma("unroll") for (int _i = 0; _i < 2; ++_i) { \
;         asm volatile("s_mov_b32 m0, %0\n\ts_nop 0\n\tglobal_load_lds_dwordx4 %1, %2" \
;             :: "s"(lds0 + (unsigned)((bufoff) + _i * 8192)), "v"(voff0), "s"((const char*)(gbase) + (size_t)(hoff) + (size_t)(_i * 8192)) : "memory"); } } while (0)
; #define PG8_LDA(dst, b, h) do { _Pragma("unroll") for (int m = 0; m < 4; ++m) _Pragma("unroll") for (int k = 0; k < 2; ++k) dst[m][k] = *(const LAS bf16x8*)(lds + PG8_SA(b, h) + aoff + m * 2048 + k * 1024); } while (0)
; #define PG8_LDB(dst, b, h) do { _Pragma("unroll") for (int n = 0; n < 2; ++n) _Pragma("unroll") for (int k = 0; k < 2; ++k) dst[n][k] = *(const LAS bf16x8*)(lds + PG8_SB(b, h) + boff + n * 2048 + k * 1024); } while (0)
; #define PG8_MMA(ai, bj, At, Bt) do { __builtin_amdgcn_s_setprio(1); _Pragma("unroll") for (int m = 0; m < 4; ++m) _Pragma("unroll") for (int n = 0; n < 2; ++n) _Pragma("unroll") for (int k = 0; k < 2; ++k) \
;         acc[ai][bj][m][n] = __builtin_amdgcn_mfma_f32_16x16x32_bf16(Bt[n][k], At[m][k], acc[ai][bj][m][n], 0, 0, 0); __builtin_amdgcn_s_setprio(0); } while (0)
; #define PG8_WAIT_L(n) asm volatile("s_waitcnt lgkmcnt(" #n ")" ::: "memory")
; #define PG8_BAR __builtin_amdgcn_s_barrier()
; #define PG8_SCHED __builtin_amdgcn_sched_barrier(0)
; template <class Epi>
; __device__ __forceinline__ void gemm_phase(LAS unsigned char* lds, const Gemm g, const StaticOrder& S, const Epi& E) {
;     ...
;             const char* aT = cA + (size_t)t * KS;
;             const char* a2 = last ? nA : aT + 2 * KS; const char* b2 = last ? nB : cB + (size_t)(t + 2) * KS;
;             PG8_LDB(B0, 0, 0); PG8_SCHED; PG8_LDA(At, 0, 0); PG8_STAGE(PG8_SA(1, 1), aT + KS, hA, 0);
;             PG8_WAIT_L(8); PG8_BAR; PG8_WAIT_L(0); PG8_MMA(0, 0, At, B0); PG8_BAR; PG8_SCHED;
;             PG8_LDB(B1, 0, 1); PG8_STAGE(PG8_SB(0, 0), b2, 0, 0);
;             PG8_BAR; PG8_WAIT_L(0); PG8_MMA(0, 1, At, B1); PG8_BAR;
;             PG8_LDA(At, 0, 1); PG8_STAGE(PG8_SA(0, 0), a2, 0, 0);
;             PG8_BAR; PG8_WAIT_L(0); PG8_MMA(1, 0, At, B0); PG8_BAR; PG8_SCHED;
.LBB0_293:
	s_add_u32 s52, s8, 0x8000
	s_addc_u32 s53, s9, 0
	ds_read_b128 v[128:131], v224
	ds_read_b128 v[132:135], v224 offset:1024
	ds_read_b128 v[136:139], v224 offset:2048
	ds_read_b128 v[140:143], v224 offset:3072
	s_add_u32 s54, s8, 0x84000
	s_addc_u32 s55, s9, 0
	s_add_u32 s96, s8, 0x86000
	s_addc_u32 s97, s9, 0
	s_cmp_eq_u32 s95, 4
	s_cselect_b32 s9, s0, s53
	s_cselect_b32 s8, s1, s52
	ds_read_b128 v[144:147], v225
	ds_read_b128 v[148:151], v225 offset:1024
	ds_read_b128 v[152:155], v225 offset:2048
	ds_read_b128 v[156:159], v225 offset:3072
	ds_read_b128 v[160:163], v225 offset:4096
	ds_read_b128 v[164:167], v225 offset:5120
	ds_read_b128 v[168:171], v225 offset:6144
	ds_read_b128 v[172:175], v225 offset:7168
	s_mov_b32 m0, s86
	s_nop 0
	global_load_lds_dwordx4 v221, s[54:55]
	s_mov_b32 m0, s87
	s_nop 0
	global_load_lds_dwordx4 v221, s[96:97]
	s_waitcnt lgkmcnt(8)
	s_waitcnt vmcnt(10)
	s_barrier
	s_waitcnt lgkmcnt(0)
	s_waitcnt lgkmcnt(7)
	v_mfma_f32_16x16x32_bf16 v[124:127], v[128:131], v[144:147], v[124:127]
	v_mfma_f32_16x16x32_bf16 v[120:123], v[136:139], v[144:147], v[120:123]
	s_waitcnt lgkmcnt(5)
	v_mfma_f32_16x16x32_bf16 v[116:119], v[128:131], v[152:155], v[116:119]
	v_mfma_f32_16x16x32_bf16 v[112:115], v[136:139], v[152:155], v[112:115]
	s_waitcnt lgkmcnt(3)
	v_mfma_f32_16x16x32_bf16 v[96:99], v[128:131], v[160:163], v[96:99]
	v_mfma_f32_16x16x32_bf16 v[88:91], v[136:139], v[160:163], v[88:91]
	s_waitcnt lgkmcnt(1)
	v_mfma_f32_16x16x32_bf16 v[80:83], v[128:131], v[168:171], v[80:83]
	v_mfma_f32_16x16x32_bf16 v[72:75], v[136:139], v[168:171], v[72:75]
	v_mfma_f32_16x16x32_bf16 v[124:127], v[132:135], v[148:151], v[124:127]
	v_mfma_f32_16x16x32_bf16 v[120:123], v[140:143], v[148:151], v[120:123]
	v_mfma_f32_16x16x32_bf16 v[116:119], v[132:135], v[156:159], v[116:119]
	v_mfma_f32_16x16x32_bf16 v[112:115], v[140:143], v[156:159], v[112:115]
	v_mfma_f32_16x16x32_bf16 v[96:99], v[132:135], v[164:167], v[96:99]
	v_mfma_f32_16x16x32_bf16 v[88:91], v[140:143], v[164:167], v[88:91]
	s_waitcnt lgkmcnt(0)
	v_mfma_f32_16x16x32_bf16 v[80:83], v[132:135], v[172:175], v[80:83]
	v_mfma_f32_16x16x32_bf16 v[72:75], v[140:143], v[172:175], v[72:75]
	s_barrier
	ds_read_b128 v[176:179], v226
	ds_read_b128 v[180:183], v226 offset:1024
	ds_read_b128 v[184:187], v226 offset:2048
	ds_read_b128 v[188:191], v226 offset:3072
	s_cselect_b32 s54, s47, s93
	s_cselect_b32 s55, s45, s94
	s_mov_b32 m0, s60
	s_nop 0
	global_load_lds_dwordx4 v221, s[54:55]
	s_add_u32 s96, s54, 0x2000
	s_addc_u32 s97, s55, 0
	s_mov_b32 m0, s61
	s_nop 0
	global_load_lds_dwordx4 v221, s[96:97]
	s_waitcnt vmcnt(10)
	s_barrier
	s_waitcnt lgkmcnt(0)
	s_waitcnt lgkmcnt(3)
	v_mfma_f32_16x16x32_bf16 v[108:111], v[176:179], v[144:147], v[108:111]
	s_waitcnt lgkmcnt(1)
	v_mfma_f32_16x16x32_bf16 v[104:107], v[184:187], v[144:147], v[104:107]
	v_mfma_f32_16x16x32_bf16 v[100:103], v[176:179], v[152:155], v[100:103]
	v_mfma_f32_16x16x32_bf16 v[92:95], v[184:187], v[152:155], v[92:95]
	v_mfma_f32_16x16x32_bf16 v[84:87], v[176:179], v[160:163], v[84:87]
	v_mfma_f32_16x16x32_bf16 v[76:79], v[184:187], v[160:163], v[76:79]
	v_mfma_f32_16x16x32_bf16 v[68:71], v[176:179], v[168:171], v[68:71]
	v_mfma_f32_16x16x32_bf16 v[64:67], v[184:187], v[168:171], v[64:67]
	v_mfma_f32_16x16x32_bf16 v[108:111], v[180:183], v[148:151], v[108:111]
	s_waitcnt lgkmcnt(0)
	v_mfma_f32_16x16x32_bf16 v[104:107], v[188:191], v[148:151], v[104:107]
	v_mfma_f32_16x16x32_bf16 v[100:103], v[180:183], v[156:159], v[100:103]
	v_mfma_f32_16x16x32_bf16 v[92:95], v[188:191], v[156:159], v[92:95]
	v_mfma_f32_16x16x32_bf16 v[84:87], v[180:183], v[164:167], v[84:87]
	v_mfma_f32_16x16x32_bf16 v[76:79], v[188:191], v[164:167], v[76:79]
	v_mfma_f32_16x16x32_bf16 v[68:71], v[180:183], v[172:175], v[68:71]
	v_mfma_f32_16x16x32_bf16 v[64:67], v[188:191], v[172:175], v[64:67]
	s_barrier
	ds_read_b128 v[144:147], v225 offset:16384
	ds_read_b128 v[148:151], v225 offset:17408
	ds_read_b128 v[152:155], v225 offset:18432
	ds_read_b128 v[156:159], v225 offset:19456
	ds_read_b128 v[160:163], v225 offset:20480
	ds_read_b128 v[164:167], v225 offset:21504
	ds_read_b128 v[168:171], v225 offset:22528
	ds_read_b128 v[172:175], v225 offset:23552
	s_mov_b32 m0, s59
	s_nop 0
	global_load_lds_dwordx4 v221, s[8:9]
	s_add_u32 s96, s8, 0x2000
	s_addc_u32 s97, s9, 0
	s_mov_b32 m0, s62
	s_nop 0
	global_load_lds_dwordx4 v221, s[96:97]
	s_barrier
	s_waitcnt lgkmcnt(0)
	s_waitcnt lgkmcnt(7)
	v_mfma_f32_16x16x32_bf16 v[60:63], v[128:131], v[144:147], v[60:63]
	v_mfma_f32_16x16x32_bf16 v[56:59], v[136:139], v[144:147], v[56:59]
	s_waitcnt lgkmcnt(5)
	v_mfma_f32_16x16x32_bf16 v[48:51], v[128:131], v[152:155], v[48:51]
	v_mfma_f32_16x16x32_bf16 v[40:43], v[136:139], v[152:155], v[40:43]
	s_waitcnt lgkmcnt(3)
	v_mfma_f32_16x16x32_bf16 v[32:35], v[128:131], v[160:163], v[32:35]
	v_mfma_f32_16x16x32_bf16 v[24:27], v[136:139], v[160:163], v[24:27]
	s_waitcnt lgkmcnt(1)
	v_mfma_f32_16x16x32_bf16 v[16:19], v[128:131], v[168:171], v[16:19]
	v_mfma_f32_16x16x32_bf16 v[8:11], v[136:139], v[168:171], v[8:11]
	v_mfma_f32_16x16x32_bf16 v[60:63], v[132:135], v[148:151], v[60:63]
	v_mfma_f32_16x16x32_bf16 v[56:59], v[140:143], v[148:151], v[56:59]
	v_mfma_f32_16x16x32_bf16 v[48:51], v[132:135], v[156:159], v[48:51]
	v_mfma_f32_16x16x32_bf16 v[40:43], v[140:143], v[156:159], v[40:43]
	v_mfma_f32_16x16x32_bf16 v[32:35], v[132:135], v[164:167], v[32:35]
	v_mfma_f32_16x16x32_bf16 v[24:27], v[140:143], v[164:167], v[24:27]
	s_waitcnt lgkmcnt(0)
	v_mfma_f32_16x16x32_bf16 v[16:19], v[132:135], v[172:175], v[16:19]
	v_mfma_f32_16x16x32_bf16 v[8:11], v[140:143], v[172:175], v[8:11]
	s_barrier
; #define PG8_STAGE(bufoff, gbase, hoff, imm) do { _Pragma("unroll") for (int _i = 0; _i < 2; ++_i) { \
;         asm volatile("s_mov_b32 m0, %0\n\ts_nop 0\n\tglobal_load_lds_dwordx4 %1, %2" \
;             :: "s"(lds0 + (unsigned)((bufoff) + _i * 8192)), "v"(voff0), "s"((const char*)(gbase) + (size_t)(hoff) + (size_t)(_i * 8192)) : "memory"); } } while (0)
; #define PG8_LDA(dst, b, h) do { _Pragma("unroll") for (int m = 0; m < 4; ++m) _Pragma("unroll") for (int k = 0; k < 2; ++k) dst[m][k] = *(const LAS bf16x8*)(lds + PG8_SA(b, h) + aoff + m * 2048 + k * 1024); } while (0)
; #define PG8_LDB(dst, b, h) do { _Pragma("unroll") for (int n = 0; n < 2; ++n) _Pragma("unroll") for (int k = 0; k < 2; ++k) dst[n][k] = *(const LAS bf16x8*)(lds + PG8_SB(b, h) + boff + n * 2048 + k * 1024); } while (0)
; #define PG8_MMA(ai, bj, At, Bt) do { __builtin_amdgcn_s_setprio(1); _Pragma("unroll") for (int m = 0; m < 4; ++m) _Pragma("unroll") for (int n = 0; n < 2; ++n) _Pragma("unroll") for (int k = 0; k < 2; ++k) \
;         acc[ai][bj][m][n] = __builtin_amdgcn_mfma_f32_16x16x32_bf16(Bt[n][k], At[m][k], acc[ai][bj][m][n], 0, 0, 0); __builtin_amdgcn_s_setprio(0); } while (0)
; #define PG8_WAIT_V(n) asm volatile("s_waitcnt vmcnt(" #n ")" ::: "memory")
; #define PG8_WAIT_L(n) asm volatile("s_waitcnt lgkmcnt(" #n ")" ::: "memory")
; #define PG8_BAR __builtin_amdgcn_s_barrier()
; #define PG8_SCHED __builtin_amdgcn_sched_barrier(0)
; template <class Epi>
; __device__ __forceinline__ void gemm_phase(LAS unsigned char* lds, const Gemm g, const StaticOrder& S, const Epi& E) {
;     ...
;             PG8_STAGE(PG8_SB(0, 1), b2, hB, 0);
;             PG8_WAIT_V(6); PG8_BAR; PG8_MMA(1, 1, At, B1); PG8_BAR;
;             PG8_LDB(B0, 1, 0); PG8_SCHED; PG8_LDA(At, 1, 0); PG8_STAGE(PG8_SA(0, 1), a2, hA, 0);
;             PG8_WAIT_L(8); PG8_BAR; PG8_WAIT_L(0); PG8_MMA(0, 0, At, B0); PG8_BAR; PG8_SCHED;
;             PG8_LDB(B1, 1, 1); PG8_STAGE(PG8_SB(1, 0), b2 + KS, 0, 0);
;             PG8_BAR; PG8_WAIT_L(0); PG8_MMA(0, 1, At, B1); PG8_BAR;
	s_add_u32 s96, s54, 0x20000
	s_addc_u32 s97, s55, 0
	s_mov_b32 m0, s63
	s_nop 0
	global_load_lds_dwordx4 v221, s[96:97]
	s_add_u32 s96, s54, 0x22000
	s_addc_u32 s97, s55, 0
	s_mov_b32 m0, s64
	s_nop 0
	global_load_lds_dwordx4 v221, s[96:97]
	s_waitcnt vmcnt(10)
	s_barrier
	v_mfma_f32_16x16x32_bf16 v[52:55], v[176:179], v[144:147], v[52:55]
	v_mfma_f32_16x16x32_bf16 v[44:47], v[184:187], v[144:147], v[44:47]
	v_mfma_f32_16x16x32_bf16 v[36:39], v[176:179], v[152:155], v[36:39]
	v_mfma_f32_16x16x32_bf16 v[28:31], v[184:187], v[152:155], v[28:31]
	v_mfma_f32_16x16x32_bf16 v[20:23], v[176:179], v[160:163], v[20:23]
	v_mfma_f32_16x16x32_bf16 v[12:15], v[184:187], v[160:163], v[12:15]
	v_mfma_f32_16x16x32_bf16 v[4:7], v[176:179], v[168:171], v[4:7]
	v_mfma_f32_16x16x32_bf16 v[0:3], v[184:187], v[168:171], v[0:3]
	v_mfma_f32_16x16x32_bf16 v[52:55], v[180:183], v[148:151], v[52:55]
	v_mfma_f32_16x16x32_bf16 v[44:47], v[188:191], v[148:151], v[44:47]
	v_mfma_f32_16x16x32_bf16 v[36:39], v[180:183], v[156:159], v[36:39]
	v_mfma_f32_16x16x32_bf16 v[28:31], v[188:191], v[156:159], v[28:31]
	v_mfma_f32_16x16x32_bf16 v[20:23], v[180:183], v[164:167], v[20:23]
	v_mfma_f32_16x16x32_bf16 v[12:15], v[188:191], v[164:167], v[12:15]
	v_mfma_f32_16x16x32_bf16 v[4:7], v[180:183], v[172:175], v[4:7]
	v_mfma_f32_16x16x32_bf16 v[0:3], v[188:191], v[172:175], v[0:3]
	s_barrier
	ds_read_b128 v[128:131], v227
	ds_read_b128 v[132:135], v227 offset:1024
	ds_read_b128 v[136:139], v227 offset:2048
	ds_read_b128 v[140:143], v227 offset:3072
	ds_read_b128 v[144:147], v225 offset:32768
	ds_read_b128 v[148:151], v225 offset:33792
	ds_read_b128 v[152:155], v225 offset:34816
	ds_read_b128 v[156:159], v225 offset:35840
	ds_read_b128 v[160:163], v225 offset:36864
	ds_read_b128 v[164:167], v225 offset:37888
	ds_read_b128 v[168:171], v225 offset:38912
	ds_read_b128 v[172:175], v225 offset:39936
	s_add_u32 s96, s8, 0x80000
	s_addc_u32 s97, s9, 0
	s_mov_b32 m0, s65
	s_nop 0
	global_load_lds_dwordx4 v221, s[96:97]
	s_add_u32 s96, s8, 0x82000
	s_addc_u32 s97, s9, 0
	s_mov_b32 m0, s66
	s_nop 0
	global_load_lds_dwordx4 v221, s[96:97]
	s_waitcnt lgkmcnt(8)
	s_waitcnt vmcnt(10)
	s_barrier
	s_waitcnt lgkmcnt(0)
	s_waitcnt lgkmcnt(7)
	v_mfma_f32_16x16x32_bf16 v[124:127], v[128:131], v[144:147], v[124:127]
	v_mfma_f32_16x16x32_bf16 v[120:123], v[136:139], v[144:147], v[120:123]
	s_waitcnt lgkmcnt(5)
	v_mfma_f32_16x16x32_bf16 v[116:119], v[128:131], v[152:155], v[116:119]
	v_mfma_f32_16x16x32_bf16 v[112:115], v[136:139], v[152:155], v[112:115]
	s_waitcnt lgkmcnt(3)
	v_mfma_f32_16x16x32_bf16 v[96:99], v[128:131], v[160:163], v[96:99]
	v_mfma_f32_16x16x32_bf16 v[88:91], v[136:139], v[160:163], v[88:91]
	s_waitcnt lgkmcnt(1)
	v_mfma_f32_16x16x32_bf16 v[80:83], v[128:131], v[168:171], v[80:83]
	v_mfma_f32_16x16x32_bf16 v[72:75], v[136:139], v[168:171], v[72:75]
	v_mfma_f32_16x16x32_bf16 v[124:127], v[132:135], v[148:151], v[124:127]
	v_mfma_f32_16x16x32_bf16 v[120:123], v[140:143], v[148:151], v[120:123]
	v_mfma_f32_16x16x32_bf16 v[116:119], v[132:135], v[156:159], v[116:119]
	v_mfma_f32_16x16x32_bf16 v[112:115], v[140:143], v[156:159], v[112:115]
	v_mfma_f32_16x16x32_bf16 v[96:99], v[132:135], v[164:167], v[96:99]
	v_mfma_f32_16x16x32_bf16 v[88:91], v[140:143], v[164:167], v[88:91]
	s_waitcnt lgkmcnt(0)
	v_mfma_f32_16x16x32_bf16 v[80:83], v[132:135], v[172:175], v[80:83]
	v_mfma_f32_16x16x32_bf16 v[72:75], v[140:143], v[172:175], v[72:75]
	s_barrier
	ds_read_b128 v[176:179], v228
	ds_read_b128 v[180:183], v228 offset:1024
	ds_read_b128 v[184:187], v228 offset:2048
	ds_read_b128 v[188:191], v228 offset:3072
	s_add_u32 s96, s54, 0x4000
	s_addc_u32 s97, s55, 0
	s_mov_b32 m0, s69
	s_nop 0
	global_load_lds_dwordx4 v221, s[96:97]
	s_add_u32 s96, s54, 0x6000
	s_addc_u32 s97, s55, 0
	s_mov_b32 m0, s70
	s_nop 0
	global_load_lds_dwordx4 v221, s[96:97]
	s_waitcnt vmcnt(10)
	s_barrier
	s_waitcnt lgkmcnt(0)
	s_waitcnt lgkmcnt(3)
	v_mfma_f32_16x16x32_bf16 v[108:111], v[176:179], v[144:147], v[108:111]
	s_waitcnt lgkmcnt(1)
	v_mfma_f32_16x16x32_bf16 v[104:107], v[184:187], v[144:147], v[104:107]
	v_mfma_f32_16x16x32_bf16 v[100:103], v[176:179], v[152:155], v[100:103]
	v_mfma_f32_16x16x32_bf16 v[92:95], v[184:187], v[152:155], v[92:95]
	v_mfma_f32_16x16x32_bf16 v[84:87], v[176:179], v[160:163], v[84:87]
	v_mfma_f32_16x16x32_bf16 v[76:79], v[184:187], v[160:163], v[76:79]
	v_mfma_f32_16x16x32_bf16 v[68:71], v[176:179], v[168:171], v[68:71]
	v_mfma_f32_16x16x32_bf16 v[64:67], v[184:187], v[168:171], v[64:67]
	v_mfma_f32_16x16x32_bf16 v[108:111], v[180:183], v[148:151], v[108:111]
	s_waitcnt lgkmcnt(0)
	v_mfma_f32_16x16x32_bf16 v[104:107], v[188:191], v[148:151], v[104:107]
	v_mfma_f32_16x16x32_bf16 v[100:103], v[180:183], v[156:159], v[100:103]
	v_mfma_f32_16x16x32_bf16 v[92:95], v[188:191], v[156:159], v[92:95]
	v_mfma_f32_16x16x32_bf16 v[84:87], v[180:183], v[164:167], v[84:87]
	v_mfma_f32_16x16x32_bf16 v[76:79], v[188:191], v[164:167], v[76:79]
	v_mfma_f32_16x16x32_bf16 v[68:71], v[180:183], v[172:175], v[68:71]
	v_mfma_f32_16x16x32_bf16 v[64:67], v[188:191], v[172:175], v[64:67]
	s_barrier
; #define PG8_STAGE(bufoff, gbase, hoff, imm) do { _Pragma("unroll") for (int _i = 0; _i < 2; ++_i) { \
;         asm volatile("s_mov_b32 m0, %0\n\ts_nop 0\n\tglobal_load_lds_dwordx4 %1, %2" \
;             :: "s"(lds0 + (unsigned)((bufoff) + _i * 8192)), "v"(voff0), "s"((const char*)(gbase) + (size_t)(hoff) + (size_t)(_i * 8192)) : "memory"); } } while (0)
; #define PG8_LDA(dst, b, h) do { _Pragma("unroll") for (int m = 0; m < 4; ++m) _Pragma("unroll") for (int k = 0; k < 2; ++k) dst[m][k] = *(const LAS bf16x8*)(lds + PG8_SA(b, h) + aoff + m * 2048 + k * 1024); } while (0)
; #define PG8_MMA(ai, bj, At, Bt) do { __builtin_amdgcn_s_setprio(1); _Pragma("unroll") for (int m = 0; m < 4; ++m) _Pragma("unroll") for (int n = 0; n < 2; ++n) _Pragma("unroll") for (int k = 0; k < 2; ++k) \
;         acc[ai][bj][m][n] = __builtin_amdgcn_mfma_f32_16x16x32_bf16(Bt[n][k], At[m][k], acc[ai][bj][m][n], 0, 0, 0); __builtin_amdgcn_s_setprio(0); } while (0)
; #define PG8_WAIT_V(n) asm volatile("s_waitcnt vmcnt(" #n ")" ::: "memory")
; #define PG8_WAIT_L(n) asm volatile("s_waitcnt lgkmcnt(" #n ")" ::: "memory")
; #define PG8_BAR __builtin_amdgcn_s_barrier()
; #define PG8_SCHED __builtin_amdgcn_sched_barrier(0)
; template <class Epi>
; __device__ __forceinline__ void gemm_phase(LAS unsigned char* lds, const Gemm g, const StaticOrder& S, const Epi& E) {
;     ...
;             PG8_LDA(At, 1, 1); PG8_STAGE(PG8_SA(1, 0), a2 + KS, 0, 0);
;             PG8_BAR; PG8_WAIT_L(0); PG8_MMA(1, 0, At, B0); PG8_BAR; PG8_SCHED;
;             PG8_STAGE(PG8_SB(1, 1), b2 + KS, hB, 0);
;             PG8_WAIT_V(6); PG8_BAR; PG8_MMA(1, 1, At, B1); PG8_BAR;
;     __device__ __forceinline__ void operator()(f32x4 (&acc)[2][2][4][2], const Unit& u, int wr, int wc, int fr, int fq, LAS unsigned char*) const {
;         const int b = u.pm >> 6;
;         const int col0 = u.pn * BM + wc * 32 + 8 * fq;
;         const size_t off0 = (size_t)(u.pm * BM + wr * 64 + fr) * D + col0;
;         f32x4 sc[2][2];
; #pragma unroll
;         for (int bj = 0; bj < 2; ++bj)
; #pragma unroll
;             for (int n = 0; n < 2; ++n) { f32x4 gt = *(const f32x4*)(gate + (size_t)b * MODW + col0 + bj * HALF + n * 4); sc[bj][n] = gt + 1.0f;
;                 if (cs) sc[bj][n] *= *(const f32x4*)(cs + col0 + bj * HALF + n * 4); }
	ds_read_b128 v[144:147], v225 offset:49152
	ds_read_b128 v[148:151], v225 offset:50176
	ds_read_b128 v[152:155], v225 offset:51200
	ds_read_b128 v[156:159], v225 offset:52224
	ds_read_b128 v[160:163], v225 offset:53248
	ds_read_b128 v[164:167], v225 offset:54272
	ds_read_b128 v[168:171], v225 offset:55296
	ds_read_b128 v[172:175], v225 offset:56320
	s_add_u32 s96, s8, 0x4000
	s_addc_u32 s97, s9, 0
	s_mov_b32 m0, s71
	s_nop 0
	global_load_lds_dwordx4 v221, s[96:97]
	s_add_u32 s8, s8, 0x6000
	s_addc_u32 s9, s9, 0
	s_mov_b32 m0, s72
	s_nop 0
	global_load_lds_dwordx4 v221, s[8:9]
	s_barrier
	s_waitcnt lgkmcnt(0)
	s_waitcnt lgkmcnt(7)
	v_mfma_f32_16x16x32_bf16 v[60:63], v[128:131], v[144:147], v[60:63]
	v_mfma_f32_16x16x32_bf16 v[56:59], v[136:139], v[144:147], v[56:59]
	s_waitcnt lgkmcnt(5)
	v_mfma_f32_16x16x32_bf16 v[48:51], v[128:131], v[152:155], v[48:51]
	v_mfma_f32_16x16x32_bf16 v[40:43], v[136:139], v[152:155], v[40:43]
	s_waitcnt lgkmcnt(3)
	v_mfma_f32_16x16x32_bf16 v[32:35], v[128:131], v[160:163], v[32:35]
	v_mfma_f32_16x16x32_bf16 v[24:27], v[136:139], v[160:163], v[24:27]
	s_waitcnt lgkmcnt(1)
	v_mfma_f32_16x16x32_bf16 v[16:19], v[128:131], v[168:171], v[16:19]
	v_mfma_f32_16x16x32_bf16 v[8:11], v[136:139], v[168:171], v[8:11]
	v_mfma_f32_16x16x32_bf16 v[60:63], v[132:135], v[148:151], v[60:63]
	v_mfma_f32_16x16x32_bf16 v[56:59], v[140:143], v[148:151], v[56:59]
	v_mfma_f32_16x16x32_bf16 v[48:51], v[132:135], v[156:159], v[48:51]
	v_mfma_f32_16x16x32_bf16 v[40:43], v[140:143], v[156:159], v[40:43]
	v_mfma_f32_16x16x32_bf16 v[32:35], v[132:135], v[164:167], v[32:35]
	v_mfma_f32_16x16x32_bf16 v[24:27], v[140:143], v[164:167], v[24:27]
	s_waitcnt lgkmcnt(0)
	v_mfma_f32_16x16x32_bf16 v[16:19], v[132:135], v[172:175], v[16:19]
	v_mfma_f32_16x16x32_bf16 v[8:11], v[140:143], v[172:175], v[8:11]
	s_barrier
	s_add_u32 s8, s54, 0x24000
	s_addc_u32 s9, s55, 0
	s_mov_b32 m0, s73
	s_nop 0
	global_load_lds_dwordx4 v221, s[8:9]
	s_add_u32 s8, s54, 0x26000
	s_addc_u32 s9, s55, 0
	s_mov_b32 m0, s85
	s_nop 0
	global_load_lds_dwordx4 v221, s[8:9]
	s_waitcnt vmcnt(10)
	s_barrier
	v_mfma_f32_16x16x32_bf16 v[52:55], v[176:179], v[144:147], v[52:55]
	v_mfma_f32_16x16x32_bf16 v[44:47], v[184:187], v[144:147], v[44:47]
	v_mfma_f32_16x16x32_bf16 v[36:39], v[176:179], v[152:155], v[36:39]
	v_mfma_f32_16x16x32_bf16 v[28:31], v[184:187], v[152:155], v[28:31]
	v_mfma_f32_16x16x32_bf16 v[20:23], v[176:179], v[160:163], v[20:23]
	v_mfma_f32_16x16x32_bf16 v[12:15], v[184:187], v[160:163], v[12:15]
	v_mfma_f32_16x16x32_bf16 v[4:7], v[176:179], v[168:171], v[4:7]
	v_mfma_f32_16x16x32_bf16 v[0:3], v[184:187], v[168:171], v[0:3]
	v_mfma_f32_16x16x32_bf16 v[52:55], v[180:183], v[148:151], v[52:55]
	v_mfma_f32_16x16x32_bf16 v[44:47], v[188:191], v[148:151], v[44:47]
	v_mfma_f32_16x16x32_bf16 v[36:39], v[180:183], v[156:159], v[36:39]
	v_mfma_f32_16x16x32_bf16 v[28:31], v[188:191], v[156:159], v[28:31]
	v_mfma_f32_16x16x32_bf16 v[20:23], v[180:183], v[164:167], v[20:23]
	v_mfma_f32_16x16x32_bf16 v[12:15], v[188:191], v[164:167], v[12:15]
	v_mfma_f32_16x16x32_bf16 v[4:7], v[180:183], v[172:175], v[4:7]
	v_mfma_f32_16x16x32_bf16 v[0:3], v[188:191], v[172:175], v[0:3]
	s_add_i32 s95, s95, 2
	s_add_u32 s93, s93, 0x8000
	s_addc_u32 s94, s94, 0
	s_cmp_gt_u32 s95, 5
	s_mov_b64 s[8:9], s[52:53]
	s_barrier
	s_cbranch_scc0 .LBB0_293
	s_ashr_i32 s0, s89, 6
	v_lshl_or_b32 v128, s92, 8, v223
	s_mul_hi_i32 s1, s0, 0xc000
	s_mul_i32 s0, s0, 0xc000
	v_ashrrev_i32_e32 v129, 31, v128
	s_add_u32 s0, s67, s0
	s_addc_u32 s1, s68, s1
	v_lshlrev_b64 v[130:131], 2, v[128:129]
	v_lshl_add_u64 v[132:133], s[0:1], 0, v[130:131]
	global_load_dwordx4 v[134:137], v[132:133], off
	v_cndmask_b32_e64 v138, 0, 1, s[42:43]
	v_cmp_ne_u32_e64 s[8:9], 1, v138
	v_lshl_add_u64 v[130:131], s[38:39], 0, v[130:131]
	s_andn2_b64 vcc, exec, s[42:43]
	s_waitcnt vmcnt(0)
	v_pk_add_f32 v[198:199], v[136:137], 1.0 op_sel_hi:[1,0]
	v_pk_add_f32 v[196:197], v[134:135], 1.0 op_sel_hi:[1,0]
	s_cbranch_vccnz .LBB0_296
	global_load_dwordx4 v[134:137], v[130:131], off
	s_waitcnt vmcnt(0)
	v_pk_mul_f32 v[198:199], v[198:199], v[136:137]
	v_pk_mul_f32 v[196:197], v[196:197], v[134:135]

; #define PG8_STAGE(bufoff, gbase, hoff, imm) do { _Pragma("unroll") for (int _i = 0; _i < 2; ++_i) { \
;         asm volatile("s_mov_b32 m0, %0\n\ts_nop 0\n\tglobal_load_lds_dwordx4 %1, %2" \
;             :: "s"(lds0 + (unsigned)((bufoff) + _i * 8192)), "v"(voff0), "s"((const char*)(gbase) + (size_t)(hoff) + (size_t)(_i * 8192)) : "memory"); } } while (0)
; #define PG8_LDA(dst, b, h) do { _Pragma("unroll") for (int m = 0; m < 4; ++m) _Pragma("unroll") for (int k = 0; k < 2; ++k) dst[m][k] = *(const LAS bf16x8*)(lds + PG8_SA(b, h) + aoff + m * 2048 + k * 1024); } while (0)
; #define PG8_LDB(dst, b, h) do { _Pragma("unroll") for (int n = 0; n < 2; ++n) _Pragma("unroll") for (int k = 0; k < 2; ++k) dst[n][k] = *(const LAS bf16x8*)(lds + PG8_SB(b, h) + boff + n * 2048 + k * 1024); } while (0)
; #define PG8_MMA(ai, bj, At, Bt) do { __builtin_amdgcn_s_setprio(1); _Pragma("unroll") for (int m = 0; m < 4; ++m) _Pragma("unroll") for (int n = 0; n < 2; ++n) _Pragma("unroll") for (int k = 0; k < 2; ++k) \
;         acc[ai][bj][m][n] = __builtin_amdgcn_mfma_f32_16x16x32_bf16(Bt[n][k], At[m][k], acc[ai][bj][m][n], 0, 0, 0); __builtin_amdgcn_s_setprio(0); } while (0)
; #define PG8_WAIT_L(n) asm volatile("s_waitcnt lgkmcnt(" #n ")" ::: "memory")
; #define PG8_BAR __builtin_amdgcn_s_barrier()
; #define PG8_SCHED __builtin_amdgcn_sched_barrier(0)
; template <class Epi>
; __device__ __forceinline__ void gemm_phase(LAS unsigned char* lds, const Gemm g, const StaticOrder& S, const Epi& E) {
;     ...
;             const char* aT = cA + (size_t)t * KS;
;             const char* a2 = last ? nA : aT + 2 * KS; const char* b2 = last ? nB : cB + (size_t)(t + 2) * KS;
;             PG8_LDB(B0, 0, 0); PG8_SCHED; PG8_LDA(At, 0, 0); PG8_STAGE(PG8_SA(1, 1), aT + KS, hA, 0);
;             PG8_WAIT_L(8); PG8_BAR; PG8_WAIT_L(0); PG8_MMA(0, 0, At, B0); PG8_BAR; PG8_SCHED;
;             PG8_LDB(B1, 0, 1); PG8_STAGE(PG8_SB(0, 0), b2, 0, 0);
;             PG8_BAR; PG8_WAIT_L(0); PG8_MMA(0, 1, At, B1); PG8_BAR;
;             PG8_LDA(At, 0, 1); PG8_STAGE(PG8_SA(0, 0), a2, 0, 0);
;             PG8_BAR; PG8_WAIT_L(0); PG8_MMA(1, 0, At, B0); PG8_BAR; PG8_SCHED;
.LBB0_434:
	s_add_u32 s56, s54, 0x8000
	v_add_u32_e32 v128, 0x10000, v133
	s_addc_u32 s57, s55, 0
	ds_read_b128 v[136:139], v128
	ds_read_b128 v[140:143], v128 offset:1024
	ds_read_b128 v[144:147], v128 offset:2048
	ds_read_b128 v[148:151], v128 offset:3072
	s_add_u32 s58, s54, 0x84000
	s_addc_u32 s59, s55, 0
	s_add_u32 s66, s54, 0x86000
	s_addc_u32 s67, s55, 0
	s_cmp_eq_u32 s65, 28
	s_cselect_b32 s55, s0, s57
	s_cselect_b32 s54, s1, s56
	ds_read_b128 v[152:155], v134
	ds_read_b128 v[156:159], v134 offset:1024
	ds_read_b128 v[160:163], v134 offset:2048
	ds_read_b128 v[164:167], v134 offset:3072
	ds_read_b128 v[168:171], v134 offset:4096
	ds_read_b128 v[172:175], v134 offset:5120
	ds_read_b128 v[176:179], v134 offset:6144
	ds_read_b128 v[180:183], v134 offset:7168
	s_mov_b32 m0, s50
	s_nop 0
	global_load_lds_dwordx4 v130, s[58:59]
	s_mov_b32 m0, s51
	s_nop 0
	global_load_lds_dwordx4 v130, s[66:67]
	s_waitcnt lgkmcnt(8)
	s_waitcnt vmcnt(10)
	s_barrier
	s_waitcnt lgkmcnt(0)
	s_waitcnt lgkmcnt(7)
	v_mfma_f32_16x16x32_bf16 v[124:127], v[136:139], v[152:155], v[124:127]
	v_mfma_f32_16x16x32_bf16 v[120:123], v[144:147], v[152:155], v[120:123]
	s_waitcnt lgkmcnt(5)
	v_mfma_f32_16x16x32_bf16 v[116:119], v[136:139], v[160:163], v[116:119]
	v_mfma_f32_16x16x32_bf16 v[108:111], v[144:147], v[160:163], v[108:111]
	s_waitcnt lgkmcnt(3)
	v_mfma_f32_16x16x32_bf16 v[100:103], v[136:139], v[168:171], v[100:103]
	v_mfma_f32_16x16x32_bf16 v[92:95], v[144:147], v[168:171], v[92:95]
	s_waitcnt lgkmcnt(1)
	v_mfma_f32_16x16x32_bf16 v[84:87], v[136:139], v[176:179], v[84:87]
	v_mfma_f32_16x16x32_bf16 v[76:79], v[144:147], v[176:179], v[76:79]
	v_mfma_f32_16x16x32_bf16 v[124:127], v[140:143], v[156:159], v[124:127]
	v_mfma_f32_16x16x32_bf16 v[120:123], v[148:151], v[156:159], v[120:123]
	v_mfma_f32_16x16x32_bf16 v[116:119], v[140:143], v[164:167], v[116:119]
	v_mfma_f32_16x16x32_bf16 v[108:111], v[148:151], v[164:167], v[108:111]
	v_mfma_f32_16x16x32_bf16 v[100:103], v[140:143], v[172:175], v[100:103]
	v_mfma_f32_16x16x32_bf16 v[92:95], v[148:151], v[172:175], v[92:95]
	s_waitcnt lgkmcnt(0)
	v_mfma_f32_16x16x32_bf16 v[84:87], v[140:143], v[180:183], v[84:87]
	v_mfma_f32_16x16x32_bf16 v[76:79], v[148:151], v[180:183], v[76:79]
	s_barrier
	v_add_u32_e32 v128, 0x14000, v133
	ds_read_b128 v[184:187], v128
	ds_read_b128 v[200:203], v128 offset:1024
	ds_read_b128 v[204:207], v128 offset:2048
	ds_read_b128 v[208:211], v128 offset:3072
	s_cselect_b32 s58, s9, s63
	s_cselect_b32 s59, s7, s64
	s_mov_b32 m0, s26
	s_nop 0
	global_load_lds_dwordx4 v130, s[58:59]
	s_add_u32 s66, s58, 0x2000
	s_addc_u32 s67, s59, 0
	s_mov_b32 m0, s27
	s_nop 0
	global_load_lds_dwordx4 v130, s[66:67]
	s_waitcnt vmcnt(10)
	s_barrier
	s_waitcnt lgkmcnt(0)
	s_waitcnt lgkmcnt(3)
	v_mfma_f32_16x16x32_bf16 v[112:115], v[184:187], v[152:155], v[112:115]
	s_waitcnt lgkmcnt(1)
	v_mfma_f32_16x16x32_bf16 v[104:107], v[204:207], v[152:155], v[104:107]
	v_mfma_f32_16x16x32_bf16 v[96:99], v[184:187], v[160:163], v[96:99]
	v_mfma_f32_16x16x32_bf16 v[88:91], v[204:207], v[160:163], v[88:91]
	v_mfma_f32_16x16x32_bf16 v[80:83], v[184:187], v[168:171], v[80:83]
	v_mfma_f32_16x16x32_bf16 v[72:75], v[204:207], v[168:171], v[72:75]
	v_mfma_f32_16x16x32_bf16 v[68:71], v[184:187], v[176:179], v[68:71]
	v_mfma_f32_16x16x32_bf16 v[64:67], v[204:207], v[176:179], v[64:67]
	v_mfma_f32_16x16x32_bf16 v[112:115], v[200:203], v[156:159], v[112:115]
	s_waitcnt lgkmcnt(0)
	v_mfma_f32_16x16x32_bf16 v[104:107], v[208:211], v[156:159], v[104:107]
	v_mfma_f32_16x16x32_bf16 v[96:99], v[200:203], v[164:167], v[96:99]
	v_mfma_f32_16x16x32_bf16 v[88:91], v[208:211], v[164:167], v[88:91]
	v_mfma_f32_16x16x32_bf16 v[80:83], v[200:203], v[172:175], v[80:83]
	v_mfma_f32_16x16x32_bf16 v[72:75], v[208:211], v[172:175], v[72:75]
	v_mfma_f32_16x16x32_bf16 v[68:71], v[200:203], v[180:183], v[68:71]
	v_mfma_f32_16x16x32_bf16 v[64:67], v[208:211], v[180:183], v[64:67]
	s_barrier
	ds_read_b128 v[152:155], v134 offset:16384
	ds_read_b128 v[156:159], v134 offset:17408
	ds_read_b128 v[160:163], v134 offset:18432
	ds_read_b128 v[164:167], v134 offset:19456
	ds_read_b128 v[168:171], v134 offset:20480
	ds_read_b128 v[172:175], v134 offset:21504
	ds_read_b128 v[176:179], v134 offset:22528
	ds_read_b128 v[180:183], v134 offset:23552
	s_mov_b32 m0, s25
	s_nop 0
	global_load_lds_dwordx4 v130, s[54:55]
	s_add_u32 s66, s54, 0x2000
	s_addc_u32 s67, s55, 0
	s_mov_b32 m0, s28
	s_nop 0
	global_load_lds_dwordx4 v130, s[66:67]
	s_barrier
	s_waitcnt lgkmcnt(0)
	s_waitcnt lgkmcnt(7)
	v_mfma_f32_16x16x32_bf16 v[60:63], v[136:139], v[152:155], v[60:63]
	v_mfma_f32_16x16x32_bf16 v[56:59], v[144:147], v[152:155], v[56:59]
	s_waitcnt lgkmcnt(5)
	v_mfma_f32_16x16x32_bf16 v[52:55], v[136:139], v[160:163], v[52:55]
	v_mfma_f32_16x16x32_bf16 v[44:47], v[144:147], v[160:163], v[44:47]
	s_waitcnt lgkmcnt(3)
	v_mfma_f32_16x16x32_bf16 v[36:39], v[136:139], v[168:171], v[36:39]
	v_mfma_f32_16x16x32_bf16 v[28:31], v[144:147], v[168:171], v[28:31]
	s_waitcnt lgkmcnt(1)
	v_mfma_f32_16x16x32_bf16 v[20:23], v[136:139], v[176:179], v[20:23]
	v_mfma_f32_16x16x32_bf16 v[12:15], v[144:147], v[176:179], v[12:15]
	v_mfma_f32_16x16x32_bf16 v[60:63], v[140:143], v[156:159], v[60:63]
	v_mfma_f32_16x16x32_bf16 v[56:59], v[148:151], v[156:159], v[56:59]
	v_mfma_f32_16x16x32_bf16 v[52:55], v[140:143], v[164:167], v[52:55]
	v_mfma_f32_16x16x32_bf16 v[44:47], v[148:151], v[164:167], v[44:47]
	v_mfma_f32_16x16x32_bf16 v[36:39], v[140:143], v[172:175], v[36:39]
	v_mfma_f32_16x16x32_bf16 v[28:31], v[148:151], v[172:175], v[28:31]
	s_waitcnt lgkmcnt(0)
	v_mfma_f32_16x16x32_bf16 v[20:23], v[140:143], v[180:183], v[20:23]
	v_mfma_f32_16x16x32_bf16 v[12:15], v[148:151], v[180:183], v[12:15]
	s_barrier
; #define PG8_STAGE(bufoff, gbase, hoff, imm) do { _Pragma("unroll") for (int _i = 0; _i < 2; ++_i) { \
;         asm volatile("s_mov_b32 m0, %0\n\ts_nop 0\n\tglobal_load_lds_dwordx4 %1, %2" \
;             :: "s"(lds0 + (unsigned)((bufoff) + _i * 8192)), "v"(voff0), "s"((const char*)(gbase) + (size_t)(hoff) + (size_t)(_i * 8192)) : "memory"); } } while (0)
; #define PG8_LDA(dst, b, h) do { _Pragma("unroll") for (int m = 0; m < 4; ++m) _Pragma("unroll") for (int k = 0; k < 2; ++k) dst[m][k] = *(const LAS bf16x8*)(lds + PG8_SA(b, h) + aoff + m * 2048 + k * 1024); } while (0)
; #define PG8_LDB(dst, b, h) do { _Pragma("unroll") for (int n = 0; n < 2; ++n) _Pragma("unroll") for (int k = 0; k < 2; ++k) dst[n][k] = *(const LAS bf16x8*)(lds + PG8_SB(b, h) + boff + n * 2048 + k * 1024); } while (0)
; #define PG8_MMA(ai, bj, At, Bt) do { __builtin_amdgcn_s_setprio(1); _Pragma("unroll") for (int m = 0; m < 4; ++m) _Pragma("unroll") for (int n = 0; n < 2; ++n) _Pragma("unroll") for (int k = 0; k < 2; ++k) \
;         acc[ai][bj][m][n] = __builtin_amdgcn_mfma_f32_16x16x32_bf16(Bt[n][k], At[m][k], acc[ai][bj][m][n], 0, 0, 0); __builtin_amdgcn_s_setprio(0); } while (0)
; #define PG8_WAIT_V(n) asm volatile("s_waitcnt vmcnt(" #n ")" ::: "memory")
; #define PG8_WAIT_L(n) asm volatile("s_waitcnt lgkmcnt(" #n ")" ::: "memory")
; #define PG8_BAR __builtin_amdgcn_s_barrier()
; #define PG8_SCHED __builtin_amdgcn_sched_barrier(0)
; template <class Epi>
; __device__ __forceinline__ void gemm_phase(LAS unsigned char* lds, const Gemm g, const StaticOrder& S, const Epi& E) {
;     ...
;             PG8_STAGE(PG8_SB(0, 1), b2, hB, 0);
;             PG8_WAIT_V(6); PG8_BAR; PG8_MMA(1, 1, At, B1); PG8_BAR;
;             PG8_LDB(B0, 1, 0); PG8_SCHED; PG8_LDA(At, 1, 0); PG8_STAGE(PG8_SA(0, 1), a2, hA, 0);
;             PG8_WAIT_L(8); PG8_BAR; PG8_WAIT_L(0); PG8_MMA(0, 0, At, B0); PG8_BAR; PG8_SCHED;
;             PG8_LDB(B1, 1, 1); PG8_STAGE(PG8_SB(1, 0), b2 + KS, 0, 0);
;             PG8_BAR; PG8_WAIT_L(0); PG8_MMA(0, 1, At, B1); PG8_BAR;
;             PG8_LDA(At, 1, 1); PG8_STAGE(PG8_SA(1, 0), a2 + KS, 0, 0);
	s_add_u32 s66, s58, 0x80000
	s_addc_u32 s67, s59, 0
	s_mov_b32 m0, s29
	s_nop 0
	global_load_lds_dwordx4 v130, s[66:67]
	s_add_u32 s66, s58, 0x82000
	s_addc_u32 s67, s59, 0
	s_mov_b32 m0, s30
	s_nop 0
	global_load_lds_dwordx4 v130, s[66:67]
	s_waitcnt vmcnt(10)
	s_barrier
	v_mfma_f32_16x16x32_bf16 v[48:51], v[184:187], v[152:155], v[48:51]
	v_mfma_f32_16x16x32_bf16 v[40:43], v[204:207], v[152:155], v[40:43]
	v_mfma_f32_16x16x32_bf16 v[32:35], v[184:187], v[160:163], v[32:35]
	v_mfma_f32_16x16x32_bf16 v[24:27], v[204:207], v[160:163], v[24:27]
	v_mfma_f32_16x16x32_bf16 v[16:19], v[184:187], v[168:171], v[16:19]
	v_mfma_f32_16x16x32_bf16 v[8:11], v[204:207], v[168:171], v[8:11]
	v_mfma_f32_16x16x32_bf16 v[4:7], v[184:187], v[176:179], v[4:7]
	v_mfma_f32_16x16x32_bf16 v[0:3], v[204:207], v[176:179], v[0:3]
	v_mfma_f32_16x16x32_bf16 v[48:51], v[200:203], v[156:159], v[48:51]
	v_mfma_f32_16x16x32_bf16 v[40:43], v[208:211], v[156:159], v[40:43]
	v_mfma_f32_16x16x32_bf16 v[32:35], v[200:203], v[164:167], v[32:35]
	v_mfma_f32_16x16x32_bf16 v[24:27], v[208:211], v[164:167], v[24:27]
	v_mfma_f32_16x16x32_bf16 v[16:19], v[200:203], v[172:175], v[16:19]
	v_mfma_f32_16x16x32_bf16 v[8:11], v[208:211], v[172:175], v[8:11]
	v_mfma_f32_16x16x32_bf16 v[4:7], v[200:203], v[180:183], v[4:7]
	v_mfma_f32_16x16x32_bf16 v[0:3], v[208:211], v[180:183], v[0:3]
	v_add_u32_e32 v128, 0x18000, v133
	s_barrier
	ds_read_b128 v[136:139], v128
	ds_read_b128 v[140:143], v128 offset:1024
	ds_read_b128 v[144:147], v128 offset:2048
	ds_read_b128 v[148:151], v128 offset:3072
	ds_read_b128 v[152:155], v134 offset:32768
	ds_read_b128 v[156:159], v134 offset:33792
	ds_read_b128 v[160:163], v134 offset:34816
	ds_read_b128 v[164:167], v134 offset:35840
	ds_read_b128 v[168:171], v134 offset:36864
	ds_read_b128 v[172:175], v134 offset:37888
	ds_read_b128 v[176:179], v134 offset:38912
	ds_read_b128 v[180:183], v134 offset:39936
	s_add_u32 s66, s54, 0x80000
	s_addc_u32 s67, s55, 0
	s_mov_b32 m0, s34
	s_nop 0
	global_load_lds_dwordx4 v130, s[66:67]
	s_add_u32 s66, s54, 0x82000
	s_addc_u32 s67, s55, 0
	s_mov_b32 m0, s37
	s_nop 0
	global_load_lds_dwordx4 v130, s[66:67]
	s_waitcnt lgkmcnt(8)
	s_waitcnt vmcnt(10)
	s_barrier
	s_waitcnt lgkmcnt(0)
	s_waitcnt lgkmcnt(7)
	v_mfma_f32_16x16x32_bf16 v[124:127], v[136:139], v[152:155], v[124:127]
	v_mfma_f32_16x16x32_bf16 v[120:123], v[144:147], v[152:155], v[120:123]
	s_waitcnt lgkmcnt(5)
	v_mfma_f32_16x16x32_bf16 v[116:119], v[136:139], v[160:163], v[116:119]
	v_mfma_f32_16x16x32_bf16 v[108:111], v[144:147], v[160:163], v[108:111]
	s_waitcnt lgkmcnt(3)
	v_mfma_f32_16x16x32_bf16 v[100:103], v[136:139], v[168:171], v[100:103]
	v_mfma_f32_16x16x32_bf16 v[92:95], v[144:147], v[168:171], v[92:95]
	s_waitcnt lgkmcnt(1)
	v_mfma_f32_16x16x32_bf16 v[84:87], v[136:139], v[176:179], v[84:87]
	v_mfma_f32_16x16x32_bf16 v[76:79], v[144:147], v[176:179], v[76:79]
	v_mfma_f32_16x16x32_bf16 v[124:127], v[140:143], v[156:159], v[124:127]
	v_mfma_f32_16x16x32_bf16 v[120:123], v[148:151], v[156:159], v[120:123]
	v_mfma_f32_16x16x32_bf16 v[116:119], v[140:143], v[164:167], v[116:119]
	v_mfma_f32_16x16x32_bf16 v[108:111], v[148:151], v[164:167], v[108:111]
	v_mfma_f32_16x16x32_bf16 v[100:103], v[140:143], v[172:175], v[100:103]
	v_mfma_f32_16x16x32_bf16 v[92:95], v[148:151], v[172:175], v[92:95]
	s_waitcnt lgkmcnt(0)
	v_mfma_f32_16x16x32_bf16 v[84:87], v[140:143], v[180:183], v[84:87]
	v_mfma_f32_16x16x32_bf16 v[76:79], v[148:151], v[180:183], v[76:79]
	s_barrier
	v_add_u32_e32 v128, 0x1c000, v133
	ds_read_b128 v[184:187], v128
	ds_read_b128 v[200:203], v128 offset:1024
	ds_read_b128 v[204:207], v128 offset:2048
	ds_read_b128 v[208:211], v128 offset:3072
	s_add_u32 s66, s58, 0x4000
	s_addc_u32 s67, s59, 0
	s_mov_b32 m0, s38
	s_nop 0
	global_load_lds_dwordx4 v130, s[66:67]
	s_add_u32 s66, s58, 0x6000
	s_addc_u32 s67, s59, 0
	s_mov_b32 m0, s39
	s_nop 0
	global_load_lds_dwordx4 v130, s[66:67]
	s_waitcnt vmcnt(10)
	s_barrier
	s_waitcnt lgkmcnt(0)
	s_waitcnt lgkmcnt(3)
	v_mfma_f32_16x16x32_bf16 v[112:115], v[184:187], v[152:155], v[112:115]
	s_waitcnt lgkmcnt(1)
	v_mfma_f32_16x16x32_bf16 v[104:107], v[204:207], v[152:155], v[104:107]
	v_mfma_f32_16x16x32_bf16 v[96:99], v[184:187], v[160:163], v[96:99]
	v_mfma_f32_16x16x32_bf16 v[88:91], v[204:207], v[160:163], v[88:91]
	v_mfma_f32_16x16x32_bf16 v[80:83], v[184:187], v[168:171], v[80:83]
	v_mfma_f32_16x16x32_bf16 v[72:75], v[204:207], v[168:171], v[72:75]
	v_mfma_f32_16x16x32_bf16 v[68:71], v[184:187], v[176:179], v[68:71]
	v_mfma_f32_16x16x32_bf16 v[64:67], v[204:207], v[176:179], v[64:67]
	v_mfma_f32_16x16x32_bf16 v[112:115], v[200:203], v[156:159], v[112:115]
	s_waitcnt lgkmcnt(0)
	v_mfma_f32_16x16x32_bf16 v[104:107], v[208:211], v[156:159], v[104:107]
	v_mfma_f32_16x16x32_bf16 v[96:99], v[200:203], v[164:167], v[96:99]
	v_mfma_f32_16x16x32_bf16 v[88:91], v[208:211], v[164:167], v[88:91]
	v_mfma_f32_16x16x32_bf16 v[80:83], v[200:203], v[172:175], v[80:83]
	v_mfma_f32_16x16x32_bf16 v[72:75], v[208:211], v[172:175], v[72:75]
	v_mfma_f32_16x16x32_bf16 v[68:71], v[200:203], v[180:183], v[68:71]
	v_mfma_f32_16x16x32_bf16 v[64:67], v[208:211], v[180:183], v[64:67]
	s_barrier
	ds_read_b128 v[152:155], v134 offset:49152
	ds_read_b128 v[156:159], v134 offset:50176
	ds_read_b128 v[160:163], v134 offset:51200
	ds_read_b128 v[164:167], v134 offset:52224
	ds_read_b128 v[168:171], v134 offset:53248
	ds_read_b128 v[172:175], v134 offset:54272
	ds_read_b128 v[176:179], v134 offset:55296
	ds_read_b128 v[180:183], v134 offset:56320
	s_add_u32 s66, s54, 0x4000
	s_addc_u32 s67, s55, 0
	s_mov_b32 m0, s40
	s_nop 0
	global_load_lds_dwordx4 v130, s[66:67]
	s_add_u32 s54, s54, 0x6000
	s_addc_u32 s55, s55, 0
	s_mov_b32 m0, s41
	s_nop 0
	global_load_lds_dwordx4 v130, s[54:55]
	s_barrier
; #define PG8_STAGE(bufoff, gbase, hoff, imm) do { _Pragma("unroll") for (int _i = 0; _i < 2; ++_i) { \
;         asm volatile("s_mov_b32 m0, %0\n\ts_nop 0\n\tglobal_load_lds_dwordx4 %1, %2" \
;             :: "s"(lds0 + (unsigned)((bufoff) + _i * 8192)), "v"(voff0), "s"((const char*)(gbase) + (size_t)(hoff) + (size_t)(_i * 8192)) : "memory"); } } while (0)
; #define PG8_MMA(ai, bj, At, Bt) do { __builtin_amdgcn_s_setprio(1); _Pragma("unroll") for (int m = 0; m < 4; ++m) _Pragma("unroll") for (int n = 0; n < 2; ++n) _Pragma("unroll") for (int k = 0; k < 2; ++k) \
;         acc[ai][bj][m][n] = __builtin_amdgcn_mfma_f32_16x16x32_bf16(Bt[n][k], At[m][k], acc[ai][bj][m][n], 0, 0, 0); __builtin_amdgcn_s_setprio(0); } while (0)
; #define PG8_WAIT_V(n) asm volatile("s_waitcnt vmcnt(" #n ")" ::: "memory")
; #define PG8_WAIT_L(n) asm volatile("s_waitcnt lgkmcnt(" #n ")" ::: "memory")
; #define PG8_BAR __builtin_amdgcn_s_barrier()
; #define PG8_SCHED __builtin_amdgcn_sched_barrier(0)
; template <class Epi>
; __device__ __forceinline__ void gemm_phase(LAS unsigned char* lds, const Gemm g, const StaticOrder& S, const Epi& E) {
;     ...
;             PG8_BAR; PG8_WAIT_L(0); PG8_MMA(1, 0, At, B0); PG8_BAR; PG8_SCHED;
;             PG8_STAGE(PG8_SB(1, 1), b2 + KS, hB, 0);
;             PG8_WAIT_V(6); PG8_BAR; PG8_MMA(1, 1, At, B1); PG8_BAR;
	s_waitcnt lgkmcnt(0)
	s_waitcnt lgkmcnt(7)
	v_mfma_f32_16x16x32_bf16 v[60:63], v[136:139], v[152:155], v[60:63]
	v_mfma_f32_16x16x32_bf16 v[56:59], v[144:147], v[152:155], v[56:59]
	s_waitcnt lgkmcnt(5)
	v_mfma_f32_16x16x32_bf16 v[52:55], v[136:139], v[160:163], v[52:55]
	v_mfma_f32_16x16x32_bf16 v[44:47], v[144:147], v[160:163], v[44:47]
	s_waitcnt lgkmcnt(3)
	v_mfma_f32_16x16x32_bf16 v[36:39], v[136:139], v[168:171], v[36:39]
	v_mfma_f32_16x16x32_bf16 v[28:31], v[144:147], v[168:171], v[28:31]
	s_waitcnt lgkmcnt(1)
	v_mfma_f32_16x16x32_bf16 v[20:23], v[136:139], v[176:179], v[20:23]
	v_mfma_f32_16x16x32_bf16 v[12:15], v[144:147], v[176:179], v[12:15]
	v_mfma_f32_16x16x32_bf16 v[60:63], v[140:143], v[156:159], v[60:63]
	v_mfma_f32_16x16x32_bf16 v[56:59], v[148:151], v[156:159], v[56:59]
	v_mfma_f32_16x16x32_bf16 v[52:55], v[140:143], v[164:167], v[52:55]
	v_mfma_f32_16x16x32_bf16 v[44:47], v[148:151], v[164:167], v[44:47]
	v_mfma_f32_16x16x32_bf16 v[36:39], v[140:143], v[172:175], v[36:39]
	v_mfma_f32_16x16x32_bf16 v[28:31], v[148:151], v[172:175], v[28:31]
	s_waitcnt lgkmcnt(0)
	v_mfma_f32_16x16x32_bf16 v[20:23], v[140:143], v[180:183], v[20:23]
	v_mfma_f32_16x16x32_bf16 v[12:15], v[148:151], v[180:183], v[12:15]
	s_barrier
	s_add_u32 s54, s58, 0x84000
	s_addc_u32 s55, s59, 0
	s_mov_b32 m0, s42
	s_nop 0
	global_load_lds_dwordx4 v130, s[54:55]
	s_add_u32 s54, s58, 0x86000
	s_addc_u32 s55, s59, 0
	s_mov_b32 m0, s43
	s_nop 0
	global_load_lds_dwordx4 v130, s[54:55]
	s_waitcnt vmcnt(10)
	s_barrier
	v_mfma_f32_16x16x32_bf16 v[48:51], v[184:187], v[152:155], v[48:51]
	v_mfma_f32_16x16x32_bf16 v[40:43], v[204:207], v[152:155], v[40:43]
	v_mfma_f32_16x16x32_bf16 v[32:35], v[184:187], v[160:163], v[32:35]
	v_mfma_f32_16x16x32_bf16 v[24:27], v[204:207], v[160:163], v[24:27]
	v_mfma_f32_16x16x32_bf16 v[16:19], v[184:187], v[168:171], v[16:19]
	v_mfma_f32_16x16x32_bf16 v[8:11], v[204:207], v[168:171], v[8:11]
	v_mfma_f32_16x16x32_bf16 v[4:7], v[184:187], v[176:179], v[4:7]
	v_mfma_f32_16x16x32_bf16 v[0:3], v[204:207], v[176:179], v[0:3]
	v_mfma_f32_16x16x32_bf16 v[48:51], v[200:203], v[156:159], v[48:51]
	v_mfma_f32_16x16x32_bf16 v[40:43], v[208:211], v[156:159], v[40:43]
	v_mfma_f32_16x16x32_bf16 v[32:35], v[200:203], v[164:167], v[32:35]
	v_mfma_f32_16x16x32_bf16 v[24:27], v[208:211], v[164:167], v[24:27]
	v_mfma_f32_16x16x32_bf16 v[16:19], v[200:203], v[172:175], v[16:19]
	v_mfma_f32_16x16x32_bf16 v[8:11], v[208:211], v[172:175], v[8:11]
	v_mfma_f32_16x16x32_bf16 v[4:7], v[200:203], v[180:183], v[4:7]
	v_mfma_f32_16x16x32_bf16 v[0:3], v[208:211], v[180:183], v[0:3]
	s_add_i32 s65, s65, 2
	s_add_u32 s63, s63, 0x8000
	s_addc_u32 s64, s64, 0
	s_cmp_gt_u32 s65, 29
	s_mov_b64 s[54:55], s[56:57]
	s_barrier
	s_cbranch_scc0 .LBB0_434
; __device__ __forceinline__ unsigned cvt_pk_bf16(float lo, float hi) { unsigned r; asm volatile("v_cvt_pk_bf16_f32 %0, %1, %2" : "=v"(r) : "v"(lo), "v"(hi)); return r; }
; #define PG8_WAIT_V(n) asm volatile("s_waitcnt vmcnt(" #n ")" ::: "memory")
; #define PG8_BAR __builtin_amdgcn_s_barrier()
; template <class Epi>
; __device__ __forceinline__ void gemm_phase(LAS unsigned char* lds, const Gemm g, const StaticOrder& S, const Epi& E) {
;     ...
;         if (!has_next) break;
; #pragma unroll
;         for (int a = 0; a < 2; ++a)
; #pragma unroll
;             for (int b = 0; b < 2; ++b)
; #pragma unroll
;                 for (int m = 0; m < 4; ++m)
; #pragma unroll
;                     for (int n = 0; n < 2; ++n) acc[a][b][m][n] = (f32x4){0.f, 0.f, 0.f, 0.f};
;         cur = nxt; cA = nA; cB = nB; ++ui;
;     }
;     PG8_WAIT_V(0);
;     if (wr == 0) PG8_BAR;
;     PG8_BAR;
;     __device__ __forceinline__ void operator()(f32x4 (&acc)[2][2][4][2], const Unit& u, int wr, int wc, int fr, int fq, LAS unsigned char*) const {
;         const int row0 = u.pm * BM + wr * 64 + fr, col0 = u.pn * BM + wc * 32 + 8 * fq;
; #pragma unroll
;         for (int ai = 0; ai < 2; ++ai)
; #pragma unroll
;             for (int m = 0; m < 4; ++m) { bf16_t* rowp = O + (size_t)(row0 + ai * HALF + m * 16) * ldc + col0;
; #pragma unroll
;                 for (int bj = 0; bj < 2; ++bj) { const f32x4 v0 = acc[ai][bj][m][0], v1 = acc[ai][bj][m][1];
;                     u32x4 w; w.x = cvt_pk_bf16(v0[0], v0[1]); w.y = cvt_pk_bf16(v0[2], v0[3]); w.z = cvt_pk_bf16(v1[0], v1[1]); w.w = cvt_pk_bf16(v1[2], v1[3]);
;                     *(u32x4*)(rowp + bj * HALF) = w; } }
	v_lshl_add_u32 v136, s62, 8, v131
	v_lshl_or_b32 v128, s61, 8, v132
	v_ashrrev_i32_e32 v137, 31, v136
	v_ashrrev_i32_e32 v129, 31, v128
	v_lshlrev_b64 v[138:139], 12, v[136:137]
	v_lshl_add_u64 v[138:139], s[2:3], 0, v[138:139]
	v_lshlrev_b64 v[140:141], 1, v[128:129]
	v_lshl_add_u64 v[128:129], v[138:139], 0, v[140:141]
	v_cvt_pk_bf16_f32 v124, v124, v125
	v_cvt_pk_bf16_f32 v125, v126, v127
	v_cvt_pk_bf16_f32 v126, v120, v121
	v_cvt_pk_bf16_f32 v127, v122, v123
	global_store_dwordx4 v[128:129], v[124:127], off
	v_cvt_pk_bf16_f32 v112, v112, v113
	v_cvt_pk_bf16_f32 v113, v114, v115
	v_cvt_pk_bf16_f32 v114, v104, v105
	v_or_b32_e32 v104, 16, v136
	v_ashrrev_i32_e32 v105, 31, v104
	v_lshlrev_b64 v[104:105], 12, v[104:105]
	v_lshl_add_u64 v[104:105], s[2:3], 0, v[104:105]
	v_cvt_pk_bf16_f32 v115, v106, v107
	global_store_dwordx4 v[128:129], v[112:115], off offset:256
	s_mov_b64 s[0:1], 0x80000
	s_mov_b32 s61, s6
	v_lshl_add_u64 v[112:113], v[104:105], 0, v[140:141]
	v_cvt_pk_bf16_f32 v104, v116, v117
	v_cvt_pk_bf16_f32 v105, v118, v119
	v_cvt_pk_bf16_f32 v106, v108, v109
	v_cvt_pk_bf16_f32 v107, v110, v111
	global_store_dwordx4 v[112:113], v[104:107], off
	v_cvt_pk_bf16_f32 v96, v96, v97
	v_cvt_pk_bf16_f32 v97, v98, v99
	v_cvt_pk_bf16_f32 v98, v88, v89
	v_or_b32_e32 v88, 32, v136
	v_ashrrev_i32_e32 v89, 31, v88
	v_lshlrev_b64 v[88:89], 12, v[88:89]
	v_lshl_add_u64 v[88:89], s[2:3], 0, v[88:89]
	v_cvt_pk_bf16_f32 v99, v90, v91
	global_store_dwordx4 v[112:113], v[96:99], off offset:256
	s_mov_b32 s62, s8
	s_mov_b64 s[56:57], s[52:53]
	v_lshl_add_u64 v[96:97], v[88:89], 0, v[140:141]
	v_cvt_pk_bf16_f32 v88, v100, v101
	v_cvt_pk_bf16_f32 v89, v102, v103
	v_cvt_pk_bf16_f32 v90, v92, v93
	v_cvt_pk_bf16_f32 v91, v94, v95
	global_store_dwordx4 v[96:97], v[88:91], off
	v_cvt_pk_bf16_f32 v80, v80, v81
	v_cvt_pk_bf16_f32 v81, v82, v83
	v_cvt_pk_bf16_f32 v82, v72, v73
	v_or_b32_e32 v72, 48, v136
	v_ashrrev_i32_e32 v73, 31, v72
	v_lshlrev_b64 v[72:73], 12, v[72:73]
	v_lshl_add_u64 v[72:73], s[2:3], 0, v[72:73]
	v_cvt_pk_bf16_f32 v83, v74, v75
	global_store_dwordx4 v[96:97], v[80:83], off offset:256
	s_mov_b64 s[54:55], s[10:11]
	s_nop 0
	v_lshl_add_u64 v[80:81], v[72:73], 0, v[140:141]
	v_cvt_pk_bf16_f32 v72, v84, v85
	v_cvt_pk_bf16_f32 v73, v86, v87
	v_cvt_pk_bf16_f32 v74, v76, v77
	v_cvt_pk_bf16_f32 v75, v78, v79
	global_store_dwordx4 v[80:81], v[72:75], off
	v_cvt_pk_bf16_f32 v68, v68, v69
	v_cvt_pk_bf16_f32 v69, v70, v71
	v_cvt_pk_bf16_f32 v70, v64, v65
	v_cvt_pk_bf16_f32 v71, v66, v67
	global_store_dwordx4 v[80:81], v[68:71], off offset:256
	v_cvt_pk_bf16_f32 v60, v60, v61
	v_cvt_pk_bf16_f32 v61, v62, v63
	v_cvt_pk_bf16_f32 v62, v56, v57
	v_add_co_u32_e32 v56, vcc, s93, v128
	v_lshl_add_u64 v[64:65], v[128:129], 0, s[0:1]
	s_nop 0
	v_addc_co_u32_e32 v57, vcc, 0, v129, vcc
	v_cvt_pk_bf16_f32 v63, v58, v59
	global_store_dwordx4 v[56:57], v[60:63], off
	v_cvt_pk_bf16_f32 v48, v48, v49
	v_cvt_pk_bf16_f32 v49, v50, v51
	v_cvt_pk_bf16_f32 v50, v40, v41
	v_cvt_pk_bf16_f32 v51, v42, v43
	global_store_dwordx4 v[64:65], v[48:51], off offset:256
	s_mov_b64 s[0:1], 0x90000
	v_cvt_pk_bf16_f32 v40, v52, v53
	v_cvt_pk_bf16_f32 v41, v54, v55
	v_cvt_pk_bf16_f32 v42, v44, v45
	v_add_co_u32_e32 v44, vcc, s33, v128
	v_lshl_add_u64 v[48:49], v[128:129], 0, s[0:1]
	s_nop 0
	v_addc_co_u32_e32 v45, vcc, 0, v129, vcc
	v_cvt_pk_bf16_f32 v43, v46, v47
	global_store_dwordx4 v[44:45], v[40:43], off
	v_cvt_pk_bf16_f32 v32, v32, v33
	v_cvt_pk_bf16_f32 v33, v34, v35
	v_cvt_pk_bf16_f32 v34, v24, v25
	v_cvt_pk_bf16_f32 v35, v26, v27
	global_store_dwordx4 v[48:49], v[32:35], off offset:256
	s_mov_b64 s[0:1], 0xa0000
	v_cvt_pk_bf16_f32 v24, v36, v37
	v_cvt_pk_bf16_f32 v25, v38, v39
	v_cvt_pk_bf16_f32 v26, v28, v29
	v_add_co_u32_e32 v28, vcc, s18, v128
	v_lshl_add_u64 v[32:33], v[128:129], 0, s[0:1]
	s_nop 0
	v_addc_co_u32_e32 v29, vcc, 0, v129, vcc
	v_cvt_pk_bf16_f32 v27, v30, v31
	global_store_dwordx4 v[28:29], v[24:27], off
	v_cvt_pk_bf16_f32 v16, v16, v17
	v_cvt_pk_bf16_f32 v17, v18, v19
	v_cvt_pk_bf16_f32 v18, v8, v9
	v_cvt_pk_bf16_f32 v19, v10, v11
	global_store_dwordx4 v[32:33], v[16:19], off offset:256
	v_cvt_pk_bf16_f32 v8, v20, v21
	v_cvt_pk_bf16_f32 v9, v22, v23
	v_cvt_pk_bf16_f32 v10, v12, v13
	v_add_co_u32_e32 v12, vcc, s19, v128
	s_mov_b64 s[0:1], 0xb0000
	s_nop 0
	v_addc_co_u32_e32 v13, vcc, 0, v129, vcc
	v_lshl_add_u64 v[16:17], v[128:129], 0, s[0:1]
	s_and_b64 vcc, exec, s[4:5]
	v_cvt_pk_bf16_f32 v11, v14, v15
	global_store_dwordx4 v[12:13], v[8:11], off
	v_cvt_pk_bf16_f32 v4, v4, v5
	v_cvt_pk_bf16_f32 v5, v6, v7
	v_cvt_pk_bf16_f32 v6, v0, v1
	v_cvt_pk_bf16_f32 v7, v2, v3
	global_store_dwordx4 v[16:17], v[4:7], off offset:256
	s_cbranch_vccz .LBB0_427
	s_waitcnt vmcnt(0)
	s_cmpk_gt_u32 s16, 0xff
	v_readlane_b32 s38, v255, 44
	s_cbranch_scc1 .LBB0_438
	s_barrier

; #define PG8_STAGE(bufoff, gbase, hoff, imm) do { _Pragma("unroll") for (int _i = 0; _i < 2; ++_i) { \
;         asm volatile("s_mov_b32 m0, %0\n\ts_nop 0\n\tglobal_load_lds_dwordx4 %1, %2" \
;             :: "s"(lds0 + (unsigned)((bufoff) + _i * 8192)), "v"(voff0), "s"((const char*)(gbase) + (size_t)(hoff) + (size_t)(_i * 8192)) : "memory"); } } while (0)
; #define PG8_LDA(dst, b, h) do { _Pragma("unroll") for (int m = 0; m < 4; ++m) _Pragma("unroll") for (int k = 0; k < 2; ++k) dst[m][k] = *(const LAS bf16x8*)(lds + PG8_SA(b, h) + aoff + m * 2048 + k * 1024); } while (0)
; #define PG8_LDB(dst, b, h) do { _Pragma("unroll") for (int n = 0; n < 2; ++n) _Pragma("unroll") for (int k = 0; k < 2; ++k) dst[n][k] = *(const LAS bf16x8*)(lds + PG8_SB(b, h) + boff + n * 2048 + k * 1024); } while (0)
; #define PG8_MMA(ai, bj, At, Bt) do { __builtin_amdgcn_s_setprio(1); _Pragma("unroll") for (int m = 0; m < 4; ++m) _Pragma("unroll") for (int n = 0; n < 2; ++n) _Pragma("unroll") for (int k = 0; k < 2; ++k) \
;         acc[ai][bj][m][n] = __builtin_amdgcn_mfma_f32_16x16x32_bf16(Bt[n][k], At[m][k], acc[ai][bj][m][n], 0, 0, 0); __builtin_amdgcn_s_setprio(0); } while (0)
; #define PG8_WAIT_L(n) asm volatile("s_waitcnt lgkmcnt(" #n ")" ::: "memory")
; #define PG8_BAR __builtin_amdgcn_s_barrier()
; #define PG8_SCHED __builtin_amdgcn_sched_barrier(0)
; template <class Epi>
; __device__ __forceinline__ void gemm_phase(LAS unsigned char* lds, const Gemm g, const StaticOrder& S, const Epi& E) {
;     ...
;             const char* aT = cA + (size_t)t * KS;
;             const char* a2 = last ? nA : aT + 2 * KS; const char* b2 = last ? nB : cB + (size_t)(t + 2) * KS;
;             PG8_LDB(B0, 0, 0); PG8_SCHED; PG8_LDA(At, 0, 0); PG8_STAGE(PG8_SA(1, 1), aT + KS, hA, 0);
;             PG8_WAIT_L(8); PG8_BAR; PG8_WAIT_L(0); PG8_MMA(0, 0, At, B0); PG8_BAR; PG8_SCHED;
;             PG8_LDB(B1, 0, 1); PG8_STAGE(PG8_SB(0, 0), b2, 0, 0);
;             PG8_BAR; PG8_WAIT_L(0); PG8_MMA(0, 1, At, B1); PG8_BAR;
;             PG8_LDA(At, 0, 1); PG8_STAGE(PG8_SA(0, 0), a2, 0, 0);
;             PG8_BAR; PG8_WAIT_L(0); PG8_MMA(1, 0, At, B0); PG8_BAR; PG8_SCHED;
.LBB0_506:
	v_add_u32_e32 v140, 0x10000, v202
	ds_read_b128 v[128:131], v140
	ds_read_b128 v[132:135], v140 offset:1024
	ds_read_b128 v[136:139], v140 offset:2048
	ds_read_b128 v[140:143], v140 offset:3072
	s_add_u32 s80, s78, 0x8000
	s_addc_u32 s81, s79, 0
	s_and_b64 s[82:83], s[84:85], exec
	s_cselect_b32 s83, s51, s81
	s_cselect_b32 s82, s71, s80
	ds_read_b128 v[144:147], v203
	ds_read_b128 v[148:151], v203 offset:1024
	ds_read_b128 v[152:155], v203 offset:2048
	ds_read_b128 v[156:159], v203 offset:3072
	ds_read_b128 v[160:163], v203 offset:4096
	ds_read_b128 v[164:167], v203 offset:5120
	ds_read_b128 v[204:207], v203 offset:6144
	ds_read_b128 v[208:211], v203 offset:7168
	s_add_u32 s48, s78, 0x84000
	s_addc_u32 s49, s79, 0
	s_mov_b32 m0, s87
	s_nop 0
	global_load_lds_dwordx4 v168, s[48:49]
	s_add_u32 s48, s78, 0x86000
	s_addc_u32 s49, s79, 0
	s_mov_b32 m0, s96
	s_nop 0
	global_load_lds_dwordx4 v168, s[48:49]
	s_waitcnt lgkmcnt(8)
	s_waitcnt vmcnt(10)
	s_barrier
	s_waitcnt lgkmcnt(0)
	s_waitcnt lgkmcnt(7)
	v_mfma_f32_16x16x32_bf16 v[96:99], v[128:131], v[144:147], v[96:99]
	v_mfma_f32_16x16x32_bf16 v[44:47], v[136:139], v[144:147], v[44:47]
	s_waitcnt lgkmcnt(5)
	v_mfma_f32_16x16x32_bf16 v[92:95], v[128:131], v[152:155], v[92:95]
	v_mfma_f32_16x16x32_bf16 v[40:43], v[136:139], v[152:155], v[40:43]
	s_waitcnt lgkmcnt(3)
	v_mfma_f32_16x16x32_bf16 v[84:87], v[128:131], v[160:163], v[84:87]
	v_mfma_f32_16x16x32_bf16 v[36:39], v[136:139], v[160:163], v[36:39]
	s_waitcnt lgkmcnt(1)
	v_mfma_f32_16x16x32_bf16 v[124:127], v[128:131], v[204:207], v[124:127]
	v_mfma_f32_16x16x32_bf16 v[120:123], v[136:139], v[204:207], v[120:123]
	v_mfma_f32_16x16x32_bf16 v[96:99], v[132:135], v[148:151], v[96:99]
	v_mfma_f32_16x16x32_bf16 v[44:47], v[140:143], v[148:151], v[44:47]
	v_mfma_f32_16x16x32_bf16 v[92:95], v[132:135], v[156:159], v[92:95]
	v_mfma_f32_16x16x32_bf16 v[40:43], v[140:143], v[156:159], v[40:43]
	v_mfma_f32_16x16x32_bf16 v[84:87], v[132:135], v[164:167], v[84:87]
	v_mfma_f32_16x16x32_bf16 v[36:39], v[140:143], v[164:167], v[36:39]
	s_waitcnt lgkmcnt(0)
	v_mfma_f32_16x16x32_bf16 v[124:127], v[132:135], v[208:211], v[124:127]
	v_mfma_f32_16x16x32_bf16 v[120:123], v[140:143], v[208:211], v[120:123]
	s_barrier
	v_add_u32_e32 v188, 0x14000, v202
	ds_read_b128 v[212:215], v188
	ds_read_b128 v[236:239], v188 offset:1024
	ds_read_b128 v[240:243], v188 offset:2048
	ds_read_b128 v[244:247], v188 offset:3072
	s_and_b64 s[48:49], s[84:85], exec
	s_cselect_b32 s78, s62, s9
	s_cselect_b32 s79, s69, s63
	s_mov_b32 m0, s25
	s_nop 0
	global_load_lds_dwordx4 v168, s[78:79]
	s_add_u32 s48, s78, 0x2000
	s_addc_u32 s49, s79, 0
	s_mov_b32 m0, s26
	s_nop 0
	global_load_lds_dwordx4 v168, s[48:49]
	s_waitcnt vmcnt(10)
	s_barrier
	s_waitcnt lgkmcnt(0)
	s_waitcnt lgkmcnt(3)
	v_mfma_f32_16x16x32_bf16 v[80:83], v[212:215], v[144:147], v[80:83]
	s_waitcnt lgkmcnt(1)
	v_mfma_f32_16x16x32_bf16 v[32:35], v[240:243], v[144:147], v[32:35]
	v_mfma_f32_16x16x32_bf16 v[76:79], v[212:215], v[152:155], v[76:79]
	v_mfma_f32_16x16x32_bf16 v[28:31], v[240:243], v[152:155], v[28:31]
	v_mfma_f32_16x16x32_bf16 v[72:75], v[212:215], v[160:163], v[72:75]
	v_mfma_f32_16x16x32_bf16 v[24:27], v[240:243], v[160:163], v[24:27]
	v_mfma_f32_16x16x32_bf16 v[116:119], v[212:215], v[204:207], v[116:119]
	v_mfma_f32_16x16x32_bf16 v[112:115], v[240:243], v[204:207], v[112:115]
	v_mfma_f32_16x16x32_bf16 v[80:83], v[236:239], v[148:151], v[80:83]
	s_waitcnt lgkmcnt(0)
	v_mfma_f32_16x16x32_bf16 v[32:35], v[244:247], v[148:151], v[32:35]
	v_mfma_f32_16x16x32_bf16 v[76:79], v[236:239], v[156:159], v[76:79]
	v_mfma_f32_16x16x32_bf16 v[28:31], v[244:247], v[156:159], v[28:31]
	v_mfma_f32_16x16x32_bf16 v[72:75], v[236:239], v[164:167], v[72:75]
	v_mfma_f32_16x16x32_bf16 v[24:27], v[244:247], v[164:167], v[24:27]
	v_mfma_f32_16x16x32_bf16 v[116:119], v[236:239], v[208:211], v[116:119]
	v_mfma_f32_16x16x32_bf16 v[112:115], v[244:247], v[208:211], v[112:115]
	s_barrier
	ds_read_b128 v[144:147], v203 offset:16384
	ds_read_b128 v[148:151], v203 offset:17408
	ds_read_b128 v[152:155], v203 offset:18432
	ds_read_b128 v[156:159], v203 offset:19456
	ds_read_b128 v[160:163], v203 offset:20480
	ds_read_b128 v[164:167], v203 offset:21504
	ds_read_b128 v[204:207], v203 offset:22528
	ds_read_b128 v[208:211], v203 offset:23552
	s_mov_b32 m0, s24
	s_nop 0
	global_load_lds_dwordx4 v168, s[82:83]
	s_add_u32 s48, s82, 0x2000
	s_addc_u32 s49, s83, 0
	s_mov_b32 m0, s27
	s_nop 0
	global_load_lds_dwordx4 v168, s[48:49]
	s_barrier
	s_waitcnt lgkmcnt(0)
	s_waitcnt lgkmcnt(7)
	v_mfma_f32_16x16x32_bf16 v[68:71], v[128:131], v[144:147], v[68:71]
	v_mfma_f32_16x16x32_bf16 v[20:23], v[136:139], v[144:147], v[20:23]
	s_waitcnt lgkmcnt(5)
	v_mfma_f32_16x16x32_bf16 v[64:67], v[128:131], v[152:155], v[64:67]
	v_mfma_f32_16x16x32_bf16 v[16:19], v[136:139], v[152:155], v[16:19]
	s_waitcnt lgkmcnt(3)
	v_mfma_f32_16x16x32_bf16 v[60:63], v[128:131], v[160:163], v[60:63]
	v_mfma_f32_16x16x32_bf16 v[12:15], v[136:139], v[160:163], v[12:15]
	s_waitcnt lgkmcnt(1)
	v_mfma_f32_16x16x32_bf16 v[108:111], v[128:131], v[204:207], v[108:111]
	v_mfma_f32_16x16x32_bf16 v[104:107], v[136:139], v[204:207], v[104:107]
	v_mfma_f32_16x16x32_bf16 v[68:71], v[132:135], v[148:151], v[68:71]
	v_mfma_f32_16x16x32_bf16 v[20:23], v[140:143], v[148:151], v[20:23]
	v_mfma_f32_16x16x32_bf16 v[64:67], v[132:135], v[156:159], v[64:67]
	v_mfma_f32_16x16x32_bf16 v[16:19], v[140:143], v[156:159], v[16:19]
	v_mfma_f32_16x16x32_bf16 v[60:63], v[132:135], v[164:167], v[60:63]
	v_mfma_f32_16x16x32_bf16 v[12:15], v[140:143], v[164:167], v[12:15]
	s_waitcnt lgkmcnt(0)
	v_mfma_f32_16x16x32_bf16 v[108:111], v[132:135], v[208:211], v[108:111]
	v_mfma_f32_16x16x32_bf16 v[104:107], v[140:143], v[208:211], v[104:107]
	s_barrier
; #define PG8_STAGE(bufoff, gbase, hoff, imm) do { _Pragma("unroll") for (int _i = 0; _i < 2; ++_i) { \
;         asm volatile("s_mov_b32 m0, %0\n\ts_nop 0\n\tglobal_load_lds_dwordx4 %1, %2" \
;             :: "s"(lds0 + (unsigned)((bufoff) + _i * 8192)), "v"(voff0), "s"((const char*)(gbase) + (size_t)(hoff) + (size_t)(_i * 8192)) : "memory"); } } while (0)
; #define PG8_LDA(dst, b, h) do { _Pragma("unroll") for (int m = 0; m < 4; ++m) _Pragma("unroll") for (int k = 0; k < 2; ++k) dst[m][k] = *(const LAS bf16x8*)(lds + PG8_SA(b, h) + aoff + m * 2048 + k * 1024); } while (0)
; #define PG8_LDB(dst, b, h) do { _Pragma("unroll") for (int n = 0; n < 2; ++n) _Pragma("unroll") for (int k = 0; k < 2; ++k) dst[n][k] = *(const LAS bf16x8*)(lds + PG8_SB(b, h) + boff + n * 2048 + k * 1024); } while (0)
; #define PG8_MMA(ai, bj, At, Bt) do { __builtin_amdgcn_s_setprio(1); _Pragma("unroll") for (int m = 0; m < 4; ++m) _Pragma("unroll") for (int n = 0; n < 2; ++n) _Pragma("unroll") for (int k = 0; k < 2; ++k) \
;         acc[ai][bj][m][n] = __builtin_amdgcn_mfma_f32_16x16x32_bf16(Bt[n][k], At[m][k], acc[ai][bj][m][n], 0, 0, 0); __builtin_amdgcn_s_setprio(0); } while (0)
; #define PG8_WAIT_V(n) asm volatile("s_waitcnt vmcnt(" #n ")" ::: "memory")
; #define PG8_WAIT_L(n) asm volatile("s_waitcnt lgkmcnt(" #n ")" ::: "memory")
; #define PG8_BAR __builtin_amdgcn_s_barrier()
; #define PG8_SCHED __builtin_amdgcn_sched_barrier(0)
; template <class Epi>
; __device__ __forceinline__ void gemm_phase(LAS unsigned char* lds, const Gemm g, const StaticOrder& S, const Epi& E) {
;     ...
;             PG8_STAGE(PG8_SB(0, 1), b2, hB, 0);
;             PG8_WAIT_V(6); PG8_BAR; PG8_MMA(1, 1, At, B1); PG8_BAR;
;             PG8_LDB(B0, 1, 0); PG8_SCHED; PG8_LDA(At, 1, 0); PG8_STAGE(PG8_SA(0, 1), a2, hA, 0);
;             PG8_WAIT_L(8); PG8_BAR; PG8_WAIT_L(0); PG8_MMA(0, 0, At, B0); PG8_BAR; PG8_SCHED;
;             PG8_LDB(B1, 1, 1); PG8_STAGE(PG8_SB(1, 0), b2 + KS, 0, 0);
	s_add_u32 s48, s78, 0x80000
	s_addc_u32 s49, s79, 0
	s_mov_b32 m0, s28
	s_nop 0
	global_load_lds_dwordx4 v168, s[48:49]
	s_add_u32 s48, s78, 0x82000
	s_addc_u32 s49, s79, 0
	s_mov_b32 m0, s29
	s_nop 0
	global_load_lds_dwordx4 v168, s[48:49]
	s_waitcnt vmcnt(10)
	s_barrier
	v_mfma_f32_16x16x32_bf16 v[56:59], v[212:215], v[144:147], v[56:59]
	v_mfma_f32_16x16x32_bf16 v[8:11], v[240:243], v[144:147], v[8:11]
	v_mfma_f32_16x16x32_bf16 v[52:55], v[212:215], v[152:155], v[52:55]
	v_mfma_f32_16x16x32_bf16 v[4:7], v[240:243], v[152:155], v[4:7]
	v_mfma_f32_16x16x32_bf16 v[48:51], v[212:215], v[160:163], v[48:51]
	v_mfma_f32_16x16x32_bf16 v[0:3], v[240:243], v[160:163], v[0:3]
	v_mfma_f32_16x16x32_bf16 v[100:103], v[212:215], v[204:207], v[100:103]
	v_mfma_f32_16x16x32_bf16 v[88:91], v[240:243], v[204:207], v[88:91]
	v_mfma_f32_16x16x32_bf16 v[56:59], v[236:239], v[148:151], v[56:59]
	v_mfma_f32_16x16x32_bf16 v[8:11], v[244:247], v[148:151], v[8:11]
	v_mfma_f32_16x16x32_bf16 v[52:55], v[236:239], v[156:159], v[52:55]
	v_mfma_f32_16x16x32_bf16 v[4:7], v[244:247], v[156:159], v[4:7]
	v_mfma_f32_16x16x32_bf16 v[48:51], v[236:239], v[164:167], v[48:51]
	v_mfma_f32_16x16x32_bf16 v[0:3], v[244:247], v[164:167], v[0:3]
	v_mfma_f32_16x16x32_bf16 v[100:103], v[236:239], v[208:211], v[100:103]
	v_mfma_f32_16x16x32_bf16 v[88:91], v[244:247], v[208:211], v[88:91]
	v_add_u32_e32 v140, 0x18000, v202
	s_barrier
	ds_read_b128 v[128:131], v140
	ds_read_b128 v[132:135], v140 offset:1024
	ds_read_b128 v[136:139], v140 offset:2048
	ds_read_b128 v[140:143], v140 offset:3072
	ds_read_b128 v[144:147], v203 offset:32768
	ds_read_b128 v[148:151], v203 offset:33792
	ds_read_b128 v[152:155], v203 offset:34816
	ds_read_b128 v[156:159], v203 offset:35840
	ds_read_b128 v[160:163], v203 offset:36864
	ds_read_b128 v[164:167], v203 offset:37888
	ds_read_b128 v[204:207], v203 offset:38912
	ds_read_b128 v[208:211], v203 offset:39936
	s_add_u32 s48, s82, 0x80000
	s_addc_u32 s49, s83, 0
	s_mov_b32 m0, s30
	s_nop 0
	global_load_lds_dwordx4 v168, s[48:49]
	s_add_u32 s48, s82, 0x82000
	s_addc_u32 s49, s83, 0
	s_mov_b32 m0, s34
	s_nop 0
	global_load_lds_dwordx4 v168, s[48:49]
	s_waitcnt lgkmcnt(8)
	s_waitcnt vmcnt(10)
	s_barrier
	s_waitcnt lgkmcnt(0)
	s_waitcnt lgkmcnt(7)
	v_mfma_f32_16x16x32_bf16 v[96:99], v[128:131], v[144:147], v[96:99]
	v_mfma_f32_16x16x32_bf16 v[44:47], v[136:139], v[144:147], v[44:47]
	s_waitcnt lgkmcnt(5)
	v_mfma_f32_16x16x32_bf16 v[92:95], v[128:131], v[152:155], v[92:95]
	v_mfma_f32_16x16x32_bf16 v[40:43], v[136:139], v[152:155], v[40:43]
	s_waitcnt lgkmcnt(3)
	v_mfma_f32_16x16x32_bf16 v[84:87], v[128:131], v[160:163], v[84:87]
	v_mfma_f32_16x16x32_bf16 v[36:39], v[136:139], v[160:163], v[36:39]
	s_waitcnt lgkmcnt(1)
	v_mfma_f32_16x16x32_bf16 v[124:127], v[128:131], v[204:207], v[124:127]
	v_mfma_f32_16x16x32_bf16 v[120:123], v[136:139], v[204:207], v[120:123]
	v_mfma_f32_16x16x32_bf16 v[96:99], v[132:135], v[148:151], v[96:99]
	v_mfma_f32_16x16x32_bf16 v[44:47], v[140:143], v[148:151], v[44:47]
	v_mfma_f32_16x16x32_bf16 v[92:95], v[132:135], v[156:159], v[92:95]
	v_mfma_f32_16x16x32_bf16 v[40:43], v[140:143], v[156:159], v[40:43]
	v_mfma_f32_16x16x32_bf16 v[84:87], v[132:135], v[164:167], v[84:87]
	v_mfma_f32_16x16x32_bf16 v[36:39], v[140:143], v[164:167], v[36:39]
	s_waitcnt lgkmcnt(0)
	v_mfma_f32_16x16x32_bf16 v[124:127], v[132:135], v[208:211], v[124:127]
	v_mfma_f32_16x16x32_bf16 v[120:123], v[140:143], v[208:211], v[120:123]
	s_barrier
	v_add_u32_e32 v188, 0x1c000, v202
	ds_read_b128 v[212:215], v188
	ds_read_b128 v[236:239], v188 offset:1024
	ds_read_b128 v[240:243], v188 offset:2048
	ds_read_b128 v[244:247], v188 offset:3072
	s_add_u32 s48, s78, 0x4000
	s_addc_u32 s49, s79, 0
	s_mov_b32 m0, s38
	s_nop 0
	global_load_lds_dwordx4 v168, s[48:49]
	s_add_u32 s48, s78, 0x6000
	s_addc_u32 s49, s79, 0
	s_mov_b32 m0, s39
	s_nop 0
	global_load_lds_dwordx4 v168, s[48:49]
	s_waitcnt vmcnt(10)
	s_barrier
; #define PG8_STAGE(bufoff, gbase, hoff, imm) do { _Pragma("unroll") for (int _i = 0; _i < 2; ++_i) { \
;         asm volatile("s_mov_b32 m0, %0\n\ts_nop 0\n\tglobal_load_lds_dwordx4 %1, %2" \
;             :: "s"(lds0 + (unsigned)((bufoff) + _i * 8192)), "v"(voff0), "s"((const char*)(gbase) + (size_t)(hoff) + (size_t)(_i * 8192)) : "memory"); } } while (0)
; #define PG8_LDA(dst, b, h) do { _Pragma("unroll") for (int m = 0; m < 4; ++m) _Pragma("unroll") for (int k = 0; k < 2; ++k) dst[m][k] = *(const LAS bf16x8*)(lds + PG8_SA(b, h) + aoff + m * 2048 + k * 1024); } while (0)
; #define PG8_MMA(ai, bj, At, Bt) do { __builtin_amdgcn_s_setprio(1); _Pragma("unroll") for (int m = 0; m < 4; ++m) _Pragma("unroll") for (int n = 0; n < 2; ++n) _Pragma("unroll") for (int k = 0; k < 2; ++k) \
;         acc[ai][bj][m][n] = __builtin_amdgcn_mfma_f32_16x16x32_bf16(Bt[n][k], At[m][k], acc[ai][bj][m][n], 0, 0, 0); __builtin_amdgcn_s_setprio(0); } while (0)
; #define PG8_WAIT_V(n) asm volatile("s_waitcnt vmcnt(" #n ")" ::: "memory")
; #define PG8_WAIT_L(n) asm volatile("s_waitcnt lgkmcnt(" #n ")" ::: "memory")
; #define PG8_BAR __builtin_amdgcn_s_barrier()
; #define PG8_SCHED __builtin_amdgcn_sched_barrier(0)
; template <class Epi>
; __device__ __forceinline__ void gemm_phase(LAS unsigned char* lds, const Gemm g, const StaticOrder& S, const Epi& E) {
;     ...
;             PG8_BAR; PG8_WAIT_L(0); PG8_MMA(0, 1, At, B1); PG8_BAR;
;             PG8_LDA(At, 1, 1); PG8_STAGE(PG8_SA(1, 0), a2 + KS, 0, 0);
;             PG8_BAR; PG8_WAIT_L(0); PG8_MMA(1, 0, At, B0); PG8_BAR; PG8_SCHED;
;             PG8_STAGE(PG8_SB(1, 1), b2 + KS, hB, 0);
;             PG8_WAIT_V(6); PG8_BAR; PG8_MMA(1, 1, At, B1); PG8_BAR;
	s_waitcnt lgkmcnt(0)
	s_waitcnt lgkmcnt(3)
	v_mfma_f32_16x16x32_bf16 v[80:83], v[212:215], v[144:147], v[80:83]
	s_waitcnt lgkmcnt(1)
	v_mfma_f32_16x16x32_bf16 v[32:35], v[240:243], v[144:147], v[32:35]
	v_mfma_f32_16x16x32_bf16 v[76:79], v[212:215], v[152:155], v[76:79]
	v_mfma_f32_16x16x32_bf16 v[28:31], v[240:243], v[152:155], v[28:31]
	v_mfma_f32_16x16x32_bf16 v[72:75], v[212:215], v[160:163], v[72:75]
	v_mfma_f32_16x16x32_bf16 v[24:27], v[240:243], v[160:163], v[24:27]
	v_mfma_f32_16x16x32_bf16 v[116:119], v[212:215], v[204:207], v[116:119]
	v_mfma_f32_16x16x32_bf16 v[112:115], v[240:243], v[204:207], v[112:115]
	v_mfma_f32_16x16x32_bf16 v[80:83], v[236:239], v[148:151], v[80:83]
	s_waitcnt lgkmcnt(0)
	v_mfma_f32_16x16x32_bf16 v[32:35], v[244:247], v[148:151], v[32:35]
	v_mfma_f32_16x16x32_bf16 v[76:79], v[236:239], v[156:159], v[76:79]
	v_mfma_f32_16x16x32_bf16 v[28:31], v[244:247], v[156:159], v[28:31]
	v_mfma_f32_16x16x32_bf16 v[72:75], v[236:239], v[164:167], v[72:75]
	v_mfma_f32_16x16x32_bf16 v[24:27], v[244:247], v[164:167], v[24:27]
	v_mfma_f32_16x16x32_bf16 v[116:119], v[236:239], v[208:211], v[116:119]
	v_mfma_f32_16x16x32_bf16 v[112:115], v[244:247], v[208:211], v[112:115]
	s_barrier
	ds_read_b128 v[144:147], v203 offset:49152
	ds_read_b128 v[148:151], v203 offset:50176
	ds_read_b128 v[152:155], v203 offset:51200
	ds_read_b128 v[156:159], v203 offset:52224
	ds_read_b128 v[160:163], v203 offset:53248
	ds_read_b128 v[164:167], v203 offset:54272
	ds_read_b128 v[204:207], v203 offset:55296
	ds_read_b128 v[208:211], v203 offset:56320
	s_add_u32 s48, s82, 0x4000
	s_addc_u32 s49, s83, 0
	s_mov_b32 m0, s40
	s_nop 0
	global_load_lds_dwordx4 v168, s[48:49]
	s_add_u32 s48, s82, 0x6000
	s_addc_u32 s49, s83, 0
	s_mov_b32 m0, s41
	s_nop 0
	global_load_lds_dwordx4 v168, s[48:49]
	s_barrier
	s_waitcnt lgkmcnt(0)
	s_waitcnt lgkmcnt(7)
	v_mfma_f32_16x16x32_bf16 v[68:71], v[128:131], v[144:147], v[68:71]
	v_mfma_f32_16x16x32_bf16 v[20:23], v[136:139], v[144:147], v[20:23]
	s_waitcnt lgkmcnt(5)
	v_mfma_f32_16x16x32_bf16 v[64:67], v[128:131], v[152:155], v[64:67]
	v_mfma_f32_16x16x32_bf16 v[16:19], v[136:139], v[152:155], v[16:19]
	s_waitcnt lgkmcnt(3)
	v_mfma_f32_16x16x32_bf16 v[60:63], v[128:131], v[160:163], v[60:63]
	v_mfma_f32_16x16x32_bf16 v[12:15], v[136:139], v[160:163], v[12:15]
	s_waitcnt lgkmcnt(1)
	v_mfma_f32_16x16x32_bf16 v[108:111], v[128:131], v[204:207], v[108:111]
	v_mfma_f32_16x16x32_bf16 v[104:107], v[136:139], v[204:207], v[104:107]
	v_mfma_f32_16x16x32_bf16 v[68:71], v[132:135], v[148:151], v[68:71]
	v_mfma_f32_16x16x32_bf16 v[20:23], v[140:143], v[148:151], v[20:23]
	v_mfma_f32_16x16x32_bf16 v[64:67], v[132:135], v[156:159], v[64:67]
	v_mfma_f32_16x16x32_bf16 v[16:19], v[140:143], v[156:159], v[16:19]
	v_mfma_f32_16x16x32_bf16 v[60:63], v[132:135], v[164:167], v[60:63]
	v_mfma_f32_16x16x32_bf16 v[12:15], v[140:143], v[164:167], v[12:15]
	s_waitcnt lgkmcnt(0)
	v_mfma_f32_16x16x32_bf16 v[108:111], v[132:135], v[208:211], v[108:111]
	v_mfma_f32_16x16x32_bf16 v[104:107], v[140:143], v[208:211], v[104:107]
	s_barrier
	s_add_u32 s48, s78, 0x84000
	s_addc_u32 s49, s79, 0
	s_mov_b32 m0, s42
	s_nop 0
	global_load_lds_dwordx4 v168, s[48:49]
	s_add_u32 s48, s78, 0x86000
	s_addc_u32 s49, s79, 0
	s_mov_b32 m0, s43
	s_nop 0
	global_load_lds_dwordx4 v168, s[48:49]
	s_waitcnt vmcnt(10)
	s_barrier
	v_mfma_f32_16x16x32_bf16 v[56:59], v[212:215], v[144:147], v[56:59]
	v_mfma_f32_16x16x32_bf16 v[8:11], v[240:243], v[144:147], v[8:11]
	v_mfma_f32_16x16x32_bf16 v[52:55], v[212:215], v[152:155], v[52:55]
	v_mfma_f32_16x16x32_bf16 v[4:7], v[240:243], v[152:155], v[4:7]
	v_mfma_f32_16x16x32_bf16 v[48:51], v[212:215], v[160:163], v[48:51]
	v_mfma_f32_16x16x32_bf16 v[0:3], v[240:243], v[160:163], v[0:3]
	v_mfma_f32_16x16x32_bf16 v[100:103], v[212:215], v[204:207], v[100:103]
	v_mfma_f32_16x16x32_bf16 v[88:91], v[240:243], v[204:207], v[88:91]
	v_mfma_f32_16x16x32_bf16 v[56:59], v[236:239], v[148:151], v[56:59]
	v_mfma_f32_16x16x32_bf16 v[8:11], v[244:247], v[148:151], v[8:11]
	v_mfma_f32_16x16x32_bf16 v[52:55], v[236:239], v[156:159], v[52:55]
	v_mfma_f32_16x16x32_bf16 v[4:7], v[244:247], v[156:159], v[4:7]
	v_mfma_f32_16x16x32_bf16 v[48:51], v[236:239], v[164:167], v[48:51]
	v_mfma_f32_16x16x32_bf16 v[0:3], v[244:247], v[164:167], v[0:3]
	v_mfma_f32_16x16x32_bf16 v[100:103], v[236:239], v[208:211], v[100:103]
	v_mfma_f32_16x16x32_bf16 v[88:91], v[244:247], v[208:211], v[88:91]
	s_add_i32 s0, s0, 2
	s_add_u32 s9, s9, 0x8000
	s_addc_u32 s63, s63, 0
	s_cmp_gt_u32 s0, 29
	s_mov_b64 s[78:79], s[80:81]
	s_barrier
	s_cbranch_scc1 .LBB0_509

; #define PG8_STAGE(bufoff, gbase, hoff, imm) do { _Pragma("unroll") for (int _i = 0; _i < 2; ++_i) { \
;         asm volatile("s_mov_b32 m0, %0\n\ts_nop 0\n\tglobal_load_lds_dwordx4 %1, %2" \
;             :: "s"(lds0 + (unsigned)((bufoff) + _i * 8192)), "v"(voff0), "s"((const char*)(gbase) + (size_t)(hoff) + (size_t)(_i * 8192)) : "memory"); } } while (0)
; #define PG8_LDA(dst, b, h) do { _Pragma("unroll") for (int m = 0; m < 4; ++m) _Pragma("unroll") for (int k = 0; k < 2; ++k) dst[m][k] = *(const LAS bf16x8*)(lds + PG8_SA(b, h) + aoff + m * 2048 + k * 1024); } while (0)
; #define PG8_LDB(dst, b, h) do { _Pragma("unroll") for (int n = 0; n < 2; ++n) _Pragma("unroll") for (int k = 0; k < 2; ++k) dst[n][k] = *(const LAS bf16x8*)(lds + PG8_SB(b, h) + boff + n * 2048 + k * 1024); } while (0)
; #define PG8_MMA(ai, bj, At, Bt) do { __builtin_amdgcn_s_setprio(1); _Pragma("unroll") for (int m = 0; m < 4; ++m) _Pragma("unroll") for (int n = 0; n < 2; ++n) _Pragma("unroll") for (int k = 0; k < 2; ++k) \
;         acc[ai][bj][m][n] = __builtin_amdgcn_mfma_f32_16x16x32_bf16(Bt[n][k], At[m][k], acc[ai][bj][m][n], 0, 0, 0); __builtin_amdgcn_s_setprio(0); } while (0)
; #define PG8_WAIT_L(n) asm volatile("s_waitcnt lgkmcnt(" #n ")" ::: "memory")
; #define PG8_BAR __builtin_amdgcn_s_barrier()
; #define PG8_SCHED __builtin_amdgcn_sched_barrier(0)
; template <class Epi>
; __device__ __forceinline__ void gemm_phase(LAS unsigned char* lds, const Gemm g, const StaticOrder& S, const Epi& E) {
;     ...
;             const char* aT = cA + (size_t)t * KS;
;             const char* a2 = last ? nA : aT + 2 * KS; const char* b2 = last ? nB : cB + (size_t)(t + 2) * KS;
;             PG8_LDB(B0, 0, 0); PG8_SCHED; PG8_LDA(At, 0, 0); PG8_STAGE(PG8_SA(1, 1), aT + KS, hA, 0);
;             PG8_WAIT_L(8); PG8_BAR; PG8_WAIT_L(0); PG8_MMA(0, 0, At, B0); PG8_BAR; PG8_SCHED;
;             PG8_LDB(B1, 0, 1); PG8_STAGE(PG8_SB(0, 0), b2, 0, 0);
;             PG8_BAR; PG8_WAIT_L(0); PG8_MMA(0, 1, At, B1); PG8_BAR;
;             PG8_LDA(At, 0, 1); PG8_STAGE(PG8_SA(0, 0), a2, 0, 0);
;             PG8_BAR; PG8_WAIT_L(0); PG8_MMA(1, 0, At, B0); PG8_BAR; PG8_SCHED;
.LBB0_610:
	s_add_u32 s62, s60, 0x8000
	v_add_u32_e32 v132, 0x10000, v236
	s_addc_u32 s63, s61, 0
	ds_read_b128 v[120:123], v132
	ds_read_b128 v[124:127], v132 offset:1024
	ds_read_b128 v[128:131], v132 offset:2048
	ds_read_b128 v[132:135], v132 offset:3072
	s_add_u32 s48, s60, 0x84000
	s_addc_u32 s49, s61, 0
	s_add_u32 s64, s60, 0x86000
	s_addc_u32 s65, s61, 0
	s_cmp_eq_u32 s71, 28
	s_cselect_b32 s61, s0, s63
	s_cselect_b32 s60, s1, s62
	ds_read_b128 v[136:139], v237
	ds_read_b128 v[140:143], v237 offset:1024
	ds_read_b128 v[152:155], v237 offset:2048
	ds_read_b128 v[156:159], v237 offset:3072
	ds_read_b128 v[160:163], v237 offset:4096
	ds_read_b128 v[164:167], v237 offset:5120
	ds_read_b128 v[168:171], v237 offset:6144
	ds_read_b128 v[172:175], v237 offset:7168
	s_mov_b32 m0, s67
	s_nop 0
	global_load_lds_dwordx4 v188, s[48:49]
	s_mov_b32 m0, s68
	s_nop 0
	global_load_lds_dwordx4 v188, s[64:65]
	s_waitcnt lgkmcnt(8)
	s_waitcnt vmcnt(10)
	s_barrier
	s_waitcnt lgkmcnt(0)
	s_waitcnt lgkmcnt(7)
	v_mfma_f32_16x16x32_bf16 v[148:151], v[120:123], v[136:139], v[148:151]
	v_mfma_f32_16x16x32_bf16 v[144:147], v[128:131], v[136:139], v[144:147]
	s_waitcnt lgkmcnt(5)
	v_mfma_f32_16x16x32_bf16 v[108:111], v[120:123], v[152:155], v[108:111]
	v_mfma_f32_16x16x32_bf16 v[104:107], v[128:131], v[152:155], v[104:107]
	s_waitcnt lgkmcnt(3)
	v_mfma_f32_16x16x32_bf16 v[92:95], v[120:123], v[160:163], v[92:95]
	v_mfma_f32_16x16x32_bf16 v[88:91], v[128:131], v[160:163], v[88:91]
	s_waitcnt lgkmcnt(1)
	v_mfma_f32_16x16x32_bf16 v[76:79], v[120:123], v[168:171], v[76:79]
	v_mfma_f32_16x16x32_bf16 v[72:75], v[128:131], v[168:171], v[72:75]
	v_mfma_f32_16x16x32_bf16 v[148:151], v[124:127], v[140:143], v[148:151]
	v_mfma_f32_16x16x32_bf16 v[144:147], v[132:135], v[140:143], v[144:147]
	v_mfma_f32_16x16x32_bf16 v[108:111], v[124:127], v[156:159], v[108:111]
	v_mfma_f32_16x16x32_bf16 v[104:107], v[132:135], v[156:159], v[104:107]
	v_mfma_f32_16x16x32_bf16 v[92:95], v[124:127], v[164:167], v[92:95]
	v_mfma_f32_16x16x32_bf16 v[88:91], v[132:135], v[164:167], v[88:91]
	s_waitcnt lgkmcnt(0)
	v_mfma_f32_16x16x32_bf16 v[76:79], v[124:127], v[172:175], v[76:79]
	v_mfma_f32_16x16x32_bf16 v[72:75], v[132:135], v[172:175], v[72:75]
	s_barrier
	v_add_u32_e32 v200, 0x14000, v236
	ds_read_b128 v[176:179], v200
	ds_read_b128 v[180:183], v200 offset:1024
	ds_read_b128 v[184:187], v200 offset:2048
	ds_read_b128 v[200:203], v200 offset:3072
	s_cselect_b32 s64, s55, s69
	s_cselect_b32 s65, s53, s70
	s_mov_b32 m0, s24
	s_nop 0
	global_load_lds_dwordx4 v188, s[64:65]
	s_add_u32 s48, s64, 0x2000
	s_addc_u32 s49, s65, 0
	s_mov_b32 m0, s25
	s_nop 0
	global_load_lds_dwordx4 v188, s[48:49]
	s_waitcnt vmcnt(10)
	s_barrier
	s_waitcnt lgkmcnt(0)
	s_waitcnt lgkmcnt(3)
	v_mfma_f32_16x16x32_bf16 v[116:119], v[176:179], v[136:139], v[116:119]
	s_waitcnt lgkmcnt(1)
	v_mfma_f32_16x16x32_bf16 v[112:115], v[184:187], v[136:139], v[112:115]
	v_mfma_f32_16x16x32_bf16 v[100:103], v[176:179], v[152:155], v[100:103]
	v_mfma_f32_16x16x32_bf16 v[96:99], v[184:187], v[152:155], v[96:99]
	v_mfma_f32_16x16x32_bf16 v[84:87], v[176:179], v[160:163], v[84:87]
	v_mfma_f32_16x16x32_bf16 v[80:83], v[184:187], v[160:163], v[80:83]
	v_mfma_f32_16x16x32_bf16 v[68:71], v[176:179], v[168:171], v[68:71]
	v_mfma_f32_16x16x32_bf16 v[64:67], v[184:187], v[168:171], v[64:67]
	v_mfma_f32_16x16x32_bf16 v[116:119], v[180:183], v[140:143], v[116:119]
	s_waitcnt lgkmcnt(0)
	v_mfma_f32_16x16x32_bf16 v[112:115], v[200:203], v[140:143], v[112:115]
	v_mfma_f32_16x16x32_bf16 v[100:103], v[180:183], v[156:159], v[100:103]
	v_mfma_f32_16x16x32_bf16 v[96:99], v[200:203], v[156:159], v[96:99]
	v_mfma_f32_16x16x32_bf16 v[84:87], v[180:183], v[164:167], v[84:87]
	v_mfma_f32_16x16x32_bf16 v[80:83], v[200:203], v[164:167], v[80:83]
	v_mfma_f32_16x16x32_bf16 v[68:71], v[180:183], v[172:175], v[68:71]
	v_mfma_f32_16x16x32_bf16 v[64:67], v[200:203], v[172:175], v[64:67]
	s_barrier
	ds_read_b128 v[136:139], v237 offset:16384
	ds_read_b128 v[140:143], v237 offset:17408
	ds_read_b128 v[152:155], v237 offset:18432
	ds_read_b128 v[156:159], v237 offset:19456
	ds_read_b128 v[160:163], v237 offset:20480
	ds_read_b128 v[164:167], v237 offset:21504
	ds_read_b128 v[168:171], v237 offset:22528
	ds_read_b128 v[172:175], v237 offset:23552
	s_mov_b32 m0, s22
	s_nop 0
	global_load_lds_dwordx4 v188, s[60:61]
	s_add_u32 s48, s60, 0x2000
	s_addc_u32 s49, s61, 0
	s_mov_b32 m0, s26
	s_nop 0
	global_load_lds_dwordx4 v188, s[48:49]
	s_barrier
	s_waitcnt lgkmcnt(0)
	s_waitcnt lgkmcnt(7)
	v_mfma_f32_16x16x32_bf16 v[60:63], v[120:123], v[136:139], v[60:63]
	v_mfma_f32_16x16x32_bf16 v[56:59], v[128:131], v[136:139], v[56:59]
	s_waitcnt lgkmcnt(5)
	v_mfma_f32_16x16x32_bf16 v[44:47], v[120:123], v[152:155], v[44:47]
	v_mfma_f32_16x16x32_bf16 v[40:43], v[128:131], v[152:155], v[40:43]
	s_waitcnt lgkmcnt(3)
	v_mfma_f32_16x16x32_bf16 v[28:31], v[120:123], v[160:163], v[28:31]
	v_mfma_f32_16x16x32_bf16 v[24:27], v[128:131], v[160:163], v[24:27]
	s_waitcnt lgkmcnt(1)
	v_mfma_f32_16x16x32_bf16 v[12:15], v[120:123], v[168:171], v[12:15]
	v_mfma_f32_16x16x32_bf16 v[8:11], v[128:131], v[168:171], v[8:11]
	v_mfma_f32_16x16x32_bf16 v[60:63], v[124:127], v[140:143], v[60:63]
	v_mfma_f32_16x16x32_bf16 v[56:59], v[132:135], v[140:143], v[56:59]
	v_mfma_f32_16x16x32_bf16 v[44:47], v[124:127], v[156:159], v[44:47]
	v_mfma_f32_16x16x32_bf16 v[40:43], v[132:135], v[156:159], v[40:43]
	v_mfma_f32_16x16x32_bf16 v[28:31], v[124:127], v[164:167], v[28:31]
	v_mfma_f32_16x16x32_bf16 v[24:27], v[132:135], v[164:167], v[24:27]
	s_waitcnt lgkmcnt(0)
	v_mfma_f32_16x16x32_bf16 v[12:15], v[124:127], v[172:175], v[12:15]
	v_mfma_f32_16x16x32_bf16 v[8:11], v[132:135], v[172:175], v[8:11]
	s_barrier
; #define PG8_STAGE(bufoff, gbase, hoff, imm) do { _Pragma("unroll") for (int _i = 0; _i < 2; ++_i) { \
;         asm volatile("s_mov_b32 m0, %0\n\ts_nop 0\n\tglobal_load_lds_dwordx4 %1, %2" \
;             :: "s"(lds0 + (unsigned)((bufoff) + _i * 8192)), "v"(voff0), "s"((const char*)(gbase) + (size_t)(hoff) + (size_t)(_i * 8192)) : "memory"); } } while (0)
; #define PG8_LDA(dst, b, h) do { _Pragma("unroll") for (int m = 0; m < 4; ++m) _Pragma("unroll") for (int k = 0; k < 2; ++k) dst[m][k] = *(const LAS bf16x8*)(lds + PG8_SA(b, h) + aoff + m * 2048 + k * 1024); } while (0)
; #define PG8_LDB(dst, b, h) do { _Pragma("unroll") for (int n = 0; n < 2; ++n) _Pragma("unroll") for (int k = 0; k < 2; ++k) dst[n][k] = *(const LAS bf16x8*)(lds + PG8_SB(b, h) + boff + n * 2048 + k * 1024); } while (0)
; #define PG8_MMA(ai, bj, At, Bt) do { __builtin_amdgcn_s_setprio(1); _Pragma("unroll") for (int m = 0; m < 4; ++m) _Pragma("unroll") for (int n = 0; n < 2; ++n) _Pragma("unroll") for (int k = 0; k < 2; ++k) \
;         acc[ai][bj][m][n] = __builtin_amdgcn_mfma_f32_16x16x32_bf16(Bt[n][k], At[m][k], acc[ai][bj][m][n], 0, 0, 0); __builtin_amdgcn_s_setprio(0); } while (0)
; #define PG8_WAIT_V(n) asm volatile("s_waitcnt vmcnt(" #n ")" ::: "memory")
; #define PG8_WAIT_L(n) asm volatile("s_waitcnt lgkmcnt(" #n ")" ::: "memory")
; #define PG8_BAR __builtin_amdgcn_s_barrier()
; #define PG8_SCHED __builtin_amdgcn_sched_barrier(0)
; template <class Epi>
; __device__ __forceinline__ void gemm_phase(LAS unsigned char* lds, const Gemm g, const StaticOrder& S, const Epi& E) {
;     ...
;             PG8_STAGE(PG8_SB(0, 1), b2, hB, 0);
;             PG8_WAIT_V(6); PG8_BAR; PG8_MMA(1, 1, At, B1); PG8_BAR;
;             PG8_LDB(B0, 1, 0); PG8_SCHED; PG8_LDA(At, 1, 0); PG8_STAGE(PG8_SA(0, 1), a2, hA, 0);
;             PG8_WAIT_L(8); PG8_BAR; PG8_WAIT_L(0); PG8_MMA(0, 0, At, B0); PG8_BAR; PG8_SCHED;
;             PG8_LDB(B1, 1, 1); PG8_STAGE(PG8_SB(1, 0), b2 + KS, 0, 0);
;             PG8_BAR; PG8_WAIT_L(0); PG8_MMA(0, 1, At, B1); PG8_BAR;
;             PG8_LDA(At, 1, 1); PG8_STAGE(PG8_SA(1, 0), a2 + KS, 0, 0);
	s_add_u32 s48, s64, 0x80000
	s_addc_u32 s49, s65, 0
	s_mov_b32 m0, s27
	s_nop 0
	global_load_lds_dwordx4 v188, s[48:49]
	s_add_u32 s48, s64, 0x82000
	s_addc_u32 s49, s65, 0
	s_mov_b32 m0, s28
	s_nop 0
	global_load_lds_dwordx4 v188, s[48:49]
	s_waitcnt vmcnt(10)
	s_barrier
	v_mfma_f32_16x16x32_bf16 v[52:55], v[176:179], v[136:139], v[52:55]
	v_mfma_f32_16x16x32_bf16 v[48:51], v[184:187], v[136:139], v[48:51]
	v_mfma_f32_16x16x32_bf16 v[36:39], v[176:179], v[152:155], v[36:39]
	v_mfma_f32_16x16x32_bf16 v[32:35], v[184:187], v[152:155], v[32:35]
	v_mfma_f32_16x16x32_bf16 v[20:23], v[176:179], v[160:163], v[20:23]
	v_mfma_f32_16x16x32_bf16 v[16:19], v[184:187], v[160:163], v[16:19]
	v_mfma_f32_16x16x32_bf16 v[4:7], v[176:179], v[168:171], v[4:7]
	v_mfma_f32_16x16x32_bf16 v[0:3], v[184:187], v[168:171], v[0:3]
	v_mfma_f32_16x16x32_bf16 v[52:55], v[180:183], v[140:143], v[52:55]
	v_mfma_f32_16x16x32_bf16 v[48:51], v[200:203], v[140:143], v[48:51]
	v_mfma_f32_16x16x32_bf16 v[36:39], v[180:183], v[156:159], v[36:39]
	v_mfma_f32_16x16x32_bf16 v[32:35], v[200:203], v[156:159], v[32:35]
	v_mfma_f32_16x16x32_bf16 v[20:23], v[180:183], v[164:167], v[20:23]
	v_mfma_f32_16x16x32_bf16 v[16:19], v[200:203], v[164:167], v[16:19]
	v_mfma_f32_16x16x32_bf16 v[4:7], v[180:183], v[172:175], v[4:7]
	v_mfma_f32_16x16x32_bf16 v[0:3], v[200:203], v[172:175], v[0:3]
	v_add_u32_e32 v132, 0x18000, v236
	s_barrier
	ds_read_b128 v[120:123], v132
	ds_read_b128 v[124:127], v132 offset:1024
	ds_read_b128 v[128:131], v132 offset:2048
	ds_read_b128 v[132:135], v132 offset:3072
	ds_read_b128 v[136:139], v237 offset:32768
	ds_read_b128 v[140:143], v237 offset:33792
	ds_read_b128 v[152:155], v237 offset:34816
	ds_read_b128 v[156:159], v237 offset:35840
	ds_read_b128 v[160:163], v237 offset:36864
	ds_read_b128 v[164:167], v237 offset:37888
	ds_read_b128 v[168:171], v237 offset:38912
	ds_read_b128 v[172:175], v237 offset:39936
	s_add_u32 s48, s60, 0x80000
	s_addc_u32 s49, s61, 0
	s_mov_b32 m0, s29
	s_nop 0
	global_load_lds_dwordx4 v188, s[48:49]
	s_add_u32 s48, s60, 0x82000
	s_addc_u32 s49, s61, 0
	s_mov_b32 m0, s30
	s_nop 0
	global_load_lds_dwordx4 v188, s[48:49]
	s_waitcnt lgkmcnt(8)
	s_waitcnt vmcnt(10)
	s_barrier
	s_waitcnt lgkmcnt(0)
	s_waitcnt lgkmcnt(7)
	v_mfma_f32_16x16x32_bf16 v[148:151], v[120:123], v[136:139], v[148:151]
	v_mfma_f32_16x16x32_bf16 v[144:147], v[128:131], v[136:139], v[144:147]
	s_waitcnt lgkmcnt(5)
	v_mfma_f32_16x16x32_bf16 v[108:111], v[120:123], v[152:155], v[108:111]
	v_mfma_f32_16x16x32_bf16 v[104:107], v[128:131], v[152:155], v[104:107]
	s_waitcnt lgkmcnt(3)
	v_mfma_f32_16x16x32_bf16 v[92:95], v[120:123], v[160:163], v[92:95]
	v_mfma_f32_16x16x32_bf16 v[88:91], v[128:131], v[160:163], v[88:91]
	s_waitcnt lgkmcnt(1)
	v_mfma_f32_16x16x32_bf16 v[76:79], v[120:123], v[168:171], v[76:79]
	v_mfma_f32_16x16x32_bf16 v[72:75], v[128:131], v[168:171], v[72:75]
	v_mfma_f32_16x16x32_bf16 v[148:151], v[124:127], v[140:143], v[148:151]
	v_mfma_f32_16x16x32_bf16 v[144:147], v[132:135], v[140:143], v[144:147]
	v_mfma_f32_16x16x32_bf16 v[108:111], v[124:127], v[156:159], v[108:111]
	v_mfma_f32_16x16x32_bf16 v[104:107], v[132:135], v[156:159], v[104:107]
	v_mfma_f32_16x16x32_bf16 v[92:95], v[124:127], v[164:167], v[92:95]
	v_mfma_f32_16x16x32_bf16 v[88:91], v[132:135], v[164:167], v[88:91]
	s_waitcnt lgkmcnt(0)
	v_mfma_f32_16x16x32_bf16 v[76:79], v[124:127], v[172:175], v[76:79]
	v_mfma_f32_16x16x32_bf16 v[72:75], v[132:135], v[172:175], v[72:75]
	s_barrier
	v_add_u32_e32 v200, 0x1c000, v236
	ds_read_b128 v[176:179], v200
	ds_read_b128 v[180:183], v200 offset:1024
	ds_read_b128 v[184:187], v200 offset:2048
	ds_read_b128 v[200:203], v200 offset:3072
	s_add_u32 s48, s64, 0x4000
	s_addc_u32 s49, s65, 0
	s_mov_b32 m0, s39
	s_nop 0
	global_load_lds_dwordx4 v188, s[48:49]
	s_add_u32 s48, s64, 0x6000
	s_addc_u32 s49, s65, 0
	s_mov_b32 m0, s40
	s_nop 0
	global_load_lds_dwordx4 v188, s[48:49]
	s_waitcnt vmcnt(10)
	s_barrier
	s_waitcnt lgkmcnt(0)
	s_waitcnt lgkmcnt(3)
	v_mfma_f32_16x16x32_bf16 v[116:119], v[176:179], v[136:139], v[116:119]
	s_waitcnt lgkmcnt(1)
	v_mfma_f32_16x16x32_bf16 v[112:115], v[184:187], v[136:139], v[112:115]
	v_mfma_f32_16x16x32_bf16 v[100:103], v[176:179], v[152:155], v[100:103]
	v_mfma_f32_16x16x32_bf16 v[96:99], v[184:187], v[152:155], v[96:99]
	v_mfma_f32_16x16x32_bf16 v[84:87], v[176:179], v[160:163], v[84:87]
	v_mfma_f32_16x16x32_bf16 v[80:83], v[184:187], v[160:163], v[80:83]
	v_mfma_f32_16x16x32_bf16 v[68:71], v[176:179], v[168:171], v[68:71]
	v_mfma_f32_16x16x32_bf16 v[64:67], v[184:187], v[168:171], v[64:67]
	v_mfma_f32_16x16x32_bf16 v[116:119], v[180:183], v[140:143], v[116:119]
	s_waitcnt lgkmcnt(0)
	v_mfma_f32_16x16x32_bf16 v[112:115], v[200:203], v[140:143], v[112:115]
	v_mfma_f32_16x16x32_bf16 v[100:103], v[180:183], v[156:159], v[100:103]
	v_mfma_f32_16x16x32_bf16 v[96:99], v[200:203], v[156:159], v[96:99]
	v_mfma_f32_16x16x32_bf16 v[84:87], v[180:183], v[164:167], v[84:87]
	v_mfma_f32_16x16x32_bf16 v[80:83], v[200:203], v[164:167], v[80:83]
	v_mfma_f32_16x16x32_bf16 v[68:71], v[180:183], v[172:175], v[68:71]
	v_mfma_f32_16x16x32_bf16 v[64:67], v[200:203], v[172:175], v[64:67]
	s_barrier
	ds_read_b128 v[136:139], v237 offset:49152
	ds_read_b128 v[140:143], v237 offset:50176
	ds_read_b128 v[152:155], v237 offset:51200
	ds_read_b128 v[156:159], v237 offset:52224
	ds_read_b128 v[160:163], v237 offset:53248
	ds_read_b128 v[164:167], v237 offset:54272
	ds_read_b128 v[168:171], v237 offset:55296
	ds_read_b128 v[172:175], v237 offset:56320
	s_add_u32 s48, s60, 0x4000
	s_addc_u32 s49, s61, 0
	s_mov_b32 m0, s41
	s_nop 0
	global_load_lds_dwordx4 v188, s[48:49]
	s_add_u32 s48, s60, 0x6000
	s_addc_u32 s49, s61, 0
	s_mov_b32 m0, s42
	s_nop 0
	global_load_lds_dwordx4 v188, s[48:49]
	s_barrier
; template <class Epi>
; __device__ __forceinline__ void gemm_phase(LAS unsigned char* lds, const Gemm g, const StaticOrder& S, const Epi& E) {
;     ...
;             PG8_BAR; PG8_WAIT_L(0); PG8_MMA(1, 0, At, B0); PG8_BAR; PG8_SCHED;
;             PG8_STAGE(PG8_SB(1, 1), b2 + KS, hB, 0);
;             PG8_WAIT_V(6); PG8_BAR; PG8_MMA(1, 1, At, B1); PG8_BAR;
;     __device__ __forceinline__ void operator()(f32x4 (&acc)[2][2][4][2], const Unit& u, int wr, int wc, int fr, int fq, LAS unsigned char*) const {
;         const int b = u.pm >> 6;
;         const int col0 = u.pn * BM + wc * 32 + 8 * fq;
;         const size_t off0 = (size_t)(u.pm * BM + wr * 64 + fr) * D + col0;
;         f32x4 sc[2][2];
; #pragma unroll
;         for (int bj = 0; bj < 2; ++bj)
; #pragma unroll
;             for (int n = 0; n < 2; ++n) { f32x4 gt = *(const f32x4*)(gate + (size_t)b * MODW + col0 + bj * HALF + n * 4); sc[bj][n] = gt + 1.0f;
;                 if (cs) sc[bj][n] *= *(const f32x4*)(cs + col0 + bj * HALF + n * 4); }
;         if (IN_F32) {
; #pragma unroll
;             for (int ai = 0; ai < 2; ++ai) {
;                 f32x4 r[4][2][2];
; #pragma unroll
;                 for (int m = 0; m < 4; ++m)
; #pragma unroll
;                     for (int bj = 0; bj < 2; ++bj)
; #pragma unroll
;                         for (int n = 0; n < 2; ++n) r[m][bj][n] = *(const f32x4*)((const float*)in + off0 + (size_t)(ai * HALF + m * 16) * D + bj * HALF + n * 4);
; #pragma unroll
;                 for (int m = 0; m < 4; ++m)
; #pragma unroll
;                     for (int bj = 0; bj < 2; ++bj) { const f32x4 r0 = r[m][bj][0] + sc[bj][0] * acc[ai][bj][m][0], r1 = r[m][bj][1] + sc[bj][1] * acc[ai][bj][m][1];
;                         u32x4 w; w.x = cvt_pk_bf16(r0[0], r0[1]); w.y = cvt_pk_bf16(r0[2], r0[3]); w.z = cvt_pk_bf16(r1[0], r1[1]); w.w = cvt_pk_bf16(r1[2], r1[3]);
;                         *(u32x4*)(out + off0 + (size_t)(ai * HALF + m * 16) * D + bj * HALF) = w; }
;                 asm volatile("" ::: "memory");
;             }
;         } else {
;             u32x4 xb[2][4][2];
; #pragma unroll
;             for (int ai = 0; ai < 2; ++ai)
; #pragma unroll
;                 for (int m = 0; m < 4; ++m)
; #pragma unroll
;                     for (int bj = 0; bj < 2; ++bj) xb[ai][m][bj] = *(const u32x4*)((const bf16_t*)in + off0 + (size_t)(ai * HALF + m * 16) * D + bj * HALF);
	s_waitcnt lgkmcnt(0)
	s_waitcnt lgkmcnt(7)
	v_mfma_f32_16x16x32_bf16 v[60:63], v[120:123], v[136:139], v[60:63]
	v_mfma_f32_16x16x32_bf16 v[56:59], v[128:131], v[136:139], v[56:59]
	s_waitcnt lgkmcnt(5)
	v_mfma_f32_16x16x32_bf16 v[44:47], v[120:123], v[152:155], v[44:47]
	v_mfma_f32_16x16x32_bf16 v[40:43], v[128:131], v[152:155], v[40:43]
	s_waitcnt lgkmcnt(3)
	v_mfma_f32_16x16x32_bf16 v[28:31], v[120:123], v[160:163], v[28:31]
	v_mfma_f32_16x16x32_bf16 v[24:27], v[128:131], v[160:163], v[24:27]
	s_waitcnt lgkmcnt(1)
	v_mfma_f32_16x16x32_bf16 v[12:15], v[120:123], v[168:171], v[12:15]
	v_mfma_f32_16x16x32_bf16 v[8:11], v[128:131], v[168:171], v[8:11]
	v_mfma_f32_16x16x32_bf16 v[60:63], v[124:127], v[140:143], v[60:63]
	v_mfma_f32_16x16x32_bf16 v[56:59], v[132:135], v[140:143], v[56:59]
	v_mfma_f32_16x16x32_bf16 v[44:47], v[124:127], v[156:159], v[44:47]
	v_mfma_f32_16x16x32_bf16 v[40:43], v[132:135], v[156:159], v[40:43]
	v_mfma_f32_16x16x32_bf16 v[28:31], v[124:127], v[164:167], v[28:31]
	v_mfma_f32_16x16x32_bf16 v[24:27], v[132:135], v[164:167], v[24:27]
	s_waitcnt lgkmcnt(0)
	v_mfma_f32_16x16x32_bf16 v[12:15], v[124:127], v[172:175], v[12:15]
	v_mfma_f32_16x16x32_bf16 v[8:11], v[132:135], v[172:175], v[8:11]
	s_barrier
	s_add_u32 s48, s64, 0x84000
	s_addc_u32 s49, s65, 0
	s_mov_b32 m0, s43
	s_nop 0
	global_load_lds_dwordx4 v188, s[48:49]
	s_add_u32 s48, s64, 0x86000
	s_addc_u32 s49, s65, 0
	s_mov_b32 m0, s66
	s_nop 0
	global_load_lds_dwordx4 v188, s[48:49]
	s_waitcnt vmcnt(10)
	s_barrier
	v_mfma_f32_16x16x32_bf16 v[52:55], v[176:179], v[136:139], v[52:55]
	v_mfma_f32_16x16x32_bf16 v[48:51], v[184:187], v[136:139], v[48:51]
	v_mfma_f32_16x16x32_bf16 v[36:39], v[176:179], v[152:155], v[36:39]
	v_mfma_f32_16x16x32_bf16 v[32:35], v[184:187], v[152:155], v[32:35]
	v_mfma_f32_16x16x32_bf16 v[20:23], v[176:179], v[160:163], v[20:23]
	v_mfma_f32_16x16x32_bf16 v[16:19], v[184:187], v[160:163], v[16:19]
	v_mfma_f32_16x16x32_bf16 v[4:7], v[176:179], v[168:171], v[4:7]
	v_mfma_f32_16x16x32_bf16 v[0:3], v[184:187], v[168:171], v[0:3]
	v_mfma_f32_16x16x32_bf16 v[52:55], v[180:183], v[140:143], v[52:55]
	v_mfma_f32_16x16x32_bf16 v[48:51], v[200:203], v[140:143], v[48:51]
	v_mfma_f32_16x16x32_bf16 v[36:39], v[180:183], v[156:159], v[36:39]
	v_mfma_f32_16x16x32_bf16 v[32:35], v[200:203], v[156:159], v[32:35]
	v_mfma_f32_16x16x32_bf16 v[20:23], v[180:183], v[164:167], v[20:23]
	v_mfma_f32_16x16x32_bf16 v[16:19], v[200:203], v[164:167], v[16:19]
	v_mfma_f32_16x16x32_bf16 v[4:7], v[180:183], v[172:175], v[4:7]
	v_mfma_f32_16x16x32_bf16 v[0:3], v[200:203], v[172:175], v[0:3]
	s_add_i32 s71, s71, 2
	s_add_u32 s69, s69, 0x8000
	s_addc_u32 s70, s70, 0
	s_cmp_gt_u32 s71, 29
	s_mov_b64 s[60:61], s[62:63]
	s_barrier
	s_cbranch_scc0 .LBB0_610
	s_ashr_i32 s0, s50, 6
	s_mul_hi_i32 s1, s0, 0xc000
	s_mul_i32 s0, s0, 0xc000
	v_lshl_or_b32 v128, s51, 8, v234
	s_add_u32 s0, s37, s0
	v_ashrrev_i32_e32 v129, 31, v128
	s_addc_u32 s1, s38, s1
	v_lshl_add_u64 v[130:131], v[128:129], 2, s[0:1]
	global_load_dwordx4 v[120:123], v[130:131], off offset:16
	global_load_dwordx4 v[124:127], v[130:131], off
	s_mov_b32 s51, s52
	s_mov_b64 s[62:63], s[58:59]
	s_mov_b64 s[60:61], s[56:57]
	s_waitcnt vmcnt(1)
	v_pk_add_f32 v[210:211], v[122:123], 1.0 op_sel_hi:[1,0]
	s_waitcnt vmcnt(0)
	v_pk_add_f32 v[214:215], v[126:127], 1.0 op_sel_hi:[1,0]
	v_pk_add_f32 v[212:213], v[124:125], 1.0 op_sel_hi:[1,0]
	v_pk_add_f32 v[208:209], v[120:121], 1.0 op_sel_hi:[1,0]
	global_load_dwordx4 v[120:123], v[130:131], off offset:528
	global_load_dwordx4 v[124:127], v[130:131], off offset:512
	s_waitcnt vmcnt(1)
	v_pk_add_f32 v[200:201], v[120:121], 1.0 op_sel_hi:[1,0]
	v_lshl_add_u32 v120, s50, 8, v233
	v_ashrrev_i32_e32 v121, 31, v120
	v_lshlrev_b64 v[120:121], 11, v[120:121]
	v_lshl_add_u64 v[120:121], v[120:121], 0, v[128:129]
	v_lshlrev_b64 v[216:217], 1, v[120:121]
	v_lshl_add_u64 v[120:121], s[8:9], 0, v[216:217]
	global_load_dwordx4 v[238:241], v[120:121], off
	global_load_dwordx4 v[184:187], v[120:121], off offset:256
	v_pk_add_f32 v[202:203], v[122:123], 1.0 op_sel_hi:[1,0]
	v_add_co_u32_e32 v122, vcc, s45, v120
	s_waitcnt vmcnt(2)
	v_pk_add_f32 v[206:207], v[126:127], 1.0 op_sel_hi:[1,0]
	v_addc_co_u32_e32 v123, vcc, 0, v121, vcc
	global_load_dwordx4 v[180:183], v[122:123], off
	global_load_dwordx4 v[176:179], v[122:123], off offset:256
	v_add_co_u32_e32 v122, vcc, s36, v120
	v_pk_add_f32 v[204:205], v[124:125], 1.0 op_sel_hi:[1,0]
	s_nop 0
	v_addc_co_u32_e32 v123, vcc, 0, v121, vcc
	global_load_dwordx4 v[172:175], v[122:123], off
	global_load_dwordx4 v[168:171], v[122:123], off offset:256
	v_add_co_u32_e32 v122, vcc, s23, v120
	s_mov_b32 s50, s54
	s_nop 0
	v_addc_co_u32_e32 v123, vcc, 0, v121, vcc
	global_load_dwordx4 v[164:167], v[122:123], off
	global_load_dwordx4 v[160:163], v[122:123], off offset:256
	v_add_co_u32_e32 v122, vcc, s93, v120
	s_waitcnt vmcnt(7)
; __device__ __forceinline__ unsigned cvt_pk_bf16(float lo, float hi) { unsigned r; asm volatile("v_cvt_pk_bf16_f32 %0, %1, %2" : "=v"(r) : "v"(lo), "v"(hi)); return r; }
;     __device__ __forceinline__ void operator()(f32x4 (&acc)[2][2][4][2], const Unit& u, int wr, int wc, int fr, int fq, LAS unsigned char*) const {
;     ...
;                     for (int bj = 0; bj < 2; ++bj) xb[ai][m][bj] = *(const u32x4*)((const bf16_t*)in + off0 + (size_t)(ai * HALF + m * 16) * D + bj * HALF);
; #pragma unroll
;             for (int ai = 0; ai < 2; ++ai)
; #pragma unroll
;                 for (int m = 0; m < 4; ++m)
; #pragma unroll
;                     for (int bj = 0; bj < 2; ++bj) { const u32x4 x = xb[ai][m][bj];
;                         f32x4 r0 = (f32x4){__uint_as_float(x.x << 16), __uint_as_float(x.x & 0xffff0000u), __uint_as_float(x.y << 16), __uint_as_float(x.y & 0xffff0000u)};
;                         f32x4 r1 = (f32x4){__uint_as_float(x.z << 16), __uint_as_float(x.z & 0xffff0000u), __uint_as_float(x.w << 16), __uint_as_float(x.w & 0xffff0000u)};
;                         r0 += sc[bj][0] * acc[ai][bj][m][0]; r1 += sc[bj][1] * acc[ai][bj][m][1];
;                         u32x4 w; w.x = cvt_pk_bf16(r0[0], r0[1]); w.y = cvt_pk_bf16(r0[2], r0[3]); w.z = cvt_pk_bf16(r1[0], r1[1]); w.w = cvt_pk_bf16(r1[2], r1[3]);
;                         *(u32x4*)(out + off0 + (size_t)(ai * HALF + m * 16) * D + bj * HALF) = w; }
	v_lshlrev_b32_e32 v230, 16, v238
	v_addc_co_u32_e32 v123, vcc, 0, v121, vcc
	global_load_dwordx4 v[156:159], v[122:123], off
	global_load_dwordx4 v[152:155], v[122:123], off offset:256
	v_add_co_u32_e32 v122, vcc, s33, v120
	v_and_b32_e32 v231, 0xffff0000, v238
	s_nop 0
	v_addc_co_u32_e32 v123, vcc, 0, v121, vcc
	global_load_dwordx4 v[140:143], v[122:123], off
	global_load_dwordx4 v[136:139], v[122:123], off offset:256
	v_add_co_u32_e32 v122, vcc, s18, v120
	v_lshlrev_b32_e32 v242, 16, v240
	s_nop 0
	v_addc_co_u32_e32 v123, vcc, 0, v121, vcc
	global_load_dwordx4 v[132:135], v[122:123], off
	global_load_dwordx4 v[128:131], v[122:123], off offset:256
	v_add_co_u32_e32 v120, vcc, s19, v120
	v_and_b32_e32 v243, 0xffff0000, v240
	s_nop 0
	v_addc_co_u32_e32 v121, vcc, 0, v121, vcc
	global_load_dwordx4 v[124:127], v[120:121], off
	s_nop 0
	global_load_dwordx4 v[120:123], v[120:121], off offset:256
	v_lshlrev_b32_e32 v238, 16, v239
	v_and_b32_e32 v239, 0xffff0000, v239
	v_lshlrev_b32_e32 v240, 16, v241
	v_and_b32_e32 v241, 0xffff0000, v241
	v_pk_fma_f32 v[148:149], v[148:149], v[212:213], v[230:231]
	v_pk_fma_f32 v[144:145], v[144:145], v[208:209], v[242:243]
	v_pk_fma_f32 v[150:151], v[150:151], v[214:215], v[238:239]
	v_pk_fma_f32 v[230:231], v[146:147], v[210:211], v[240:241]
	v_cvt_pk_bf16_f32 v146, v148, v149
	v_cvt_pk_bf16_f32 v147, v150, v151
	v_cvt_pk_bf16_f32 v148, v144, v145
	v_lshl_add_u64 v[144:145], s[10:11], 0, v[216:217]
	v_cvt_pk_bf16_f32 v149, v230, v231
	global_store_dwordx4 v[144:145], v[146:149], off
	s_waitcnt vmcnt(15)
	v_lshlrev_b32_e32 v150, 16, v186
	v_and_b32_e32 v151, 0xffff0000, v186
	v_lshlrev_b32_e32 v146, 16, v184
	v_and_b32_e32 v147, 0xffff0000, v184
	v_lshlrev_b32_e32 v148, 16, v185
	v_and_b32_e32 v149, 0xffff0000, v185
	v_lshlrev_b32_e32 v184, 16, v187
	v_and_b32_e32 v185, 0xffff0000, v187
	v_pk_fma_f32 v[118:119], v[118:119], v[206:207], v[148:149]
	v_pk_fma_f32 v[116:117], v[116:117], v[204:205], v[146:147]
	v_pk_fma_f32 v[146:147], v[114:115], v[202:203], v[184:185]
	v_pk_fma_f32 v[114:115], v[112:113], v[200:201], v[150:151]
	v_cvt_pk_bf16_f32 v112, v116, v117
	v_cvt_pk_bf16_f32 v113, v118, v119
	s_waitcnt vmcnt(14)
	v_lshlrev_b32_e32 v116, 16, v182
	v_cvt_pk_bf16_f32 v114, v114, v115
	v_cvt_pk_bf16_f32 v115, v146, v147
	global_store_dwordx4 v[144:145], v[112:115], off offset:256
	v_and_b32_e32 v117, 0xffff0000, v182
	v_lshlrev_b32_e32 v118, 16, v183
	v_lshlrev_b32_e32 v112, 16, v180
	v_and_b32_e32 v113, 0xffff0000, v180
	v_and_b32_e32 v119, 0xffff0000, v183
	v_pk_fma_f32 v[108:109], v[108:109], v[212:213], v[112:113]
	v_lshlrev_b32_e32 v114, 16, v181
	v_and_b32_e32 v115, 0xffff0000, v181
	v_pk_fma_f32 v[112:113], v[106:107], v[210:211], v[118:119]
	v_pk_fma_f32 v[106:107], v[104:105], v[208:209], v[116:117]
	v_cvt_pk_bf16_f32 v104, v108, v109
	v_add_co_u32_e32 v108, vcc, s45, v144
	v_pk_fma_f32 v[110:111], v[110:111], v[214:215], v[114:115]
	s_nop 0
	v_addc_co_u32_e32 v109, vcc, 0, v145, vcc
	v_cvt_pk_bf16_f32 v105, v110, v111
	v_cvt_pk_bf16_f32 v106, v106, v107
	v_cvt_pk_bf16_f32 v107, v112, v113
	global_store_dwordx4 v[108:109], v[104:107], off
	s_waitcnt vmcnt(15)
	v_lshlrev_b32_e32 v110, 16, v178
	v_and_b32_e32 v111, 0xffff0000, v178
	v_lshlrev_b32_e32 v104, 16, v176
	v_and_b32_e32 v105, 0xffff0000, v176
	v_lshlrev_b32_e32 v106, 16, v177
	v_and_b32_e32 v107, 0xffff0000, v177
	v_lshlrev_b32_e32 v112, 16, v179
	v_and_b32_e32 v113, 0xffff0000, v179
	v_pk_fma_f32 v[102:103], v[102:103], v[206:207], v[106:107]
	v_pk_fma_f32 v[100:101], v[100:101], v[204:205], v[104:105]
	v_pk_fma_f32 v[104:105], v[98:99], v[202:203], v[112:113]
	v_pk_fma_f32 v[98:99], v[96:97], v[200:201], v[110:111]
	v_cvt_pk_bf16_f32 v96, v100, v101
	v_cvt_pk_bf16_f32 v97, v102, v103
	s_waitcnt vmcnt(14)
	v_lshlrev_b32_e32 v100, 16, v174
	v_cvt_pk_bf16_f32 v98, v98, v99
	v_cvt_pk_bf16_f32 v99, v104, v105
	global_store_dwordx4 v[108:109], v[96:99], off offset:256
	v_and_b32_e32 v101, 0xffff0000, v174
	v_lshlrev_b32_e32 v102, 16, v175
	v_lshlrev_b32_e32 v96, 16, v172
	v_and_b32_e32 v97, 0xffff0000, v172
	v_and_b32_e32 v103, 0xffff0000, v175
	v_pk_fma_f32 v[92:93], v[92:93], v[212:213], v[96:97]
	v_lshlrev_b32_e32 v98, 16, v173
	v_and_b32_e32 v99, 0xffff0000, v173
	v_pk_fma_f32 v[96:97], v[90:91], v[210:211], v[102:103]
	v_pk_fma_f32 v[90:91], v[88:89], v[208:209], v[100:101]
	v_cvt_pk_bf16_f32 v88, v92, v93
	v_add_co_u32_e32 v92, vcc, s36, v144
	v_pk_fma_f32 v[94:95], v[94:95], v[214:215], v[98:99]
	s_nop 0
	v_addc_co_u32_e32 v93, vcc, 0, v145, vcc
	v_cvt_pk_bf16_f32 v89, v94, v95
	v_cvt_pk_bf16_f32 v90, v90, v91
	v_cvt_pk_bf16_f32 v91, v96, v97
	global_store_dwordx4 v[92:93], v[88:91], off
	s_waitcnt vmcnt(15)
	v_lshlrev_b32_e32 v94, 16, v170
	v_and_b32_e32 v95, 0xffff0000, v170
	v_lshlrev_b32_e32 v88, 16, v168
	v_and_b32_e32 v89, 0xffff0000, v168
	v_lshlrev_b32_e32 v90, 16, v169
	v_and_b32_e32 v91, 0xffff0000, v169
	v_lshlrev_b32_e32 v96, 16, v171
	v_and_b32_e32 v97, 0xffff0000, v171
	v_pk_fma_f32 v[86:87], v[86:87], v[206:207], v[90:91]
	v_pk_fma_f32 v[84:85], v[84:85], v[204:205], v[88:89]
	v_pk_fma_f32 v[88:89], v[82:83], v[202:203], v[96:97]
	v_pk_fma_f32 v[82:83], v[80:81], v[200:201], v[94:95]
	v_cvt_pk_bf16_f32 v80, v84, v85
	v_cvt_pk_bf16_f32 v81, v86, v87
	s_waitcnt vmcnt(14)
; __device__ __forceinline__ unsigned cvt_pk_bf16(float lo, float hi) { unsigned r; asm volatile("v_cvt_pk_bf16_f32 %0, %1, %2" : "=v"(r) : "v"(lo), "v"(hi)); return r; }
;     __device__ __forceinline__ void operator()(f32x4 (&acc)[2][2][4][2], const Unit& u, int wr, int wc, int fr, int fq, LAS unsigned char*) const {
;     ...
;             for (int ai = 0; ai < 2; ++ai)
; #pragma unroll
;                 for (int m = 0; m < 4; ++m)
; #pragma unroll
;                     for (int bj = 0; bj < 2; ++bj) { const u32x4 x = xb[ai][m][bj];
;                         f32x4 r0 = (f32x4){__uint_as_float(x.x << 16), __uint_as_float(x.x & 0xffff0000u), __uint_as_float(x.y << 16), __uint_as_float(x.y & 0xffff0000u)};
;                         f32x4 r1 = (f32x4){__uint_as_float(x.z << 16), __uint_as_float(x.z & 0xffff0000u), __uint_as_float(x.w << 16), __uint_as_float(x.w & 0xffff0000u)};
;                         r0 += sc[bj][0] * acc[ai][bj][m][0]; r1 += sc[bj][1] * acc[ai][bj][m][1];
;                         u32x4 w; w.x = cvt_pk_bf16(r0[0], r0[1]); w.y = cvt_pk_bf16(r0[2], r0[3]); w.z = cvt_pk_bf16(r1[0], r1[1]); w.w = cvt_pk_bf16(r1[2], r1[3]);
;                         *(u32x4*)(out + off0 + (size_t)(ai * HALF + m * 16) * D + bj * HALF) = w; }
	v_lshlrev_b32_e32 v84, 16, v166
	v_cvt_pk_bf16_f32 v82, v82, v83
	v_cvt_pk_bf16_f32 v83, v88, v89
	global_store_dwordx4 v[92:93], v[80:83], off offset:256
	v_and_b32_e32 v85, 0xffff0000, v166
	v_lshlrev_b32_e32 v86, 16, v167
	v_lshlrev_b32_e32 v80, 16, v164
	v_and_b32_e32 v81, 0xffff0000, v164
	v_and_b32_e32 v87, 0xffff0000, v167
	v_pk_fma_f32 v[76:77], v[76:77], v[212:213], v[80:81]
	v_lshlrev_b32_e32 v82, 16, v165
	v_and_b32_e32 v83, 0xffff0000, v165
	v_pk_fma_f32 v[80:81], v[74:75], v[210:211], v[86:87]
	v_pk_fma_f32 v[74:75], v[72:73], v[208:209], v[84:85]
	v_cvt_pk_bf16_f32 v72, v76, v77
	v_add_co_u32_e32 v76, vcc, s23, v144
	v_pk_fma_f32 v[78:79], v[78:79], v[214:215], v[82:83]
	s_nop 0
	v_addc_co_u32_e32 v77, vcc, 0, v145, vcc
	v_cvt_pk_bf16_f32 v73, v78, v79
	v_cvt_pk_bf16_f32 v74, v74, v75
	v_cvt_pk_bf16_f32 v75, v80, v81
	global_store_dwordx4 v[76:77], v[72:75], off
	s_waitcnt vmcnt(15)
	v_lshlrev_b32_e32 v78, 16, v162
	v_and_b32_e32 v79, 0xffff0000, v162
	v_lshlrev_b32_e32 v72, 16, v160
	v_and_b32_e32 v73, 0xffff0000, v160
	v_lshlrev_b32_e32 v74, 16, v161
	v_and_b32_e32 v75, 0xffff0000, v161
	v_lshlrev_b32_e32 v80, 16, v163
	v_and_b32_e32 v81, 0xffff0000, v163
	v_pk_fma_f32 v[70:71], v[70:71], v[206:207], v[74:75]
	v_pk_fma_f32 v[68:69], v[68:69], v[204:205], v[72:73]
	v_pk_fma_f32 v[72:73], v[66:67], v[202:203], v[80:81]
	v_pk_fma_f32 v[66:67], v[64:65], v[200:201], v[78:79]
	v_cvt_pk_bf16_f32 v64, v68, v69
	v_cvt_pk_bf16_f32 v65, v70, v71
	s_waitcnt vmcnt(14)
	v_lshlrev_b32_e32 v68, 16, v158
	v_cvt_pk_bf16_f32 v66, v66, v67
	v_cvt_pk_bf16_f32 v67, v72, v73
	global_store_dwordx4 v[76:77], v[64:67], off offset:256
	v_and_b32_e32 v69, 0xffff0000, v158
	v_lshlrev_b32_e32 v70, 16, v159
	v_lshlrev_b32_e32 v64, 16, v156
	v_and_b32_e32 v65, 0xffff0000, v156
	v_and_b32_e32 v71, 0xffff0000, v159
	v_pk_fma_f32 v[60:61], v[60:61], v[212:213], v[64:65]
	v_lshlrev_b32_e32 v66, 16, v157
	v_and_b32_e32 v67, 0xffff0000, v157
	v_pk_fma_f32 v[64:65], v[58:59], v[210:211], v[70:71]
	v_pk_fma_f32 v[58:59], v[56:57], v[208:209], v[68:69]
	v_cvt_pk_bf16_f32 v56, v60, v61
	v_add_co_u32_e32 v60, vcc, s93, v144
	v_pk_fma_f32 v[62:63], v[62:63], v[214:215], v[66:67]
	s_nop 0
	v_addc_co_u32_e32 v61, vcc, 0, v145, vcc
	v_cvt_pk_bf16_f32 v57, v62, v63
	v_cvt_pk_bf16_f32 v58, v58, v59
	v_cvt_pk_bf16_f32 v59, v64, v65
	global_store_dwordx4 v[60:61], v[56:59], off
	s_waitcnt vmcnt(15)
	v_lshlrev_b32_e32 v62, 16, v154
	v_and_b32_e32 v63, 0xffff0000, v154
	v_lshlrev_b32_e32 v56, 16, v152
	v_and_b32_e32 v57, 0xffff0000, v152
	v_lshlrev_b32_e32 v58, 16, v153
	v_and_b32_e32 v59, 0xffff0000, v153
	v_lshlrev_b32_e32 v64, 16, v155
	v_and_b32_e32 v65, 0xffff0000, v155
	v_pk_fma_f32 v[54:55], v[54:55], v[206:207], v[58:59]
	v_pk_fma_f32 v[52:53], v[52:53], v[204:205], v[56:57]
	v_pk_fma_f32 v[56:57], v[50:51], v[202:203], v[64:65]
	v_pk_fma_f32 v[50:51], v[48:49], v[200:201], v[62:63]
	v_cvt_pk_bf16_f32 v48, v52, v53
	v_cvt_pk_bf16_f32 v49, v54, v55
	s_waitcnt vmcnt(14)
	v_lshlrev_b32_e32 v52, 16, v142
	v_cvt_pk_bf16_f32 v50, v50, v51
	v_cvt_pk_bf16_f32 v51, v56, v57
	global_store_dwordx4 v[60:61], v[48:51], off offset:256
	v_and_b32_e32 v53, 0xffff0000, v142
	v_lshlrev_b32_e32 v54, 16, v143
	v_lshlrev_b32_e32 v48, 16, v140
	v_and_b32_e32 v49, 0xffff0000, v140
	v_and_b32_e32 v55, 0xffff0000, v143
	v_pk_fma_f32 v[44:45], v[44:45], v[212:213], v[48:49]
	v_lshlrev_b32_e32 v50, 16, v141
	v_and_b32_e32 v51, 0xffff0000, v141
	v_pk_fma_f32 v[48:49], v[42:43], v[210:211], v[54:55]
	v_pk_fma_f32 v[42:43], v[40:41], v[208:209], v[52:53]
	v_cvt_pk_bf16_f32 v40, v44, v45
	v_add_co_u32_e32 v44, vcc, s33, v144
	v_pk_fma_f32 v[46:47], v[46:47], v[214:215], v[50:51]
	s_nop 0
	v_addc_co_u32_e32 v45, vcc, 0, v145, vcc
	v_cvt_pk_bf16_f32 v41, v46, v47
	v_cvt_pk_bf16_f32 v42, v42, v43
	v_cvt_pk_bf16_f32 v43, v48, v49
	global_store_dwordx4 v[44:45], v[40:43], off
	s_waitcnt vmcnt(15)
; __device__ __forceinline__ unsigned cvt_pk_bf16(float lo, float hi) { unsigned r; asm volatile("v_cvt_pk_bf16_f32 %0, %1, %2" : "=v"(r) : "v"(lo), "v"(hi)); return r; }
; #define PG8_WAIT_V(n) asm volatile("s_waitcnt vmcnt(" #n ")" ::: "memory")
; #define PG8_BAR __builtin_amdgcn_s_barrier()
; template <class Epi>
; __device__ __forceinline__ void gemm_phase(LAS unsigned char* lds, const Gemm g, const StaticOrder& S, const Epi& E) {
;     ...
;         if (!has_next) break;
; #pragma unroll
;         for (int a = 0; a < 2; ++a)
; #pragma unroll
;             for (int b = 0; b < 2; ++b)
; #pragma unroll
;                 for (int m = 0; m < 4; ++m)
; #pragma unroll
;                     for (int n = 0; n < 2; ++n) acc[a][b][m][n] = (f32x4){0.f, 0.f, 0.f, 0.f};
;         cur = nxt; cA = nA; cB = nB; ++ui;
;     }
;     PG8_WAIT_V(0);
;     if (wr == 0) PG8_BAR;
;     PG8_BAR;
;     __device__ __forceinline__ void operator()(f32x4 (&acc)[2][2][4][2], const Unit& u, int wr, int wc, int fr, int fq, LAS unsigned char*) const {
;     ...
;             for (int ai = 0; ai < 2; ++ai)
; #pragma unroll
;                 for (int m = 0; m < 4; ++m)
; #pragma unroll
;                     for (int bj = 0; bj < 2; ++bj) { const u32x4 x = xb[ai][m][bj];
;                         f32x4 r0 = (f32x4){__uint_as_float(x.x << 16), __uint_as_float(x.x & 0xffff0000u), __uint_as_float(x.y << 16), __uint_as_float(x.y & 0xffff0000u)};
;                         f32x4 r1 = (f32x4){__uint_as_float(x.z << 16), __uint_as_float(x.z & 0xffff0000u), __uint_as_float(x.w << 16), __uint_as_float(x.w & 0xffff0000u)};
;                         r0 += sc[bj][0] * acc[ai][bj][m][0]; r1 += sc[bj][1] * acc[ai][bj][m][1];
;                         u32x4 w; w.x = cvt_pk_bf16(r0[0], r0[1]); w.y = cvt_pk_bf16(r0[2], r0[3]); w.z = cvt_pk_bf16(r1[0], r1[1]); w.w = cvt_pk_bf16(r1[2], r1[3]);
;                         *(u32x4*)(out + off0 + (size_t)(ai * HALF + m * 16) * D + bj * HALF) = w; }
	v_lshlrev_b32_e32 v46, 16, v138
	v_and_b32_e32 v47, 0xffff0000, v138
	v_lshlrev_b32_e32 v40, 16, v136
	v_and_b32_e32 v41, 0xffff0000, v136
	v_lshlrev_b32_e32 v42, 16, v137
	v_and_b32_e32 v43, 0xffff0000, v137
	v_lshlrev_b32_e32 v48, 16, v139
	v_and_b32_e32 v49, 0xffff0000, v139
	v_pk_fma_f32 v[38:39], v[38:39], v[206:207], v[42:43]
	v_pk_fma_f32 v[36:37], v[36:37], v[204:205], v[40:41]
	v_pk_fma_f32 v[40:41], v[34:35], v[202:203], v[48:49]
	v_pk_fma_f32 v[34:35], v[32:33], v[200:201], v[46:47]
	v_cvt_pk_bf16_f32 v32, v36, v37
	v_cvt_pk_bf16_f32 v33, v38, v39
	s_waitcnt vmcnt(14)
	v_lshlrev_b32_e32 v36, 16, v134
	v_cvt_pk_bf16_f32 v34, v34, v35
	v_cvt_pk_bf16_f32 v35, v40, v41
	global_store_dwordx4 v[44:45], v[32:35], off offset:256
	v_and_b32_e32 v37, 0xffff0000, v134
	v_lshlrev_b32_e32 v38, 16, v135
	v_lshlrev_b32_e32 v32, 16, v132
	v_and_b32_e32 v33, 0xffff0000, v132
	v_and_b32_e32 v39, 0xffff0000, v135
	v_pk_fma_f32 v[28:29], v[28:29], v[212:213], v[32:33]
	v_lshlrev_b32_e32 v34, 16, v133
	v_and_b32_e32 v35, 0xffff0000, v133
	v_pk_fma_f32 v[32:33], v[26:27], v[210:211], v[38:39]
	v_pk_fma_f32 v[26:27], v[24:25], v[208:209], v[36:37]
	v_cvt_pk_bf16_f32 v24, v28, v29
	v_add_co_u32_e32 v28, vcc, s18, v144
	v_pk_fma_f32 v[30:31], v[30:31], v[214:215], v[34:35]
	s_nop 0
	v_addc_co_u32_e32 v29, vcc, 0, v145, vcc
	v_cvt_pk_bf16_f32 v25, v30, v31
	v_cvt_pk_bf16_f32 v26, v26, v27
	v_cvt_pk_bf16_f32 v27, v32, v33
	global_store_dwordx4 v[28:29], v[24:27], off
	s_waitcnt vmcnt(15)
	v_lshlrev_b32_e32 v30, 16, v130
	v_and_b32_e32 v31, 0xffff0000, v130
	v_lshlrev_b32_e32 v24, 16, v128
	v_and_b32_e32 v25, 0xffff0000, v128
	v_lshlrev_b32_e32 v26, 16, v129
	v_and_b32_e32 v27, 0xffff0000, v129
	v_lshlrev_b32_e32 v32, 16, v131
	v_and_b32_e32 v33, 0xffff0000, v131
	v_pk_fma_f32 v[22:23], v[22:23], v[206:207], v[26:27]
	v_pk_fma_f32 v[20:21], v[20:21], v[204:205], v[24:25]
	v_pk_fma_f32 v[24:25], v[18:19], v[202:203], v[32:33]
	v_pk_fma_f32 v[18:19], v[16:17], v[200:201], v[30:31]
	v_cvt_pk_bf16_f32 v16, v20, v21
	v_cvt_pk_bf16_f32 v17, v22, v23
	s_waitcnt vmcnt(14)
	v_lshlrev_b32_e32 v20, 16, v126
	v_cvt_pk_bf16_f32 v18, v18, v19
	v_cvt_pk_bf16_f32 v19, v24, v25
	global_store_dwordx4 v[28:29], v[16:19], off offset:256
	v_and_b32_e32 v21, 0xffff0000, v126
	v_lshlrev_b32_e32 v22, 16, v127
	v_lshlrev_b32_e32 v16, 16, v124
	v_and_b32_e32 v17, 0xffff0000, v124
	v_and_b32_e32 v23, 0xffff0000, v127
	v_pk_fma_f32 v[12:13], v[12:13], v[212:213], v[16:17]
	v_lshlrev_b32_e32 v18, 16, v125
	v_and_b32_e32 v19, 0xffff0000, v125
	v_pk_fma_f32 v[16:17], v[10:11], v[210:211], v[22:23]
	v_pk_fma_f32 v[10:11], v[8:9], v[208:209], v[20:21]
	v_cvt_pk_bf16_f32 v8, v12, v13
	v_add_co_u32_e32 v12, vcc, s19, v144
	v_pk_fma_f32 v[14:15], v[14:15], v[214:215], v[18:19]
	s_nop 0
	v_addc_co_u32_e32 v13, vcc, 0, v145, vcc
	v_cvt_pk_bf16_f32 v9, v14, v15
	v_cvt_pk_bf16_f32 v10, v10, v11
	v_cvt_pk_bf16_f32 v11, v16, v17
	global_store_dwordx4 v[12:13], v[8:11], off
	s_waitcnt vmcnt(15)
	v_lshlrev_b32_e32 v14, 16, v122
	v_and_b32_e32 v15, 0xffff0000, v122
	v_lshlrev_b32_e32 v8, 16, v120
	v_and_b32_e32 v9, 0xffff0000, v120
	v_lshlrev_b32_e32 v16, 16, v123
	v_and_b32_e32 v17, 0xffff0000, v123
	v_lshlrev_b32_e32 v10, 16, v121
	v_and_b32_e32 v11, 0xffff0000, v121
	v_pk_fma_f32 v[4:5], v[4:5], v[204:205], v[8:9]
	v_pk_fma_f32 v[8:9], v[2:3], v[202:203], v[16:17]
	v_pk_fma_f32 v[2:3], v[0:1], v[200:201], v[14:15]
	s_and_b64 vcc, exec, s[4:5]
	v_pk_fma_f32 v[6:7], v[6:7], v[206:207], v[10:11]
	v_cvt_pk_bf16_f32 v0, v4, v5
	s_nop 0
	v_cvt_pk_bf16_f32 v1, v6, v7
	v_cvt_pk_bf16_f32 v2, v2, v3
	v_cvt_pk_bf16_f32 v3, v8, v9
	global_store_dwordx4 v[12:13], v[0:3], off offset:256
	s_cbranch_vccz .LBB0_603
	s_waitcnt vmcnt(0)
	s_cmpk_gt_u32 s16, 0xff
	v_readlane_b32 s38, v255, 44
	s_movk_i32 s30, 0x7ff
	s_cbranch_scc1 .LBB0_614
	s_barrier

; #define PG8_STAGE(bufoff, gbase, hoff, imm) do { _Pragma("unroll") for (int _i = 0; _i < 2; ++_i) { \
;         asm volatile("s_mov_b32 m0, %0\n\ts_nop 0\n\tglobal_load_lds_dwordx4 %1, %2" \
;             :: "s"(lds0 + (unsigned)((bufoff) + _i * 8192)), "v"(voff0), "s"((const char*)(gbase) + (size_t)(hoff) + (size_t)(_i * 8192)) : "memory"); } } while (0)
; #define PG8_LDA(dst, b, h) do { _Pragma("unroll") for (int m = 0; m < 4; ++m) _Pragma("unroll") for (int k = 0; k < 2; ++k) dst[m][k] = *(const LAS bf16x8*)(lds + PG8_SA(b, h) + aoff + m * 2048 + k * 1024); } while (0)
; #define PG8_LDB(dst, b, h) do { _Pragma("unroll") for (int n = 0; n < 2; ++n) _Pragma("unroll") for (int k = 0; k < 2; ++k) dst[n][k] = *(const LAS bf16x8*)(lds + PG8_SB(b, h) + boff + n * 2048 + k * 1024); } while (0)
; #define PG8_MMA(ai, bj, At, Bt) do { __builtin_amdgcn_s_setprio(1); _Pragma("unroll") for (int m = 0; m < 4; ++m) _Pragma("unroll") for (int n = 0; n < 2; ++n) _Pragma("unroll") for (int k = 0; k < 2; ++k) \
;         acc[ai][bj][m][n] = __builtin_amdgcn_mfma_f32_16x16x32_bf16(Bt[n][k], At[m][k], acc[ai][bj][m][n], 0, 0, 0); __builtin_amdgcn_s_setprio(0); } while (0)
; #define PG8_WAIT_L(n) asm volatile("s_waitcnt lgkmcnt(" #n ")" ::: "memory")
; #define PG8_BAR __builtin_amdgcn_s_barrier()
; #define PG8_SCHED __builtin_amdgcn_sched_barrier(0)
; template <class Epi>
; __device__ __forceinline__ void gemm_phase(LAS unsigned char* lds, const Gemm g, const StaticOrder& S, const Epi& E) {
;     ...
;             const char* aT = cA + (size_t)t * KS;
;             const char* a2 = last ? nA : aT + 2 * KS; const char* b2 = last ? nB : cB + (size_t)(t + 2) * KS;
;             PG8_LDB(B0, 0, 0); PG8_SCHED; PG8_LDA(At, 0, 0); PG8_STAGE(PG8_SA(1, 1), aT + KS, hA, 0);
;             PG8_WAIT_L(8); PG8_BAR; PG8_WAIT_L(0); PG8_MMA(0, 0, At, B0); PG8_BAR; PG8_SCHED;
;             PG8_LDB(B1, 0, 1); PG8_STAGE(PG8_SB(0, 0), b2, 0, 0);
;             PG8_BAR; PG8_WAIT_L(0); PG8_MMA(0, 1, At, B1); PG8_BAR;
;             PG8_LDA(At, 0, 1); PG8_STAGE(PG8_SA(0, 0), a2, 0, 0);
;             PG8_BAR; PG8_WAIT_L(0); PG8_MMA(1, 0, At, B0); PG8_BAR; PG8_SCHED;
.LBB0_738:
	v_add_u32_e32 v140, 0x10000, v177
	ds_read_b128 v[128:131], v140
	ds_read_b128 v[132:135], v140 offset:1024
	ds_read_b128 v[136:139], v140 offset:2048
	ds_read_b128 v[140:143], v140 offset:3072
	s_add_u32 s78, s76, 0x8000
	s_addc_u32 s79, s77, 0
	s_and_b64 s[48:49], s[82:83], exec
	s_cselect_b32 s81, s50, s79
	s_cselect_b32 s80, s51, s78
	ds_read_b128 v[144:147], v178
	ds_read_b128 v[148:151], v178 offset:1024
	ds_read_b128 v[184:187], v178 offset:2048
	ds_read_b128 v[200:203], v178 offset:3072
	ds_read_b128 v[204:207], v178 offset:4096
	ds_read_b128 v[208:211], v178 offset:5120
	ds_read_b128 v[212:215], v178 offset:6144
	ds_read_b128 v[236:239], v178 offset:7168
	s_add_u32 s48, s76, 0x84000
	s_addc_u32 s49, s77, 0
	s_mov_b32 m0, s34
	s_nop 0
	global_load_lds_dwordx4 v152, s[48:49]
	s_add_u32 s48, s76, 0x86000
	s_addc_u32 s49, s77, 0
	s_mov_b32 m0, s25
	s_nop 0
	global_load_lds_dwordx4 v152, s[48:49]
	s_waitcnt lgkmcnt(8)
	s_waitcnt vmcnt(10)
	s_barrier
	s_waitcnt lgkmcnt(0)
	s_waitcnt lgkmcnt(7)
	v_mfma_f32_16x16x32_bf16 v[116:119], v[128:131], v[144:147], v[116:119]
	v_mfma_f32_16x16x32_bf16 v[80:83], v[136:139], v[144:147], v[80:83]
	s_waitcnt lgkmcnt(5)
	v_mfma_f32_16x16x32_bf16 v[88:91], v[128:131], v[184:187], v[88:91]
	v_mfma_f32_16x16x32_bf16 v[84:87], v[136:139], v[184:187], v[84:87]
	s_waitcnt lgkmcnt(3)
	v_mfma_f32_16x16x32_bf16 v[120:123], v[128:131], v[204:207], v[120:123]
	v_mfma_f32_16x16x32_bf16 v[92:95], v[136:139], v[204:207], v[92:95]
	s_waitcnt lgkmcnt(1)
	v_mfma_f32_16x16x32_bf16 v[124:127], v[128:131], v[212:215], v[124:127]
	v_mfma_f32_16x16x32_bf16 v[96:99], v[136:139], v[212:215], v[96:99]
	v_mfma_f32_16x16x32_bf16 v[116:119], v[132:135], v[148:151], v[116:119]
	v_mfma_f32_16x16x32_bf16 v[80:83], v[140:143], v[148:151], v[80:83]
	v_mfma_f32_16x16x32_bf16 v[88:91], v[132:135], v[200:203], v[88:91]
	v_mfma_f32_16x16x32_bf16 v[84:87], v[140:143], v[200:203], v[84:87]
	v_mfma_f32_16x16x32_bf16 v[120:123], v[132:135], v[208:211], v[120:123]
	v_mfma_f32_16x16x32_bf16 v[92:95], v[140:143], v[208:211], v[92:95]
	s_waitcnt lgkmcnt(0)
	v_mfma_f32_16x16x32_bf16 v[124:127], v[132:135], v[236:239], v[124:127]
	v_mfma_f32_16x16x32_bf16 v[96:99], v[140:143], v[236:239], v[96:99]
	s_barrier
	v_add_u32_e32 v188, 0x14000, v177
	ds_read_b128 v[240:243], v188
	ds_read_b128 v[244:247], v188 offset:1024
	ds_read_b128 v[248:251], v188 offset:2048
	ds_read_b128 v[230:233], v188 offset:3072
	s_and_b64 s[48:49], s[82:83], exec
	s_cselect_b32 s76, s0, s1
	s_cselect_b32 s77, s69, s9
	s_mov_b32 m0, s28
	s_nop 0
	global_load_lds_dwordx4 v152, s[76:77]
	s_add_u32 s48, s76, 0x2000
	s_addc_u32 s49, s77, 0
	s_mov_b32 m0, s29
	s_nop 0
	global_load_lds_dwordx4 v152, s[48:49]
	s_waitcnt vmcnt(10)
	s_barrier
	s_waitcnt lgkmcnt(0)
	s_waitcnt lgkmcnt(3)
	v_mfma_f32_16x16x32_bf16 v[48:51], v[240:243], v[144:147], v[48:51]
	s_waitcnt lgkmcnt(1)
	v_mfma_f32_16x16x32_bf16 v[16:19], v[248:251], v[144:147], v[16:19]
	v_mfma_f32_16x16x32_bf16 v[52:55], v[240:243], v[184:187], v[52:55]
	v_mfma_f32_16x16x32_bf16 v[20:23], v[248:251], v[184:187], v[20:23]
	v_mfma_f32_16x16x32_bf16 v[56:59], v[240:243], v[204:207], v[56:59]
	v_mfma_f32_16x16x32_bf16 v[24:27], v[248:251], v[204:207], v[24:27]
	v_mfma_f32_16x16x32_bf16 v[60:63], v[240:243], v[212:215], v[60:63]
	v_mfma_f32_16x16x32_bf16 v[28:31], v[248:251], v[212:215], v[28:31]
	v_mfma_f32_16x16x32_bf16 v[48:51], v[244:247], v[148:151], v[48:51]
	s_waitcnt lgkmcnt(0)
	v_mfma_f32_16x16x32_bf16 v[16:19], v[230:233], v[148:151], v[16:19]
	v_mfma_f32_16x16x32_bf16 v[52:55], v[244:247], v[200:203], v[52:55]
	v_mfma_f32_16x16x32_bf16 v[20:23], v[230:233], v[200:203], v[20:23]
	v_mfma_f32_16x16x32_bf16 v[56:59], v[244:247], v[208:211], v[56:59]
	v_mfma_f32_16x16x32_bf16 v[24:27], v[230:233], v[208:211], v[24:27]
	v_mfma_f32_16x16x32_bf16 v[60:63], v[244:247], v[236:239], v[60:63]
	v_mfma_f32_16x16x32_bf16 v[28:31], v[230:233], v[236:239], v[28:31]
	s_barrier
	ds_read_b128 v[144:147], v178 offset:16384
	ds_read_b128 v[148:151], v178 offset:17408
	ds_read_b128 v[184:187], v178 offset:18432
	ds_read_b128 v[200:203], v178 offset:19456
	ds_read_b128 v[204:207], v178 offset:20480
	ds_read_b128 v[208:211], v178 offset:21504
	ds_read_b128 v[212:215], v178 offset:22528
	ds_read_b128 v[236:239], v178 offset:23552
	s_mov_b32 m0, s89
	s_nop 0
	global_load_lds_dwordx4 v152, s[80:81]
	s_add_u32 s48, s80, 0x2000
	s_addc_u32 s49, s81, 0
	s_mov_b32 m0, s40
	s_nop 0
	global_load_lds_dwordx4 v152, s[48:49]
	s_barrier
	s_waitcnt lgkmcnt(0)
	s_waitcnt lgkmcnt(7)
	v_mfma_f32_16x16x32_bf16 v[100:103], v[128:131], v[144:147], v[100:103]
	v_mfma_f32_16x16x32_bf16 v[64:67], v[136:139], v[144:147], v[64:67]
	s_waitcnt lgkmcnt(5)
	v_mfma_f32_16x16x32_bf16 v[104:107], v[128:131], v[184:187], v[104:107]
	v_mfma_f32_16x16x32_bf16 v[68:71], v[136:139], v[184:187], v[68:71]
	s_waitcnt lgkmcnt(3)
	v_mfma_f32_16x16x32_bf16 v[108:111], v[128:131], v[204:207], v[108:111]
	v_mfma_f32_16x16x32_bf16 v[72:75], v[136:139], v[204:207], v[72:75]
	s_waitcnt lgkmcnt(1)
	v_mfma_f32_16x16x32_bf16 v[112:115], v[128:131], v[212:215], v[112:115]
	v_mfma_f32_16x16x32_bf16 v[76:79], v[136:139], v[212:215], v[76:79]
	v_mfma_f32_16x16x32_bf16 v[100:103], v[132:135], v[148:151], v[100:103]
	v_mfma_f32_16x16x32_bf16 v[64:67], v[140:143], v[148:151], v[64:67]
	v_mfma_f32_16x16x32_bf16 v[104:107], v[132:135], v[200:203], v[104:107]
	v_mfma_f32_16x16x32_bf16 v[68:71], v[140:143], v[200:203], v[68:71]
	v_mfma_f32_16x16x32_bf16 v[108:111], v[132:135], v[208:211], v[108:111]
	v_mfma_f32_16x16x32_bf16 v[72:75], v[140:143], v[208:211], v[72:75]
	s_waitcnt lgkmcnt(0)
	v_mfma_f32_16x16x32_bf16 v[112:115], v[132:135], v[236:239], v[112:115]
	v_mfma_f32_16x16x32_bf16 v[76:79], v[140:143], v[236:239], v[76:79]
	s_barrier
; #define PG8_STAGE(bufoff, gbase, hoff, imm) do { _Pragma("unroll") for (int _i = 0; _i < 2; ++_i) { \
;         asm volatile("s_mov_b32 m0, %0\n\ts_nop 0\n\tglobal_load_lds_dwordx4 %1, %2" \
;             :: "s"(lds0 + (unsigned)((bufoff) + _i * 8192)), "v"(voff0), "s"((const char*)(gbase) + (size_t)(hoff) + (size_t)(_i * 8192)) : "memory"); } } while (0)
; #define PG8_LDA(dst, b, h) do { _Pragma("unroll") for (int m = 0; m < 4; ++m) _Pragma("unroll") for (int k = 0; k < 2; ++k) dst[m][k] = *(const LAS bf16x8*)(lds + PG8_SA(b, h) + aoff + m * 2048 + k * 1024); } while (0)
; #define PG8_LDB(dst, b, h) do { _Pragma("unroll") for (int n = 0; n < 2; ++n) _Pragma("unroll") for (int k = 0; k < 2; ++k) dst[n][k] = *(const LAS bf16x8*)(lds + PG8_SB(b, h) + boff + n * 2048 + k * 1024); } while (0)
; #define PG8_MMA(ai, bj, At, Bt) do { __builtin_amdgcn_s_setprio(1); _Pragma("unroll") for (int m = 0; m < 4; ++m) _Pragma("unroll") for (int n = 0; n < 2; ++n) _Pragma("unroll") for (int k = 0; k < 2; ++k) \
;         acc[ai][bj][m][n] = __builtin_amdgcn_mfma_f32_16x16x32_bf16(Bt[n][k], At[m][k], acc[ai][bj][m][n], 0, 0, 0); __builtin_amdgcn_s_setprio(0); } while (0)
; #define PG8_WAIT_V(n) asm volatile("s_waitcnt vmcnt(" #n ")" ::: "memory")
; #define PG8_WAIT_L(n) asm volatile("s_waitcnt lgkmcnt(" #n ")" ::: "memory")
; #define PG8_BAR __builtin_amdgcn_s_barrier()
; #define PG8_SCHED __builtin_amdgcn_sched_barrier(0)
; template <class Epi>
; __device__ __forceinline__ void gemm_phase(LAS unsigned char* lds, const Gemm g, const StaticOrder& S, const Epi& E) {
;     ...
;             PG8_STAGE(PG8_SB(0, 1), b2, hB, 0);
;             PG8_WAIT_V(6); PG8_BAR; PG8_MMA(1, 1, At, B1); PG8_BAR;
;             PG8_LDB(B0, 1, 0); PG8_SCHED; PG8_LDA(At, 1, 0); PG8_STAGE(PG8_SA(0, 1), a2, hA, 0);
;             PG8_WAIT_L(8); PG8_BAR; PG8_WAIT_L(0); PG8_MMA(0, 0, At, B0); PG8_BAR; PG8_SCHED;
;             PG8_LDB(B1, 1, 1); PG8_STAGE(PG8_SB(1, 0), b2 + KS, 0, 0);
	s_add_u32 s48, s76, 0x80000
	s_addc_u32 s49, s77, 0
	s_mov_b32 m0, s41
	s_nop 0
	global_load_lds_dwordx4 v152, s[48:49]
	s_add_u32 s48, s76, 0x82000
	s_addc_u32 s49, s77, 0
	s_mov_b32 m0, s42
	s_nop 0
	global_load_lds_dwordx4 v152, s[48:49]
	s_waitcnt vmcnt(10)
	s_barrier
	v_mfma_f32_16x16x32_bf16 v[32:35], v[240:243], v[144:147], v[32:35]
	v_mfma_f32_16x16x32_bf16 v[0:3], v[248:251], v[144:147], v[0:3]
	v_mfma_f32_16x16x32_bf16 v[36:39], v[240:243], v[184:187], v[36:39]
	v_mfma_f32_16x16x32_bf16 v[4:7], v[248:251], v[184:187], v[4:7]
	v_mfma_f32_16x16x32_bf16 v[40:43], v[240:243], v[204:207], v[40:43]
	v_mfma_f32_16x16x32_bf16 v[8:11], v[248:251], v[204:207], v[8:11]
	v_mfma_f32_16x16x32_bf16 v[44:47], v[240:243], v[212:215], v[44:47]
	v_mfma_f32_16x16x32_bf16 v[12:15], v[248:251], v[212:215], v[12:15]
	v_mfma_f32_16x16x32_bf16 v[32:35], v[244:247], v[148:151], v[32:35]
	v_mfma_f32_16x16x32_bf16 v[0:3], v[230:233], v[148:151], v[0:3]
	v_mfma_f32_16x16x32_bf16 v[36:39], v[244:247], v[200:203], v[36:39]
	v_mfma_f32_16x16x32_bf16 v[4:7], v[230:233], v[200:203], v[4:7]
	v_mfma_f32_16x16x32_bf16 v[40:43], v[244:247], v[208:211], v[40:43]
	v_mfma_f32_16x16x32_bf16 v[8:11], v[230:233], v[208:211], v[8:11]
	v_mfma_f32_16x16x32_bf16 v[44:47], v[244:247], v[236:239], v[44:47]
	v_mfma_f32_16x16x32_bf16 v[12:15], v[230:233], v[236:239], v[12:15]
	v_add_u32_e32 v140, 0x18000, v177
	s_barrier
	ds_read_b128 v[128:131], v140
	ds_read_b128 v[132:135], v140 offset:1024
	ds_read_b128 v[136:139], v140 offset:2048
	ds_read_b128 v[140:143], v140 offset:3072
	ds_read_b128 v[144:147], v178 offset:32768
	ds_read_b128 v[148:151], v178 offset:33792
	ds_read_b128 v[184:187], v178 offset:34816
	ds_read_b128 v[200:203], v178 offset:35840
	ds_read_b128 v[204:207], v178 offset:36864
	ds_read_b128 v[208:211], v178 offset:37888
	ds_read_b128 v[212:215], v178 offset:38912
	ds_read_b128 v[230:233], v178 offset:39936
	s_add_u32 s48, s80, 0x80000
	s_addc_u32 s49, s81, 0
	s_mov_b32 m0, s43
	s_nop 0
	global_load_lds_dwordx4 v152, s[48:49]
	s_add_u32 s48, s80, 0x82000
	s_addc_u32 s49, s81, 0
	s_mov_b32 m0, s92
	s_nop 0
	global_load_lds_dwordx4 v152, s[48:49]
	s_waitcnt lgkmcnt(8)
	s_waitcnt vmcnt(10)
	s_barrier
	s_waitcnt lgkmcnt(0)
	s_waitcnt lgkmcnt(7)
	v_mfma_f32_16x16x32_bf16 v[116:119], v[128:131], v[144:147], v[116:119]
	v_mfma_f32_16x16x32_bf16 v[80:83], v[136:139], v[144:147], v[80:83]
	s_waitcnt lgkmcnt(5)
	v_mfma_f32_16x16x32_bf16 v[88:91], v[128:131], v[184:187], v[88:91]
	v_mfma_f32_16x16x32_bf16 v[84:87], v[136:139], v[184:187], v[84:87]
	s_waitcnt lgkmcnt(3)
	v_mfma_f32_16x16x32_bf16 v[120:123], v[128:131], v[204:207], v[120:123]
	v_mfma_f32_16x16x32_bf16 v[92:95], v[136:139], v[204:207], v[92:95]
	s_waitcnt lgkmcnt(1)
	v_mfma_f32_16x16x32_bf16 v[124:127], v[128:131], v[212:215], v[124:127]
	v_mfma_f32_16x16x32_bf16 v[96:99], v[136:139], v[212:215], v[96:99]
	v_mfma_f32_16x16x32_bf16 v[116:119], v[132:135], v[148:151], v[116:119]
	v_mfma_f32_16x16x32_bf16 v[80:83], v[140:143], v[148:151], v[80:83]
	v_mfma_f32_16x16x32_bf16 v[88:91], v[132:135], v[200:203], v[88:91]
	v_mfma_f32_16x16x32_bf16 v[84:87], v[140:143], v[200:203], v[84:87]
	v_mfma_f32_16x16x32_bf16 v[120:123], v[132:135], v[208:211], v[120:123]
	v_mfma_f32_16x16x32_bf16 v[92:95], v[140:143], v[208:211], v[92:95]
	s_waitcnt lgkmcnt(0)
	v_mfma_f32_16x16x32_bf16 v[124:127], v[132:135], v[230:233], v[124:127]
	v_mfma_f32_16x16x32_bf16 v[96:99], v[140:143], v[230:233], v[96:99]
	s_barrier
	v_add_u32_e32 v188, 0x1c000, v177
	ds_read_b128 v[236:239], v188
	ds_read_b128 v[240:243], v188 offset:1024
	ds_read_b128 v[244:247], v188 offset:2048
	ds_read_b128 v[248:251], v188 offset:3072
	s_add_u32 s48, s76, 0x4000
	s_addc_u32 s49, s77, 0
	s_mov_b32 m0, s16
	s_nop 0
	global_load_lds_dwordx4 v152, s[48:49]
	s_add_u32 s48, s76, 0x6000
	s_addc_u32 s49, s77, 0
	s_mov_b32 m0, s17
	s_nop 0
	global_load_lds_dwordx4 v152, s[48:49]
	s_waitcnt vmcnt(10)
	s_barrier
; #define PG8_STAGE(bufoff, gbase, hoff, imm) do { _Pragma("unroll") for (int _i = 0; _i < 2; ++_i) { \
;         asm volatile("s_mov_b32 m0, %0\n\ts_nop 0\n\tglobal_load_lds_dwordx4 %1, %2" \
;             :: "s"(lds0 + (unsigned)((bufoff) + _i * 8192)), "v"(voff0), "s"((const char*)(gbase) + (size_t)(hoff) + (size_t)(_i * 8192)) : "memory"); } } while (0)
; #define PG8_LDA(dst, b, h) do { _Pragma("unroll") for (int m = 0; m < 4; ++m) _Pragma("unroll") for (int k = 0; k < 2; ++k) dst[m][k] = *(const LAS bf16x8*)(lds + PG8_SA(b, h) + aoff + m * 2048 + k * 1024); } while (0)
; #define PG8_MMA(ai, bj, At, Bt) do { __builtin_amdgcn_s_setprio(1); _Pragma("unroll") for (int m = 0; m < 4; ++m) _Pragma("unroll") for (int n = 0; n < 2; ++n) _Pragma("unroll") for (int k = 0; k < 2; ++k) \
;         acc[ai][bj][m][n] = __builtin_amdgcn_mfma_f32_16x16x32_bf16(Bt[n][k], At[m][k], acc[ai][bj][m][n], 0, 0, 0); __builtin_amdgcn_s_setprio(0); } while (0)
; #define PG8_WAIT_V(n) asm volatile("s_waitcnt vmcnt(" #n ")" ::: "memory")
; #define PG8_WAIT_L(n) asm volatile("s_waitcnt lgkmcnt(" #n ")" ::: "memory")
; #define PG8_BAR __builtin_amdgcn_s_barrier()
; #define PG8_SCHED __builtin_amdgcn_sched_barrier(0)
; template <class Epi>
; __device__ __forceinline__ void gemm_phase(LAS unsigned char* lds, const Gemm g, const StaticOrder& S, const Epi& E) {
;     ...
;             PG8_BAR; PG8_WAIT_L(0); PG8_MMA(0, 1, At, B1); PG8_BAR;
;             PG8_LDA(At, 1, 1); PG8_STAGE(PG8_SA(1, 0), a2 + KS, 0, 0);
;             PG8_BAR; PG8_WAIT_L(0); PG8_MMA(1, 0, At, B0); PG8_BAR; PG8_SCHED;
;             PG8_STAGE(PG8_SB(1, 1), b2 + KS, hB, 0);
;             PG8_WAIT_V(6); PG8_BAR; PG8_MMA(1, 1, At, B1); PG8_BAR;
	s_waitcnt lgkmcnt(0)
	s_waitcnt lgkmcnt(3)
	v_mfma_f32_16x16x32_bf16 v[48:51], v[236:239], v[144:147], v[48:51]
	s_waitcnt lgkmcnt(1)
	v_mfma_f32_16x16x32_bf16 v[16:19], v[244:247], v[144:147], v[16:19]
	v_mfma_f32_16x16x32_bf16 v[52:55], v[236:239], v[184:187], v[52:55]
	v_mfma_f32_16x16x32_bf16 v[20:23], v[244:247], v[184:187], v[20:23]
	v_mfma_f32_16x16x32_bf16 v[56:59], v[236:239], v[204:207], v[56:59]
	v_mfma_f32_16x16x32_bf16 v[24:27], v[244:247], v[204:207], v[24:27]
	v_mfma_f32_16x16x32_bf16 v[60:63], v[236:239], v[212:215], v[60:63]
	v_mfma_f32_16x16x32_bf16 v[28:31], v[244:247], v[212:215], v[28:31]
	v_mfma_f32_16x16x32_bf16 v[48:51], v[240:243], v[148:151], v[48:51]
	s_waitcnt lgkmcnt(0)
	v_mfma_f32_16x16x32_bf16 v[16:19], v[248:251], v[148:151], v[16:19]
	v_mfma_f32_16x16x32_bf16 v[52:55], v[240:243], v[200:203], v[52:55]
	v_mfma_f32_16x16x32_bf16 v[20:23], v[248:251], v[200:203], v[20:23]
	v_mfma_f32_16x16x32_bf16 v[56:59], v[240:243], v[208:211], v[56:59]
	v_mfma_f32_16x16x32_bf16 v[24:27], v[248:251], v[208:211], v[24:27]
	v_mfma_f32_16x16x32_bf16 v[60:63], v[240:243], v[230:233], v[60:63]
	v_mfma_f32_16x16x32_bf16 v[28:31], v[248:251], v[230:233], v[28:31]
	s_barrier
	ds_read_b128 v[144:147], v178 offset:49152
	ds_read_b128 v[148:151], v178 offset:50176
	ds_read_b128 v[184:187], v178 offset:51200
	ds_read_b128 v[200:203], v178 offset:52224
	ds_read_b128 v[204:207], v178 offset:53248
	ds_read_b128 v[208:211], v178 offset:54272
	ds_read_b128 v[212:215], v178 offset:55296
	ds_read_b128 v[230:233], v178 offset:56320
	s_add_u32 s48, s80, 0x4000
	s_addc_u32 s49, s81, 0
	s_mov_b32 m0, s24
	s_nop 0
	global_load_lds_dwordx4 v152, s[48:49]
	s_add_u32 s48, s80, 0x6000
	s_addc_u32 s49, s81, 0
	s_mov_b32 m0, s37
	s_nop 0
	global_load_lds_dwordx4 v152, s[48:49]
	s_barrier
	s_waitcnt lgkmcnt(0)
	s_waitcnt lgkmcnt(7)
	v_mfma_f32_16x16x32_bf16 v[100:103], v[128:131], v[144:147], v[100:103]
	v_mfma_f32_16x16x32_bf16 v[64:67], v[136:139], v[144:147], v[64:67]
	s_waitcnt lgkmcnt(5)
	v_mfma_f32_16x16x32_bf16 v[104:107], v[128:131], v[184:187], v[104:107]
	v_mfma_f32_16x16x32_bf16 v[68:71], v[136:139], v[184:187], v[68:71]
	s_waitcnt lgkmcnt(3)
	v_mfma_f32_16x16x32_bf16 v[108:111], v[128:131], v[204:207], v[108:111]
	v_mfma_f32_16x16x32_bf16 v[72:75], v[136:139], v[204:207], v[72:75]
	s_waitcnt lgkmcnt(1)
	v_mfma_f32_16x16x32_bf16 v[112:115], v[128:131], v[212:215], v[112:115]
	v_mfma_f32_16x16x32_bf16 v[76:79], v[136:139], v[212:215], v[76:79]
	v_mfma_f32_16x16x32_bf16 v[100:103], v[132:135], v[148:151], v[100:103]
	v_mfma_f32_16x16x32_bf16 v[64:67], v[140:143], v[148:151], v[64:67]
	v_mfma_f32_16x16x32_bf16 v[104:107], v[132:135], v[200:203], v[104:107]
	v_mfma_f32_16x16x32_bf16 v[68:71], v[140:143], v[200:203], v[68:71]
	v_mfma_f32_16x16x32_bf16 v[108:111], v[132:135], v[208:211], v[108:111]
	v_mfma_f32_16x16x32_bf16 v[72:75], v[140:143], v[208:211], v[72:75]
	s_waitcnt lgkmcnt(0)
	v_mfma_f32_16x16x32_bf16 v[112:115], v[132:135], v[230:233], v[112:115]
	v_mfma_f32_16x16x32_bf16 v[76:79], v[140:143], v[230:233], v[76:79]
	s_barrier
	s_add_u32 s48, s76, 0x84000
	s_addc_u32 s49, s77, 0
	s_mov_b32 m0, s97
	s_nop 0
	global_load_lds_dwordx4 v152, s[48:49]
	s_add_u32 s48, s76, 0x86000
	s_addc_u32 s49, s77, 0
	s_mov_b32 m0, s38
	s_nop 0
	global_load_lds_dwordx4 v152, s[48:49]
	s_waitcnt vmcnt(10)
	s_barrier
	v_mfma_f32_16x16x32_bf16 v[32:35], v[236:239], v[144:147], v[32:35]
	v_mfma_f32_16x16x32_bf16 v[0:3], v[244:247], v[144:147], v[0:3]
	v_mfma_f32_16x16x32_bf16 v[36:39], v[236:239], v[184:187], v[36:39]
	v_mfma_f32_16x16x32_bf16 v[4:7], v[244:247], v[184:187], v[4:7]
	v_mfma_f32_16x16x32_bf16 v[40:43], v[236:239], v[204:207], v[40:43]
	v_mfma_f32_16x16x32_bf16 v[8:11], v[244:247], v[204:207], v[8:11]
	v_mfma_f32_16x16x32_bf16 v[44:47], v[236:239], v[212:215], v[44:47]
	v_mfma_f32_16x16x32_bf16 v[12:15], v[244:247], v[212:215], v[12:15]
	v_mfma_f32_16x16x32_bf16 v[32:35], v[240:243], v[148:151], v[32:35]
	v_mfma_f32_16x16x32_bf16 v[0:3], v[248:251], v[148:151], v[0:3]
	v_mfma_f32_16x16x32_bf16 v[36:39], v[240:243], v[200:203], v[36:39]
	v_mfma_f32_16x16x32_bf16 v[4:7], v[248:251], v[200:203], v[4:7]
	v_mfma_f32_16x16x32_bf16 v[40:43], v[240:243], v[208:211], v[40:43]
	v_mfma_f32_16x16x32_bf16 v[8:11], v[248:251], v[208:211], v[8:11]
	v_mfma_f32_16x16x32_bf16 v[44:47], v[240:243], v[230:233], v[44:47]
	v_mfma_f32_16x16x32_bf16 v[12:15], v[248:251], v[230:233], v[12:15]
	s_add_i32 s71, s71, 2
	s_add_u32 s1, s1, 0x8000
	s_addc_u32 s9, s9, 0
	s_cmp_gt_u32 s71, 29
	s_mov_b64 s[76:77], s[78:79]
	s_barrier
	s_cbranch_scc1 .LBB0_741

; #define PG8_STAGE(bufoff, gbase, hoff, imm) do { _Pragma("unroll") for (int _i = 0; _i < 2; ++_i) { \
;         asm volatile("s_mov_b32 m0, %0\n\ts_nop 0\n\tglobal_load_lds_dwordx4 %1, %2" \
;             :: "s"(lds0 + (unsigned)((bufoff) + _i * 8192)), "v"(voff0), "s"((const char*)(gbase) + (size_t)(hoff) + (size_t)(_i * 8192)) : "memory"); } } while (0)
; #define PG8_LDA(dst, b, h) do { _Pragma("unroll") for (int m = 0; m < 4; ++m) _Pragma("unroll") for (int k = 0; k < 2; ++k) dst[m][k] = *(const LAS bf16x8*)(lds + PG8_SA(b, h) + aoff + m * 2048 + k * 1024); } while (0)
; #define PG8_LDB(dst, b, h) do { _Pragma("unroll") for (int n = 0; n < 2; ++n) _Pragma("unroll") for (int k = 0; k < 2; ++k) dst[n][k] = *(const LAS bf16x8*)(lds + PG8_SB(b, h) + boff + n * 2048 + k * 1024); } while (0)
; #define PG8_MMA(ai, bj, At, Bt) do { __builtin_amdgcn_s_setprio(1); _Pragma("unroll") for (int m = 0; m < 4; ++m) _Pragma("unroll") for (int n = 0; n < 2; ++n) _Pragma("unroll") for (int k = 0; k < 2; ++k) \
;         acc[ai][bj][m][n] = __builtin_amdgcn_mfma_f32_16x16x32_bf16(Bt[n][k], At[m][k], acc[ai][bj][m][n], 0, 0, 0); __builtin_amdgcn_s_setprio(0); } while (0)
; #define PG8_WAIT_L(n) asm volatile("s_waitcnt lgkmcnt(" #n ")" ::: "memory")
; #define PG8_BAR __builtin_amdgcn_s_barrier()
; #define PG8_SCHED __builtin_amdgcn_sched_barrier(0)
; template <class Epi>
; __device__ __forceinline__ void gemm_phase(LAS unsigned char* lds, const Gemm g, const StaticOrder& S, const Epi& E) {
;     ...
;             const char* aT = cA + (size_t)t * KS;
;             const char* a2 = last ? nA : aT + 2 * KS; const char* b2 = last ? nB : cB + (size_t)(t + 2) * KS;
;             PG8_LDB(B0, 0, 0); PG8_SCHED; PG8_LDA(At, 0, 0); PG8_STAGE(PG8_SA(1, 1), aT + KS, hA, 0);
;             PG8_WAIT_L(8); PG8_BAR; PG8_WAIT_L(0); PG8_MMA(0, 0, At, B0); PG8_BAR; PG8_SCHED;
;             PG8_LDB(B1, 0, 1); PG8_STAGE(PG8_SB(0, 0), b2, 0, 0);
;             PG8_BAR; PG8_WAIT_L(0); PG8_MMA(0, 1, At, B1); PG8_BAR;
;             PG8_LDA(At, 0, 1); PG8_STAGE(PG8_SA(0, 0), a2, 0, 0);
;             PG8_BAR; PG8_WAIT_L(0); PG8_MMA(1, 0, At, B0); PG8_BAR; PG8_SCHED;
.LBB0_860:
	s_add_u32 s58, s56, 0x8000
	v_add_u32_e32 v132, 0x10000, v236
	s_addc_u32 s59, s57, 0
	ds_read_b128 v[120:123], v132
	ds_read_b128 v[124:127], v132 offset:1024
	ds_read_b128 v[128:131], v132 offset:2048
	ds_read_b128 v[132:135], v132 offset:3072
	s_add_u32 s48, s56, 0x164000
	s_addc_u32 s49, s57, 0
	s_add_u32 s60, s56, 0x166000
	s_addc_u32 s61, s57, 0
	s_cmpk_eq_i32 s69, 0x54
	s_cselect_b32 s57, s7, s59
	s_cselect_b32 s56, s6, s58
	ds_read_b128 v[136:139], v237
	ds_read_b128 v[140:143], v237 offset:1024
	ds_read_b128 v[152:155], v237 offset:2048
	ds_read_b128 v[156:159], v237 offset:3072
	ds_read_b128 v[160:163], v237 offset:4096
	ds_read_b128 v[164:167], v237 offset:5120
	ds_read_b128 v[168:171], v237 offset:6144
	ds_read_b128 v[172:175], v237 offset:7168
	s_mov_b32 m0, s65
	s_nop 0
	global_load_lds_dwordx4 v188, s[48:49]
	s_mov_b32 m0, s66
	s_nop 0
	global_load_lds_dwordx4 v188, s[60:61]
	s_waitcnt lgkmcnt(8)
	s_waitcnt vmcnt(10)
	s_barrier
	s_waitcnt lgkmcnt(0)
	s_waitcnt lgkmcnt(7)
	v_mfma_f32_16x16x32_bf16 v[148:151], v[120:123], v[136:139], v[148:151]
	v_mfma_f32_16x16x32_bf16 v[144:147], v[128:131], v[136:139], v[144:147]
	s_waitcnt lgkmcnt(5)
	v_mfma_f32_16x16x32_bf16 v[108:111], v[120:123], v[152:155], v[108:111]
	v_mfma_f32_16x16x32_bf16 v[104:107], v[128:131], v[152:155], v[104:107]
	s_waitcnt lgkmcnt(3)
	v_mfma_f32_16x16x32_bf16 v[92:95], v[120:123], v[160:163], v[92:95]
	v_mfma_f32_16x16x32_bf16 v[88:91], v[128:131], v[160:163], v[88:91]
	s_waitcnt lgkmcnt(1)
	v_mfma_f32_16x16x32_bf16 v[76:79], v[120:123], v[168:171], v[76:79]
	v_mfma_f32_16x16x32_bf16 v[72:75], v[128:131], v[168:171], v[72:75]
	v_mfma_f32_16x16x32_bf16 v[148:151], v[124:127], v[140:143], v[148:151]
	v_mfma_f32_16x16x32_bf16 v[144:147], v[132:135], v[140:143], v[144:147]
	v_mfma_f32_16x16x32_bf16 v[108:111], v[124:127], v[156:159], v[108:111]
	v_mfma_f32_16x16x32_bf16 v[104:107], v[132:135], v[156:159], v[104:107]
	v_mfma_f32_16x16x32_bf16 v[92:95], v[124:127], v[164:167], v[92:95]
	v_mfma_f32_16x16x32_bf16 v[88:91], v[132:135], v[164:167], v[88:91]
	s_waitcnt lgkmcnt(0)
	v_mfma_f32_16x16x32_bf16 v[76:79], v[124:127], v[172:175], v[76:79]
	v_mfma_f32_16x16x32_bf16 v[72:75], v[132:135], v[172:175], v[72:75]
	s_barrier
	v_add_u32_e32 v200, 0x14000, v236
	ds_read_b128 v[176:179], v200
	ds_read_b128 v[180:183], v200 offset:1024
	ds_read_b128 v[184:187], v200 offset:2048
	ds_read_b128 v[200:203], v200 offset:3072
	s_cselect_b32 s60, s8, s0
	s_cselect_b32 s61, s9, s1
	s_mov_b32 m0, s26
	s_nop 0
	global_load_lds_dwordx4 v188, s[60:61]
	s_add_u32 s48, s60, 0x2000
	s_addc_u32 s49, s61, 0
	s_mov_b32 m0, s27
	s_nop 0
	global_load_lds_dwordx4 v188, s[48:49]
	s_waitcnt vmcnt(10)
	s_barrier
	s_waitcnt lgkmcnt(0)
	s_waitcnt lgkmcnt(3)
	v_mfma_f32_16x16x32_bf16 v[116:119], v[176:179], v[136:139], v[116:119]
	s_waitcnt lgkmcnt(1)
	v_mfma_f32_16x16x32_bf16 v[112:115], v[184:187], v[136:139], v[112:115]
	v_mfma_f32_16x16x32_bf16 v[100:103], v[176:179], v[152:155], v[100:103]
	v_mfma_f32_16x16x32_bf16 v[96:99], v[184:187], v[152:155], v[96:99]
	v_mfma_f32_16x16x32_bf16 v[84:87], v[176:179], v[160:163], v[84:87]
	v_mfma_f32_16x16x32_bf16 v[80:83], v[184:187], v[160:163], v[80:83]
	v_mfma_f32_16x16x32_bf16 v[68:71], v[176:179], v[168:171], v[68:71]
	v_mfma_f32_16x16x32_bf16 v[64:67], v[184:187], v[168:171], v[64:67]
	v_mfma_f32_16x16x32_bf16 v[116:119], v[180:183], v[140:143], v[116:119]
	s_waitcnt lgkmcnt(0)
	v_mfma_f32_16x16x32_bf16 v[112:115], v[200:203], v[140:143], v[112:115]
	v_mfma_f32_16x16x32_bf16 v[100:103], v[180:183], v[156:159], v[100:103]
	v_mfma_f32_16x16x32_bf16 v[96:99], v[200:203], v[156:159], v[96:99]
	v_mfma_f32_16x16x32_bf16 v[84:87], v[180:183], v[164:167], v[84:87]
	v_mfma_f32_16x16x32_bf16 v[80:83], v[200:203], v[164:167], v[80:83]
	v_mfma_f32_16x16x32_bf16 v[68:71], v[180:183], v[172:175], v[68:71]
	v_mfma_f32_16x16x32_bf16 v[64:67], v[200:203], v[172:175], v[64:67]
	s_barrier
	ds_read_b128 v[136:139], v237 offset:16384
	ds_read_b128 v[140:143], v237 offset:17408
	ds_read_b128 v[152:155], v237 offset:18432
	ds_read_b128 v[156:159], v237 offset:19456
	ds_read_b128 v[160:163], v237 offset:20480
	ds_read_b128 v[164:167], v237 offset:21504
	ds_read_b128 v[168:171], v237 offset:22528
	ds_read_b128 v[172:175], v237 offset:23552
	s_mov_b32 m0, s25
	s_nop 0
	global_load_lds_dwordx4 v188, s[56:57]
	s_add_u32 s48, s56, 0x2000
	s_addc_u32 s49, s57, 0
	s_mov_b32 m0, s28
	s_nop 0
	global_load_lds_dwordx4 v188, s[48:49]
	s_barrier
	s_waitcnt lgkmcnt(0)
	s_waitcnt lgkmcnt(7)
	v_mfma_f32_16x16x32_bf16 v[60:63], v[120:123], v[136:139], v[60:63]
	v_mfma_f32_16x16x32_bf16 v[56:59], v[128:131], v[136:139], v[56:59]
	s_waitcnt lgkmcnt(5)
	v_mfma_f32_16x16x32_bf16 v[44:47], v[120:123], v[152:155], v[44:47]
	v_mfma_f32_16x16x32_bf16 v[40:43], v[128:131], v[152:155], v[40:43]
	s_waitcnt lgkmcnt(3)
	v_mfma_f32_16x16x32_bf16 v[28:31], v[120:123], v[160:163], v[28:31]
	v_mfma_f32_16x16x32_bf16 v[24:27], v[128:131], v[160:163], v[24:27]
	s_waitcnt lgkmcnt(1)
	v_mfma_f32_16x16x32_bf16 v[12:15], v[120:123], v[168:171], v[12:15]
	v_mfma_f32_16x16x32_bf16 v[8:11], v[128:131], v[168:171], v[8:11]
	v_mfma_f32_16x16x32_bf16 v[60:63], v[124:127], v[140:143], v[60:63]
	v_mfma_f32_16x16x32_bf16 v[56:59], v[132:135], v[140:143], v[56:59]
	v_mfma_f32_16x16x32_bf16 v[44:47], v[124:127], v[156:159], v[44:47]
	v_mfma_f32_16x16x32_bf16 v[40:43], v[132:135], v[156:159], v[40:43]
	v_mfma_f32_16x16x32_bf16 v[28:31], v[124:127], v[164:167], v[28:31]
	v_mfma_f32_16x16x32_bf16 v[24:27], v[132:135], v[164:167], v[24:27]
	s_waitcnt lgkmcnt(0)
	v_mfma_f32_16x16x32_bf16 v[12:15], v[124:127], v[172:175], v[12:15]
	v_mfma_f32_16x16x32_bf16 v[8:11], v[132:135], v[172:175], v[8:11]
	s_barrier
; #define PG8_STAGE(bufoff, gbase, hoff, imm) do { _Pragma("unroll") for (int _i = 0; _i < 2; ++_i) { \
;         asm volatile("s_mov_b32 m0, %0\n\ts_nop 0\n\tglobal_load_lds_dwordx4 %1, %2" \
;             :: "s"(lds0 + (unsigned)((bufoff) + _i * 8192)), "v"(voff0), "s"((const char*)(gbase) + (size_t)(hoff) + (size_t)(_i * 8192)) : "memory"); } } while (0)
; #define PG8_LDA(dst, b, h) do { _Pragma("unroll") for (int m = 0; m < 4; ++m) _Pragma("unroll") for (int k = 0; k < 2; ++k) dst[m][k] = *(const LAS bf16x8*)(lds + PG8_SA(b, h) + aoff + m * 2048 + k * 1024); } while (0)
; #define PG8_LDB(dst, b, h) do { _Pragma("unroll") for (int n = 0; n < 2; ++n) _Pragma("unroll") for (int k = 0; k < 2; ++k) dst[n][k] = *(const LAS bf16x8*)(lds + PG8_SB(b, h) + boff + n * 2048 + k * 1024); } while (0)
; #define PG8_MMA(ai, bj, At, Bt) do { __builtin_amdgcn_s_setprio(1); _Pragma("unroll") for (int m = 0; m < 4; ++m) _Pragma("unroll") for (int n = 0; n < 2; ++n) _Pragma("unroll") for (int k = 0; k < 2; ++k) \
;         acc[ai][bj][m][n] = __builtin_amdgcn_mfma_f32_16x16x32_bf16(Bt[n][k], At[m][k], acc[ai][bj][m][n], 0, 0, 0); __builtin_amdgcn_s_setprio(0); } while (0)
; #define PG8_WAIT_V(n) asm volatile("s_waitcnt vmcnt(" #n ")" ::: "memory")
; #define PG8_WAIT_L(n) asm volatile("s_waitcnt lgkmcnt(" #n ")" ::: "memory")
; #define PG8_BAR __builtin_amdgcn_s_barrier()
; #define PG8_SCHED __builtin_amdgcn_sched_barrier(0)
; template <class Epi>
; __device__ __forceinline__ void gemm_phase(LAS unsigned char* lds, const Gemm g, const StaticOrder& S, const Epi& E) {
;     ...
;             PG8_STAGE(PG8_SB(0, 1), b2, hB, 0);
;             PG8_WAIT_V(6); PG8_BAR; PG8_MMA(1, 1, At, B1); PG8_BAR;
;             PG8_LDB(B0, 1, 0); PG8_SCHED; PG8_LDA(At, 1, 0); PG8_STAGE(PG8_SA(0, 1), a2, hA, 0);
;             PG8_WAIT_L(8); PG8_BAR; PG8_WAIT_L(0); PG8_MMA(0, 0, At, B0); PG8_BAR; PG8_SCHED;
;             PG8_LDB(B1, 1, 1); PG8_STAGE(PG8_SB(1, 0), b2 + KS, 0, 0);
;             PG8_BAR; PG8_WAIT_L(0); PG8_MMA(0, 1, At, B1); PG8_BAR;
;             PG8_LDA(At, 1, 1); PG8_STAGE(PG8_SA(1, 0), a2 + KS, 0, 0);
	s_add_u32 s48, s60, 0x160000
	s_addc_u32 s49, s61, 0
	s_mov_b32 m0, s29
	s_nop 0
	global_load_lds_dwordx4 v188, s[48:49]
	s_add_u32 s48, s60, 0x162000
	s_addc_u32 s49, s61, 0
	s_mov_b32 m0, s30
	s_nop 0
	global_load_lds_dwordx4 v188, s[48:49]
	s_waitcnt vmcnt(10)
	s_barrier
	v_mfma_f32_16x16x32_bf16 v[52:55], v[176:179], v[136:139], v[52:55]
	v_mfma_f32_16x16x32_bf16 v[48:51], v[184:187], v[136:139], v[48:51]
	v_mfma_f32_16x16x32_bf16 v[36:39], v[176:179], v[152:155], v[36:39]
	v_mfma_f32_16x16x32_bf16 v[32:35], v[184:187], v[152:155], v[32:35]
	v_mfma_f32_16x16x32_bf16 v[20:23], v[176:179], v[160:163], v[20:23]
	v_mfma_f32_16x16x32_bf16 v[16:19], v[184:187], v[160:163], v[16:19]
	v_mfma_f32_16x16x32_bf16 v[4:7], v[176:179], v[168:171], v[4:7]
	v_mfma_f32_16x16x32_bf16 v[0:3], v[184:187], v[168:171], v[0:3]
	v_mfma_f32_16x16x32_bf16 v[52:55], v[180:183], v[140:143], v[52:55]
	v_mfma_f32_16x16x32_bf16 v[48:51], v[200:203], v[140:143], v[48:51]
	v_mfma_f32_16x16x32_bf16 v[36:39], v[180:183], v[156:159], v[36:39]
	v_mfma_f32_16x16x32_bf16 v[32:35], v[200:203], v[156:159], v[32:35]
	v_mfma_f32_16x16x32_bf16 v[20:23], v[180:183], v[164:167], v[20:23]
	v_mfma_f32_16x16x32_bf16 v[16:19], v[200:203], v[164:167], v[16:19]
	v_mfma_f32_16x16x32_bf16 v[4:7], v[180:183], v[172:175], v[4:7]
	v_mfma_f32_16x16x32_bf16 v[0:3], v[200:203], v[172:175], v[0:3]
	v_add_u32_e32 v132, 0x18000, v236
	s_barrier
	ds_read_b128 v[120:123], v132
	ds_read_b128 v[124:127], v132 offset:1024
	ds_read_b128 v[128:131], v132 offset:2048
	ds_read_b128 v[132:135], v132 offset:3072
	ds_read_b128 v[136:139], v237 offset:32768
	ds_read_b128 v[140:143], v237 offset:33792
	ds_read_b128 v[152:155], v237 offset:34816
	ds_read_b128 v[156:159], v237 offset:35840
	ds_read_b128 v[160:163], v237 offset:36864
	ds_read_b128 v[164:167], v237 offset:37888
	ds_read_b128 v[168:171], v237 offset:38912
	ds_read_b128 v[172:175], v237 offset:39936
	s_add_u32 s48, s56, 0x160000
	s_addc_u32 s49, s57, 0
	s_mov_b32 m0, s34
	s_nop 0
	global_load_lds_dwordx4 v188, s[48:49]
	s_add_u32 s48, s56, 0x162000
	s_addc_u32 s49, s57, 0
	s_mov_b32 m0, s37
	s_nop 0
	global_load_lds_dwordx4 v188, s[48:49]
	s_waitcnt lgkmcnt(8)
	s_waitcnt vmcnt(10)
	s_barrier
	s_waitcnt lgkmcnt(0)
	s_waitcnt lgkmcnt(7)
	v_mfma_f32_16x16x32_bf16 v[148:151], v[120:123], v[136:139], v[148:151]
	v_mfma_f32_16x16x32_bf16 v[144:147], v[128:131], v[136:139], v[144:147]
	s_waitcnt lgkmcnt(5)
	v_mfma_f32_16x16x32_bf16 v[108:111], v[120:123], v[152:155], v[108:111]
	v_mfma_f32_16x16x32_bf16 v[104:107], v[128:131], v[152:155], v[104:107]
	s_waitcnt lgkmcnt(3)
	v_mfma_f32_16x16x32_bf16 v[92:95], v[120:123], v[160:163], v[92:95]
	v_mfma_f32_16x16x32_bf16 v[88:91], v[128:131], v[160:163], v[88:91]
	s_waitcnt lgkmcnt(1)
	v_mfma_f32_16x16x32_bf16 v[76:79], v[120:123], v[168:171], v[76:79]
	v_mfma_f32_16x16x32_bf16 v[72:75], v[128:131], v[168:171], v[72:75]
	v_mfma_f32_16x16x32_bf16 v[148:151], v[124:127], v[140:143], v[148:151]
	v_mfma_f32_16x16x32_bf16 v[144:147], v[132:135], v[140:143], v[144:147]
	v_mfma_f32_16x16x32_bf16 v[108:111], v[124:127], v[156:159], v[108:111]
	v_mfma_f32_16x16x32_bf16 v[104:107], v[132:135], v[156:159], v[104:107]
	v_mfma_f32_16x16x32_bf16 v[92:95], v[124:127], v[164:167], v[92:95]
	v_mfma_f32_16x16x32_bf16 v[88:91], v[132:135], v[164:167], v[88:91]
	s_waitcnt lgkmcnt(0)
	v_mfma_f32_16x16x32_bf16 v[76:79], v[124:127], v[172:175], v[76:79]
	v_mfma_f32_16x16x32_bf16 v[72:75], v[132:135], v[172:175], v[72:75]
	s_barrier
	v_add_u32_e32 v200, 0x1c000, v236
	ds_read_b128 v[176:179], v200
	ds_read_b128 v[180:183], v200 offset:1024
	ds_read_b128 v[184:187], v200 offset:2048
	ds_read_b128 v[200:203], v200 offset:3072
	s_add_u32 s48, s60, 0x4000
	s_addc_u32 s49, s61, 0
	s_mov_b32 m0, s41
	s_nop 0
	global_load_lds_dwordx4 v188, s[48:49]
	s_add_u32 s48, s60, 0x6000
	s_addc_u32 s49, s61, 0
	s_mov_b32 m0, s42
	s_nop 0
	global_load_lds_dwordx4 v188, s[48:49]
	s_waitcnt vmcnt(10)
	s_barrier
	s_waitcnt lgkmcnt(0)
	s_waitcnt lgkmcnt(3)
	v_mfma_f32_16x16x32_bf16 v[116:119], v[176:179], v[136:139], v[116:119]
	s_waitcnt lgkmcnt(1)
	v_mfma_f32_16x16x32_bf16 v[112:115], v[184:187], v[136:139], v[112:115]
	v_mfma_f32_16x16x32_bf16 v[100:103], v[176:179], v[152:155], v[100:103]
	v_mfma_f32_16x16x32_bf16 v[96:99], v[184:187], v[152:155], v[96:99]
	v_mfma_f32_16x16x32_bf16 v[84:87], v[176:179], v[160:163], v[84:87]
	v_mfma_f32_16x16x32_bf16 v[80:83], v[184:187], v[160:163], v[80:83]
	v_mfma_f32_16x16x32_bf16 v[68:71], v[176:179], v[168:171], v[68:71]
	v_mfma_f32_16x16x32_bf16 v[64:67], v[184:187], v[168:171], v[64:67]
	v_mfma_f32_16x16x32_bf16 v[116:119], v[180:183], v[140:143], v[116:119]
	s_waitcnt lgkmcnt(0)
	v_mfma_f32_16x16x32_bf16 v[112:115], v[200:203], v[140:143], v[112:115]
	v_mfma_f32_16x16x32_bf16 v[100:103], v[180:183], v[156:159], v[100:103]
	v_mfma_f32_16x16x32_bf16 v[96:99], v[200:203], v[156:159], v[96:99]
	v_mfma_f32_16x16x32_bf16 v[84:87], v[180:183], v[164:167], v[84:87]
	v_mfma_f32_16x16x32_bf16 v[80:83], v[200:203], v[164:167], v[80:83]
	v_mfma_f32_16x16x32_bf16 v[68:71], v[180:183], v[172:175], v[68:71]
	v_mfma_f32_16x16x32_bf16 v[64:67], v[200:203], v[172:175], v[64:67]
	s_barrier
	ds_read_b128 v[136:139], v237 offset:49152
	ds_read_b128 v[140:143], v237 offset:50176
	ds_read_b128 v[152:155], v237 offset:51200
	ds_read_b128 v[156:159], v237 offset:52224
	ds_read_b128 v[160:163], v237 offset:53248
	ds_read_b128 v[164:167], v237 offset:54272
	ds_read_b128 v[168:171], v237 offset:55296
	ds_read_b128 v[172:175], v237 offset:56320
	s_add_u32 s48, s56, 0x4000
	s_addc_u32 s49, s57, 0
	s_mov_b32 m0, s43
	s_nop 0
	global_load_lds_dwordx4 v188, s[48:49]
	s_add_u32 s48, s56, 0x6000
	s_addc_u32 s49, s57, 0
	s_mov_b32 m0, s62
	s_nop 0
	global_load_lds_dwordx4 v188, s[48:49]
	s_barrier
; #define PG8_BAR __builtin_amdgcn_s_barrier()
; template <class Epi>
; __device__ __forceinline__ void gemm_phase(LAS unsigned char* lds, const Gemm g, const StaticOrder& S, const Epi& E) {
;     ...
;             PG8_WAIT_V(6); PG8_BAR; PG8_MMA(1, 1, At, B1); PG8_BAR;
;             PG8_LDB(B0, 1, 0); PG8_SCHED; PG8_LDA(At, 1, 0); PG8_STAGE(PG8_SA(0, 1), a2, hA, 0);
;             PG8_WAIT_L(8); PG8_BAR; PG8_WAIT_L(0); PG8_MMA(0, 0, At, B0); PG8_BAR; PG8_SCHED;
;             PG8_LDB(B1, 1, 1); PG8_STAGE(PG8_SB(1, 0), b2 + KS, 0, 0);
;             PG8_BAR; PG8_WAIT_L(0); PG8_MMA(0, 1, At, B1); PG8_BAR;
;             PG8_LDA(At, 1, 1); PG8_STAGE(PG8_SA(1, 0), a2 + KS, 0, 0);
;             PG8_BAR; PG8_WAIT_L(0); PG8_MMA(1, 0, At, B0); PG8_BAR; PG8_SCHED;
;             PG8_STAGE(PG8_SB(1, 1), b2 + KS, hB, 0);
;             PG8_WAIT_V(6); PG8_BAR; PG8_MMA(1, 1, At, B1); PG8_BAR;
;     __device__ __forceinline__ void operator()(f32x4 (&acc)[2][2][4][2], const Unit& u, int wr, int wc, int fr, int fq, LAS unsigned char*) const {
;         const int b = u.pm >> 6;
;         const int col0 = u.pn * BM + wc * 32 + 8 * fq;
;         const size_t off0 = (size_t)(u.pm * BM + wr * 64 + fr) * D + col0;
;         f32x4 sc[2][2];
; #pragma unroll
;         for (int bj = 0; bj < 2; ++bj)
; #pragma unroll
;             for (int n = 0; n < 2; ++n) { f32x4 gt = *(const f32x4*)(gate + (size_t)b * MODW + col0 + bj * HALF + n * 4); sc[bj][n] = gt + 1.0f;
;                 if (cs) sc[bj][n] *= *(const f32x4*)(cs + col0 + bj * HALF + n * 4); }
;         if (IN_F32) {
; #pragma unroll
;             for (int ai = 0; ai < 2; ++ai) {
;                 f32x4 r[4][2][2];
; #pragma unroll
;                 for (int m = 0; m < 4; ++m)
; #pragma unroll
;                     for (int bj = 0; bj < 2; ++bj)
; #pragma unroll
;                         for (int n = 0; n < 2; ++n) r[m][bj][n] = *(const f32x4*)((const float*)in + off0 + (size_t)(ai * HALF + m * 16) * D + bj * HALF + n * 4);
; #pragma unroll
;                 for (int m = 0; m < 4; ++m)
; #pragma unroll
;                     for (int bj = 0; bj < 2; ++bj) { const f32x4 r0 = r[m][bj][0] + sc[bj][0] * acc[ai][bj][m][0], r1 = r[m][bj][1] + sc[bj][1] * acc[ai][bj][m][1];
;                         u32x4 w; w.x = cvt_pk_bf16(r0[0], r0[1]); w.y = cvt_pk_bf16(r0[2], r0[3]); w.z = cvt_pk_bf16(r1[0], r1[1]); w.w = cvt_pk_bf16(r1[2], r1[3]);
	s_waitcnt lgkmcnt(0)
	s_waitcnt lgkmcnt(7)
	v_mfma_f32_16x16x32_bf16 v[60:63], v[120:123], v[136:139], v[60:63]
	v_mfma_f32_16x16x32_bf16 v[56:59], v[128:131], v[136:139], v[56:59]
	s_waitcnt lgkmcnt(5)
	v_mfma_f32_16x16x32_bf16 v[44:47], v[120:123], v[152:155], v[44:47]
	v_mfma_f32_16x16x32_bf16 v[40:43], v[128:131], v[152:155], v[40:43]
	s_waitcnt lgkmcnt(3)
	v_mfma_f32_16x16x32_bf16 v[28:31], v[120:123], v[160:163], v[28:31]
	v_mfma_f32_16x16x32_bf16 v[24:27], v[128:131], v[160:163], v[24:27]
	s_waitcnt lgkmcnt(1)
	v_mfma_f32_16x16x32_bf16 v[12:15], v[120:123], v[168:171], v[12:15]
	v_mfma_f32_16x16x32_bf16 v[8:11], v[128:131], v[168:171], v[8:11]
	v_mfma_f32_16x16x32_bf16 v[60:63], v[124:127], v[140:143], v[60:63]
	v_mfma_f32_16x16x32_bf16 v[56:59], v[132:135], v[140:143], v[56:59]
	v_mfma_f32_16x16x32_bf16 v[44:47], v[124:127], v[156:159], v[44:47]
	v_mfma_f32_16x16x32_bf16 v[40:43], v[132:135], v[156:159], v[40:43]
	v_mfma_f32_16x16x32_bf16 v[28:31], v[124:127], v[164:167], v[28:31]
	v_mfma_f32_16x16x32_bf16 v[24:27], v[132:135], v[164:167], v[24:27]
	s_waitcnt lgkmcnt(0)
	v_mfma_f32_16x16x32_bf16 v[12:15], v[124:127], v[172:175], v[12:15]
	v_mfma_f32_16x16x32_bf16 v[8:11], v[132:135], v[172:175], v[8:11]
	s_barrier
	s_add_u32 s48, s60, 0x164000
	s_addc_u32 s49, s61, 0
	s_mov_b32 m0, s63
	s_nop 0
	global_load_lds_dwordx4 v188, s[48:49]
	s_add_u32 s48, s60, 0x166000
	s_addc_u32 s49, s61, 0
	s_mov_b32 m0, s64
	s_nop 0
	global_load_lds_dwordx4 v188, s[48:49]
	s_waitcnt vmcnt(10)
	s_barrier
	v_mfma_f32_16x16x32_bf16 v[52:55], v[176:179], v[136:139], v[52:55]
	v_mfma_f32_16x16x32_bf16 v[48:51], v[184:187], v[136:139], v[48:51]
	v_mfma_f32_16x16x32_bf16 v[36:39], v[176:179], v[152:155], v[36:39]
	v_mfma_f32_16x16x32_bf16 v[32:35], v[184:187], v[152:155], v[32:35]
	v_mfma_f32_16x16x32_bf16 v[20:23], v[176:179], v[160:163], v[20:23]
	v_mfma_f32_16x16x32_bf16 v[16:19], v[184:187], v[160:163], v[16:19]
	v_mfma_f32_16x16x32_bf16 v[4:7], v[176:179], v[168:171], v[4:7]
	v_mfma_f32_16x16x32_bf16 v[0:3], v[184:187], v[168:171], v[0:3]
	v_mfma_f32_16x16x32_bf16 v[52:55], v[180:183], v[140:143], v[52:55]
	v_mfma_f32_16x16x32_bf16 v[48:51], v[200:203], v[140:143], v[48:51]
	v_mfma_f32_16x16x32_bf16 v[36:39], v[180:183], v[156:159], v[36:39]
	v_mfma_f32_16x16x32_bf16 v[32:35], v[200:203], v[156:159], v[32:35]
	v_mfma_f32_16x16x32_bf16 v[20:23], v[180:183], v[164:167], v[20:23]
	v_mfma_f32_16x16x32_bf16 v[16:19], v[200:203], v[164:167], v[16:19]
	v_mfma_f32_16x16x32_bf16 v[4:7], v[180:183], v[172:175], v[4:7]
	v_mfma_f32_16x16x32_bf16 v[0:3], v[200:203], v[172:175], v[0:3]
	s_add_i32 s69, s69, 2
	s_add_u32 s0, s0, 0x8000
	s_addc_u32 s1, s1, 0
	s_cmpk_gt_u32 s69, 0x55
	s_mov_b64 s[56:57], s[58:59]
	s_barrier
	s_cbranch_scc0 .LBB0_860
	s_ashr_i32 s0, s50, 6
	s_mul_hi_i32 s1, s0, 0xc000
	s_mul_i32 s0, s0, 0xc000
	v_lshl_or_b32 v128, s51, 8, v234
	s_add_u32 s0, s39, s0
	v_ashrrev_i32_e32 v129, 31, v128
	s_addc_u32 s1, s40, s1
	v_lshl_add_u64 v[130:131], v[128:129], 2, s[0:1]
	global_load_dwordx4 v[120:123], v[130:131], off offset:16
	global_load_dwordx4 v[124:127], v[130:131], off
	s_mov_b32 s51, s67
	s_mov_b64 s[58:59], s[8:9]
	s_mov_b64 s[56:57], s[6:7]
	s_waitcnt vmcnt(1)
	v_pk_add_f32 v[210:211], v[122:123], 1.0 op_sel_hi:[1,0]
	s_waitcnt vmcnt(0)
	v_pk_add_f32 v[214:215], v[126:127], 1.0 op_sel_hi:[1,0]
	v_pk_add_f32 v[212:213], v[124:125], 1.0 op_sel_hi:[1,0]
	v_pk_add_f32 v[208:209], v[120:121], 1.0 op_sel_hi:[1,0]
	global_load_dwordx4 v[120:123], v[130:131], off offset:528
	global_load_dwordx4 v[124:127], v[130:131], off offset:512
	s_waitcnt vmcnt(1)
	v_pk_add_f32 v[200:201], v[120:121], 1.0 op_sel_hi:[1,0]
	v_lshl_add_u32 v120, s50, 8, v233
	v_ashrrev_i32_e32 v121, 31, v120
	v_lshlrev_b64 v[120:121], 11, v[120:121]
	v_lshl_add_u64 v[120:121], v[120:121], 0, v[128:129]
	v_lshlrev_b64 v[216:217], 1, v[120:121]
	v_lshl_add_u64 v[120:121], s[52:53], 0, v[216:217]
	global_load_dwordx4 v[238:241], v[120:121], off
	global_load_dwordx4 v[184:187], v[120:121], off offset:256
	v_pk_add_f32 v[202:203], v[122:123], 1.0 op_sel_hi:[1,0]
	v_add_co_u32_e32 v122, vcc, s45, v120
	s_waitcnt vmcnt(2)
	v_pk_add_f32 v[206:207], v[126:127], 1.0 op_sel_hi:[1,0]
	v_addc_co_u32_e32 v123, vcc, 0, v121, vcc
	global_load_dwordx4 v[180:183], v[122:123], off
	global_load_dwordx4 v[176:179], v[122:123], off offset:256
	v_add_co_u32_e32 v122, vcc, s36, v120
	v_pk_add_f32 v[204:205], v[124:125], 1.0 op_sel_hi:[1,0]
	s_nop 0
	v_addc_co_u32_e32 v123, vcc, 0, v121, vcc
	global_load_dwordx4 v[172:175], v[122:123], off
	global_load_dwordx4 v[168:171], v[122:123], off offset:256
	v_add_co_u32_e32 v122, vcc, s23, v120
	s_mov_b32 s50, s68
	s_nop 0
	v_addc_co_u32_e32 v123, vcc, 0, v121, vcc
	global_load_dwordx4 v[164:167], v[122:123], off
	global_load_dwordx4 v[160:163], v[122:123], off offset:256
	v_add_co_u32_e32 v122, vcc, s93, v120
	s_waitcnt vmcnt(7)
; __device__ __forceinline__ unsigned cvt_pk_bf16(float lo, float hi) { unsigned r; asm volatile("v_cvt_pk_bf16_f32 %0, %1, %2" : "=v"(r) : "v"(lo), "v"(hi)); return r; }
;     __device__ __forceinline__ void operator()(f32x4 (&acc)[2][2][4][2], const Unit& u, int wr, int wc, int fr, int fq, LAS unsigned char*) const {
;     ...
;             u32x4 xb[2][4][2];
; #pragma unroll
;             for (int ai = 0; ai < 2; ++ai)
; #pragma unroll
;                 for (int m = 0; m < 4; ++m)
; #pragma unroll
;                     for (int bj = 0; bj < 2; ++bj) xb[ai][m][bj] = *(const u32x4*)((const bf16_t*)in + off0 + (size_t)(ai * HALF + m * 16) * D + bj * HALF);
; #pragma unroll
;             for (int ai = 0; ai < 2; ++ai)
; #pragma unroll
;                 for (int m = 0; m < 4; ++m)
; #pragma unroll
;                     for (int bj = 0; bj < 2; ++bj) { const u32x4 x = xb[ai][m][bj];
;                         f32x4 r0 = (f32x4){__uint_as_float(x.x << 16), __uint_as_float(x.x & 0xffff0000u), __uint_as_float(x.y << 16), __uint_as_float(x.y & 0xffff0000u)};
;                         f32x4 r1 = (f32x4){__uint_as_float(x.z << 16), __uint_as_float(x.z & 0xffff0000u), __uint_as_float(x.w << 16), __uint_as_float(x.w & 0xffff0000u)};
;                         r0 += sc[bj][0] * acc[ai][bj][m][0]; r1 += sc[bj][1] * acc[ai][bj][m][1];
;                         u32x4 w; w.x = cvt_pk_bf16(r0[0], r0[1]); w.y = cvt_pk_bf16(r0[2], r0[3]); w.z = cvt_pk_bf16(r1[0], r1[1]); w.w = cvt_pk_bf16(r1[2], r1[3]);
;                         *(u32x4*)(out + off0 + (size_t)(ai * HALF + m * 16) * D + bj * HALF) = w; }
	v_lshlrev_b32_e32 v230, 16, v238
	v_addc_co_u32_e32 v123, vcc, 0, v121, vcc
	global_load_dwordx4 v[156:159], v[122:123], off
	global_load_dwordx4 v[152:155], v[122:123], off offset:256
	v_add_co_u32_e32 v122, vcc, s33, v120
	v_and_b32_e32 v231, 0xffff0000, v238
	s_nop 0
	v_addc_co_u32_e32 v123, vcc, 0, v121, vcc
	global_load_dwordx4 v[140:143], v[122:123], off
	global_load_dwordx4 v[136:139], v[122:123], off offset:256
	v_add_co_u32_e32 v122, vcc, s18, v120
	v_lshlrev_b32_e32 v242, 16, v240
	s_nop 0
	v_addc_co_u32_e32 v123, vcc, 0, v121, vcc
	global_load_dwordx4 v[132:135], v[122:123], off
	global_load_dwordx4 v[128:131], v[122:123], off offset:256
	v_add_co_u32_e32 v120, vcc, s19, v120
	v_and_b32_e32 v243, 0xffff0000, v240
	s_nop 0
	v_addc_co_u32_e32 v121, vcc, 0, v121, vcc
	global_load_dwordx4 v[124:127], v[120:121], off
	s_nop 0
	global_load_dwordx4 v[120:123], v[120:121], off offset:256
	v_lshlrev_b32_e32 v238, 16, v239
	v_and_b32_e32 v239, 0xffff0000, v239
	v_lshlrev_b32_e32 v240, 16, v241
	v_and_b32_e32 v241, 0xffff0000, v241
	v_pk_fma_f32 v[148:149], v[148:149], v[212:213], v[230:231]
	v_pk_fma_f32 v[144:145], v[144:145], v[208:209], v[242:243]
	v_pk_fma_f32 v[150:151], v[150:151], v[214:215], v[238:239]
	v_pk_fma_f32 v[230:231], v[146:147], v[210:211], v[240:241]
	v_cvt_pk_bf16_f32 v146, v148, v149
	v_cvt_pk_bf16_f32 v147, v150, v151
	v_cvt_pk_bf16_f32 v148, v144, v145
	v_lshl_add_u64 v[144:145], s[54:55], 0, v[216:217]
	v_cvt_pk_bf16_f32 v149, v230, v231
	global_store_dwordx4 v[144:145], v[146:149], off
	s_waitcnt vmcnt(15)
	v_lshlrev_b32_e32 v150, 16, v186
	v_and_b32_e32 v151, 0xffff0000, v186
	v_lshlrev_b32_e32 v146, 16, v184
	v_and_b32_e32 v147, 0xffff0000, v184
	v_lshlrev_b32_e32 v148, 16, v185
	v_and_b32_e32 v149, 0xffff0000, v185
	v_lshlrev_b32_e32 v184, 16, v187
	v_and_b32_e32 v185, 0xffff0000, v187
	v_pk_fma_f32 v[118:119], v[118:119], v[206:207], v[148:149]
	v_pk_fma_f32 v[116:117], v[116:117], v[204:205], v[146:147]
	v_pk_fma_f32 v[146:147], v[114:115], v[202:203], v[184:185]
	v_pk_fma_f32 v[114:115], v[112:113], v[200:201], v[150:151]
	v_cvt_pk_bf16_f32 v112, v116, v117
	v_cvt_pk_bf16_f32 v113, v118, v119
	s_waitcnt vmcnt(14)
	v_lshlrev_b32_e32 v116, 16, v182
	v_cvt_pk_bf16_f32 v114, v114, v115
	v_cvt_pk_bf16_f32 v115, v146, v147
	global_store_dwordx4 v[144:145], v[112:115], off offset:256
	v_and_b32_e32 v117, 0xffff0000, v182
	v_lshlrev_b32_e32 v118, 16, v183
	v_lshlrev_b32_e32 v112, 16, v180
	v_and_b32_e32 v113, 0xffff0000, v180
	v_and_b32_e32 v119, 0xffff0000, v183
	v_pk_fma_f32 v[108:109], v[108:109], v[212:213], v[112:113]
	v_lshlrev_b32_e32 v114, 16, v181
	v_and_b32_e32 v115, 0xffff0000, v181
	v_pk_fma_f32 v[112:113], v[106:107], v[210:211], v[118:119]
	v_pk_fma_f32 v[106:107], v[104:105], v[208:209], v[116:117]
	v_cvt_pk_bf16_f32 v104, v108, v109
	v_add_co_u32_e32 v108, vcc, s45, v144
	v_pk_fma_f32 v[110:111], v[110:111], v[214:215], v[114:115]
	s_nop 0
	v_addc_co_u32_e32 v109, vcc, 0, v145, vcc
	v_cvt_pk_bf16_f32 v105, v110, v111
	v_cvt_pk_bf16_f32 v106, v106, v107
	v_cvt_pk_bf16_f32 v107, v112, v113
	global_store_dwordx4 v[108:109], v[104:107], off
	s_waitcnt vmcnt(15)
	v_lshlrev_b32_e32 v110, 16, v178
	v_and_b32_e32 v111, 0xffff0000, v178
	v_lshlrev_b32_e32 v104, 16, v176
	v_and_b32_e32 v105, 0xffff0000, v176
	v_lshlrev_b32_e32 v106, 16, v177
	v_and_b32_e32 v107, 0xffff0000, v177
	v_lshlrev_b32_e32 v112, 16, v179
	v_and_b32_e32 v113, 0xffff0000, v179
	v_pk_fma_f32 v[102:103], v[102:103], v[206:207], v[106:107]
	v_pk_fma_f32 v[100:101], v[100:101], v[204:205], v[104:105]
	v_pk_fma_f32 v[104:105], v[98:99], v[202:203], v[112:113]
	v_pk_fma_f32 v[98:99], v[96:97], v[200:201], v[110:111]
	v_cvt_pk_bf16_f32 v96, v100, v101
	v_cvt_pk_bf16_f32 v97, v102, v103
	s_waitcnt vmcnt(14)
	v_lshlrev_b32_e32 v100, 16, v174
	v_cvt_pk_bf16_f32 v98, v98, v99
	v_cvt_pk_bf16_f32 v99, v104, v105
	global_store_dwordx4 v[108:109], v[96:99], off offset:256
	v_and_b32_e32 v101, 0xffff0000, v174
	v_lshlrev_b32_e32 v102, 16, v175
	v_lshlrev_b32_e32 v96, 16, v172
	v_and_b32_e32 v97, 0xffff0000, v172
	v_and_b32_e32 v103, 0xffff0000, v175
	v_pk_fma_f32 v[92:93], v[92:93], v[212:213], v[96:97]
	v_lshlrev_b32_e32 v98, 16, v173
	v_and_b32_e32 v99, 0xffff0000, v173
	v_pk_fma_f32 v[96:97], v[90:91], v[210:211], v[102:103]
	v_pk_fma_f32 v[90:91], v[88:89], v[208:209], v[100:101]
	v_cvt_pk_bf16_f32 v88, v92, v93
	v_add_co_u32_e32 v92, vcc, s36, v144
	v_pk_fma_f32 v[94:95], v[94:95], v[214:215], v[98:99]
	s_nop 0
	v_addc_co_u32_e32 v93, vcc, 0, v145, vcc
	v_cvt_pk_bf16_f32 v89, v94, v95
	v_cvt_pk_bf16_f32 v90, v90, v91
	v_cvt_pk_bf16_f32 v91, v96, v97
	global_store_dwordx4 v[92:93], v[88:91], off
	s_waitcnt vmcnt(15)
	v_lshlrev_b32_e32 v94, 16, v170
	v_and_b32_e32 v95, 0xffff0000, v170
	v_lshlrev_b32_e32 v88, 16, v168
	v_and_b32_e32 v89, 0xffff0000, v168
	v_lshlrev_b32_e32 v90, 16, v169
	v_and_b32_e32 v91, 0xffff0000, v169
	v_lshlrev_b32_e32 v96, 16, v171
	v_and_b32_e32 v97, 0xffff0000, v171
	v_pk_fma_f32 v[86:87], v[86:87], v[206:207], v[90:91]
	v_pk_fma_f32 v[84:85], v[84:85], v[204:205], v[88:89]
	v_pk_fma_f32 v[88:89], v[82:83], v[202:203], v[96:97]
	v_pk_fma_f32 v[82:83], v[80:81], v[200:201], v[94:95]
	v_cvt_pk_bf16_f32 v80, v84, v85
	v_cvt_pk_bf16_f32 v81, v86, v87
	s_waitcnt vmcnt(14)
; __device__ __forceinline__ unsigned cvt_pk_bf16(float lo, float hi) { unsigned r; asm volatile("v_cvt_pk_bf16_f32 %0, %1, %2" : "=v"(r) : "v"(lo), "v"(hi)); return r; }
;     __device__ __forceinline__ void operator()(f32x4 (&acc)[2][2][4][2], const Unit& u, int wr, int wc, int fr, int fq, LAS unsigned char*) const {
;     ...
; #pragma unroll
;             for (int ai = 0; ai < 2; ++ai)
; #pragma unroll
;                 for (int m = 0; m < 4; ++m)
; #pragma unroll
;                     for (int bj = 0; bj < 2; ++bj) { const u32x4 x = xb[ai][m][bj];
;                         f32x4 r0 = (f32x4){__uint_as_float(x.x << 16), __uint_as_float(x.x & 0xffff0000u), __uint_as_float(x.y << 16), __uint_as_float(x.y & 0xffff0000u)};
;                         f32x4 r1 = (f32x4){__uint_as_float(x.z << 16), __uint_as_float(x.z & 0xffff0000u), __uint_as_float(x.w << 16), __uint_as_float(x.w & 0xffff0000u)};
;                         r0 += sc[bj][0] * acc[ai][bj][m][0]; r1 += sc[bj][1] * acc[ai][bj][m][1];
;                         u32x4 w; w.x = cvt_pk_bf16(r0[0], r0[1]); w.y = cvt_pk_bf16(r0[2], r0[3]); w.z = cvt_pk_bf16(r1[0], r1[1]); w.w = cvt_pk_bf16(r1[2], r1[3]);
;                         *(u32x4*)(out + off0 + (size_t)(ai * HALF + m * 16) * D + bj * HALF) = w; }
	v_lshlrev_b32_e32 v84, 16, v166
	v_cvt_pk_bf16_f32 v82, v82, v83
	v_cvt_pk_bf16_f32 v83, v88, v89
	global_store_dwordx4 v[92:93], v[80:83], off offset:256
	v_and_b32_e32 v85, 0xffff0000, v166
	v_lshlrev_b32_e32 v86, 16, v167
	v_lshlrev_b32_e32 v80, 16, v164
	v_and_b32_e32 v81, 0xffff0000, v164
	v_and_b32_e32 v87, 0xffff0000, v167
	v_pk_fma_f32 v[76:77], v[76:77], v[212:213], v[80:81]
	v_lshlrev_b32_e32 v82, 16, v165
	v_and_b32_e32 v83, 0xffff0000, v165
	v_pk_fma_f32 v[80:81], v[74:75], v[210:211], v[86:87]
	v_pk_fma_f32 v[74:75], v[72:73], v[208:209], v[84:85]
	v_cvt_pk_bf16_f32 v72, v76, v77
	v_add_co_u32_e32 v76, vcc, s23, v144
	v_pk_fma_f32 v[78:79], v[78:79], v[214:215], v[82:83]
	s_nop 0
	v_addc_co_u32_e32 v77, vcc, 0, v145, vcc
	v_cvt_pk_bf16_f32 v73, v78, v79
	v_cvt_pk_bf16_f32 v74, v74, v75
	v_cvt_pk_bf16_f32 v75, v80, v81
	global_store_dwordx4 v[76:77], v[72:75], off
	s_waitcnt vmcnt(15)
	v_lshlrev_b32_e32 v78, 16, v162
	v_and_b32_e32 v79, 0xffff0000, v162
	v_lshlrev_b32_e32 v72, 16, v160
	v_and_b32_e32 v73, 0xffff0000, v160
	v_lshlrev_b32_e32 v74, 16, v161
	v_and_b32_e32 v75, 0xffff0000, v161
	v_lshlrev_b32_e32 v80, 16, v163
	v_and_b32_e32 v81, 0xffff0000, v163
	v_pk_fma_f32 v[70:71], v[70:71], v[206:207], v[74:75]
	v_pk_fma_f32 v[68:69], v[68:69], v[204:205], v[72:73]
	v_pk_fma_f32 v[72:73], v[66:67], v[202:203], v[80:81]
	v_pk_fma_f32 v[66:67], v[64:65], v[200:201], v[78:79]
	v_cvt_pk_bf16_f32 v64, v68, v69
	v_cvt_pk_bf16_f32 v65, v70, v71
	s_waitcnt vmcnt(14)
	v_lshlrev_b32_e32 v68, 16, v158
	v_cvt_pk_bf16_f32 v66, v66, v67
	v_cvt_pk_bf16_f32 v67, v72, v73
	global_store_dwordx4 v[76:77], v[64:67], off offset:256
	v_and_b32_e32 v69, 0xffff0000, v158
	v_lshlrev_b32_e32 v70, 16, v159
	v_lshlrev_b32_e32 v64, 16, v156
	v_and_b32_e32 v65, 0xffff0000, v156
	v_and_b32_e32 v71, 0xffff0000, v159
	v_pk_fma_f32 v[60:61], v[60:61], v[212:213], v[64:65]
	v_lshlrev_b32_e32 v66, 16, v157
	v_and_b32_e32 v67, 0xffff0000, v157
	v_pk_fma_f32 v[64:65], v[58:59], v[210:211], v[70:71]
	v_pk_fma_f32 v[58:59], v[56:57], v[208:209], v[68:69]
	v_cvt_pk_bf16_f32 v56, v60, v61
	v_add_co_u32_e32 v60, vcc, s93, v144
	v_pk_fma_f32 v[62:63], v[62:63], v[214:215], v[66:67]
	s_nop 0
	v_addc_co_u32_e32 v61, vcc, 0, v145, vcc
	v_cvt_pk_bf16_f32 v57, v62, v63
	v_cvt_pk_bf16_f32 v58, v58, v59
	v_cvt_pk_bf16_f32 v59, v64, v65
	global_store_dwordx4 v[60:61], v[56:59], off
	s_waitcnt vmcnt(15)
	v_lshlrev_b32_e32 v62, 16, v154
	v_and_b32_e32 v63, 0xffff0000, v154
	v_lshlrev_b32_e32 v56, 16, v152
	v_and_b32_e32 v57, 0xffff0000, v152
	v_lshlrev_b32_e32 v58, 16, v153
	v_and_b32_e32 v59, 0xffff0000, v153
	v_lshlrev_b32_e32 v64, 16, v155
	v_and_b32_e32 v65, 0xffff0000, v155
	v_pk_fma_f32 v[54:55], v[54:55], v[206:207], v[58:59]
	v_pk_fma_f32 v[52:53], v[52:53], v[204:205], v[56:57]
	v_pk_fma_f32 v[56:57], v[50:51], v[202:203], v[64:65]
	v_pk_fma_f32 v[50:51], v[48:49], v[200:201], v[62:63]
	v_cvt_pk_bf16_f32 v48, v52, v53
	v_cvt_pk_bf16_f32 v49, v54, v55
	s_waitcnt vmcnt(14)
	v_lshlrev_b32_e32 v52, 16, v142
	v_cvt_pk_bf16_f32 v50, v50, v51
	v_cvt_pk_bf16_f32 v51, v56, v57
	global_store_dwordx4 v[60:61], v[48:51], off offset:256
	v_and_b32_e32 v53, 0xffff0000, v142
	v_lshlrev_b32_e32 v54, 16, v143
	v_lshlrev_b32_e32 v48, 16, v140
	v_and_b32_e32 v49, 0xffff0000, v140
	v_and_b32_e32 v55, 0xffff0000, v143
	v_pk_fma_f32 v[44:45], v[44:45], v[212:213], v[48:49]
	v_lshlrev_b32_e32 v50, 16, v141
	v_and_b32_e32 v51, 0xffff0000, v141
	v_pk_fma_f32 v[48:49], v[42:43], v[210:211], v[54:55]
	v_pk_fma_f32 v[42:43], v[40:41], v[208:209], v[52:53]
	v_cvt_pk_bf16_f32 v40, v44, v45
	v_add_co_u32_e32 v44, vcc, s33, v144
	v_pk_fma_f32 v[46:47], v[46:47], v[214:215], v[50:51]
	s_nop 0
	v_addc_co_u32_e32 v45, vcc, 0, v145, vcc
	v_cvt_pk_bf16_f32 v41, v46, v47
	v_cvt_pk_bf16_f32 v42, v42, v43
	v_cvt_pk_bf16_f32 v43, v48, v49
	global_store_dwordx4 v[44:45], v[40:43], off
	s_waitcnt vmcnt(15)
; __device__ __forceinline__ unsigned cvt_pk_bf16(float lo, float hi) { unsigned r; asm volatile("v_cvt_pk_bf16_f32 %0, %1, %2" : "=v"(r) : "v"(lo), "v"(hi)); return r; }
; #define PG8_WAIT_V(n) asm volatile("s_waitcnt vmcnt(" #n ")" ::: "memory")
; #define PG8_BAR __builtin_amdgcn_s_barrier()
; template <class Epi>
; __device__ __forceinline__ void gemm_phase(LAS unsigned char* lds, const Gemm g, const StaticOrder& S, const Epi& E) {
;     ...
;         if (!has_next) break;
; #pragma unroll
;         for (int a = 0; a < 2; ++a)
; #pragma unroll
;             for (int b = 0; b < 2; ++b)
; #pragma unroll
;                 for (int m = 0; m < 4; ++m)
; #pragma unroll
;                     for (int n = 0; n < 2; ++n) acc[a][b][m][n] = (f32x4){0.f, 0.f, 0.f, 0.f};
;         cur = nxt; cA = nA; cB = nB; ++ui;
;     }
;     PG8_WAIT_V(0);
;     if (wr == 0) PG8_BAR;
;     __device__ __forceinline__ void operator()(f32x4 (&acc)[2][2][4][2], const Unit& u, int wr, int wc, int fr, int fq, LAS unsigned char*) const {
;     ...
; #pragma unroll
;             for (int ai = 0; ai < 2; ++ai)
; #pragma unroll
;                 for (int m = 0; m < 4; ++m)
; #pragma unroll
;                     for (int bj = 0; bj < 2; ++bj) { const u32x4 x = xb[ai][m][bj];
;                         f32x4 r0 = (f32x4){__uint_as_float(x.x << 16), __uint_as_float(x.x & 0xffff0000u), __uint_as_float(x.y << 16), __uint_as_float(x.y & 0xffff0000u)};
;                         f32x4 r1 = (f32x4){__uint_as_float(x.z << 16), __uint_as_float(x.z & 0xffff0000u), __uint_as_float(x.w << 16), __uint_as_float(x.w & 0xffff0000u)};
;                         r0 += sc[bj][0] * acc[ai][bj][m][0]; r1 += sc[bj][1] * acc[ai][bj][m][1];
;                         u32x4 w; w.x = cvt_pk_bf16(r0[0], r0[1]); w.y = cvt_pk_bf16(r0[2], r0[3]); w.z = cvt_pk_bf16(r1[0], r1[1]); w.w = cvt_pk_bf16(r1[2], r1[3]);
;                         *(u32x4*)(out + off0 + (size_t)(ai * HALF + m * 16) * D + bj * HALF) = w; }
	v_lshlrev_b32_e32 v46, 16, v138
	v_and_b32_e32 v47, 0xffff0000, v138
	v_lshlrev_b32_e32 v40, 16, v136
	v_and_b32_e32 v41, 0xffff0000, v136
	v_lshlrev_b32_e32 v42, 16, v137
	v_and_b32_e32 v43, 0xffff0000, v137
	v_lshlrev_b32_e32 v48, 16, v139
	v_and_b32_e32 v49, 0xffff0000, v139
	v_pk_fma_f32 v[38:39], v[38:39], v[206:207], v[42:43]
	v_pk_fma_f32 v[36:37], v[36:37], v[204:205], v[40:41]
	v_pk_fma_f32 v[40:41], v[34:35], v[202:203], v[48:49]
	v_pk_fma_f32 v[34:35], v[32:33], v[200:201], v[46:47]
	v_cvt_pk_bf16_f32 v32, v36, v37
	v_cvt_pk_bf16_f32 v33, v38, v39
	s_waitcnt vmcnt(14)
	v_lshlrev_b32_e32 v36, 16, v134
	v_cvt_pk_bf16_f32 v34, v34, v35
	v_cvt_pk_bf16_f32 v35, v40, v41
	global_store_dwordx4 v[44:45], v[32:35], off offset:256
	v_and_b32_e32 v37, 0xffff0000, v134
	v_lshlrev_b32_e32 v38, 16, v135
	v_lshlrev_b32_e32 v32, 16, v132
	v_and_b32_e32 v33, 0xffff0000, v132
	v_and_b32_e32 v39, 0xffff0000, v135
	v_pk_fma_f32 v[28:29], v[28:29], v[212:213], v[32:33]
	v_lshlrev_b32_e32 v34, 16, v133
	v_and_b32_e32 v35, 0xffff0000, v133
	v_pk_fma_f32 v[32:33], v[26:27], v[210:211], v[38:39]
	v_pk_fma_f32 v[26:27], v[24:25], v[208:209], v[36:37]
	v_cvt_pk_bf16_f32 v24, v28, v29
	v_add_co_u32_e32 v28, vcc, s18, v144
	v_pk_fma_f32 v[30:31], v[30:31], v[214:215], v[34:35]
	s_nop 0
	v_addc_co_u32_e32 v29, vcc, 0, v145, vcc
	v_cvt_pk_bf16_f32 v25, v30, v31
	v_cvt_pk_bf16_f32 v26, v26, v27
	v_cvt_pk_bf16_f32 v27, v32, v33
	global_store_dwordx4 v[28:29], v[24:27], off
	s_waitcnt vmcnt(15)
	v_lshlrev_b32_e32 v30, 16, v130
	v_and_b32_e32 v31, 0xffff0000, v130
	v_lshlrev_b32_e32 v24, 16, v128
	v_and_b32_e32 v25, 0xffff0000, v128
	v_lshlrev_b32_e32 v26, 16, v129
	v_and_b32_e32 v27, 0xffff0000, v129
	v_lshlrev_b32_e32 v32, 16, v131
	v_and_b32_e32 v33, 0xffff0000, v131
	v_pk_fma_f32 v[22:23], v[22:23], v[206:207], v[26:27]
	v_pk_fma_f32 v[20:21], v[20:21], v[204:205], v[24:25]
	v_pk_fma_f32 v[24:25], v[18:19], v[202:203], v[32:33]
	v_pk_fma_f32 v[18:19], v[16:17], v[200:201], v[30:31]
	v_cvt_pk_bf16_f32 v16, v20, v21
	v_cvt_pk_bf16_f32 v17, v22, v23
	s_waitcnt vmcnt(14)
	v_lshlrev_b32_e32 v20, 16, v126
	v_cvt_pk_bf16_f32 v18, v18, v19
	v_cvt_pk_bf16_f32 v19, v24, v25
	global_store_dwordx4 v[28:29], v[16:19], off offset:256
	v_and_b32_e32 v21, 0xffff0000, v126
	v_lshlrev_b32_e32 v22, 16, v127
	v_lshlrev_b32_e32 v16, 16, v124
	v_and_b32_e32 v17, 0xffff0000, v124
	v_and_b32_e32 v23, 0xffff0000, v127
	v_pk_fma_f32 v[12:13], v[12:13], v[212:213], v[16:17]
	v_lshlrev_b32_e32 v18, 16, v125
	v_and_b32_e32 v19, 0xffff0000, v125
	v_pk_fma_f32 v[16:17], v[10:11], v[210:211], v[22:23]
	v_pk_fma_f32 v[10:11], v[8:9], v[208:209], v[20:21]
	v_cvt_pk_bf16_f32 v8, v12, v13
	v_add_co_u32_e32 v12, vcc, s19, v144
	v_pk_fma_f32 v[14:15], v[14:15], v[214:215], v[18:19]
	s_nop 0
	v_addc_co_u32_e32 v13, vcc, 0, v145, vcc
	v_cvt_pk_bf16_f32 v9, v14, v15
	v_cvt_pk_bf16_f32 v10, v10, v11
	v_cvt_pk_bf16_f32 v11, v16, v17
	global_store_dwordx4 v[12:13], v[8:11], off
	s_waitcnt vmcnt(15)
	v_lshlrev_b32_e32 v14, 16, v122
	v_and_b32_e32 v15, 0xffff0000, v122
	v_lshlrev_b32_e32 v8, 16, v120
	v_and_b32_e32 v9, 0xffff0000, v120
	v_lshlrev_b32_e32 v16, 16, v123
	v_and_b32_e32 v17, 0xffff0000, v123
	v_lshlrev_b32_e32 v10, 16, v121
	v_and_b32_e32 v11, 0xffff0000, v121
	v_pk_fma_f32 v[4:5], v[4:5], v[204:205], v[8:9]
	v_pk_fma_f32 v[8:9], v[2:3], v[202:203], v[16:17]
	v_pk_fma_f32 v[2:3], v[0:1], v[200:201], v[14:15]
	s_and_b64 vcc, exec, s[4:5]
	v_pk_fma_f32 v[6:7], v[6:7], v[206:207], v[10:11]
	v_cvt_pk_bf16_f32 v0, v4, v5
	s_nop 0
	v_cvt_pk_bf16_f32 v1, v6, v7
	v_cvt_pk_bf16_f32 v2, v2, v3
	v_cvt_pk_bf16_f32 v3, v8, v9
	global_store_dwordx4 v[12:13], v[0:3], off offset:256
	s_cbranch_vccz .LBB0_849
	s_waitcnt vmcnt(0)
	s_cmpk_gt_u32 s21, 0xff
	v_readlane_b32 s38, v255, 44
	s_cbranch_scc1 .LBB0_864
	s_barrier
